# baseline (speedup 1.0000x reference)
; #define PG8_STAGE(bufoff, gbase, voff) do { _Pragma("unroll") for (int _i = 0; _i < 2; ++_i) \
;         __builtin_amdgcn_global_load_lds((const unsigned*)((const char*)(gbase) + (voff)[_i]), (LAS unsigned*)(lds + (bufoff) + ldsw + _i * 8192), 16, 0, 0); } while (0)
; #define PG8_LDA(dst, b, h) do { _Pragma("unroll") for (int m = 0; m < 4; ++m) _Pragma("unroll") for (int k = 0; k < 2; ++k) dst[m][k] = *(const LAS bf16x8*)(lds + PG8_SA(b, h) + aoff + m * 2048 + k * 1024); } while (0)
; #define PG8_LDB(dst, b, h) do { _Pragma("unroll") for (int n = 0; n < 2; ++n) _Pragma("unroll") for (int k = 0; k < 2; ++k) dst[n][k] = *(const LAS bf16x8*)(lds + PG8_SB(b, h) + boff + n * 2048 + k * 1024); } while (0)
; #define PG8_MMA(ai, bj, At, Bt) do { __builtin_amdgcn_s_setprio(1); _Pragma("unroll") for (int m = 0; m < 4; ++m) _Pragma("unroll") for (int n = 0; n < 2; ++n) _Pragma("unroll") for (int k = 0; k < 2; ++k) \
;         acc[ai][bj][m][n] = __builtin_amdgcn_mfma_f32_16x16x32_bf16(Bt[n][k], At[m][k], acc[ai][bj][m][n], 0, 0, 0); __builtin_amdgcn_s_setprio(0); } while (0)
; #define PG8_WAIT_L(n) asm volatile("s_waitcnt lgkmcnt(" #n ")" ::: "memory")
; #define PG8_BAR __builtin_amdgcn_s_barrier()
; #define PG8_SCHED __builtin_amdgcn_sched_barrier(0)
;     ...
;             const char* a1 = cA + (size_t)(t + 1) * kstep;
;             const char* a2 = last ? nA : cA + (size_t)(t + 2) * kstep; const char* b2 = last ? nB : cB + (size_t)(t + 2) * kstep;
;             const char* a3 = a2 + kstep; const char* b3 = b2 + kstep;
;             PG8_LDB(B0, 0, 0); PG8_SCHED; PG8_LDA(At, 0, 0); PG8_STAGE(PG8_SA(1, 1), a1 + hstep, voffA);
;             PG8_WAIT_L(8); PG8_BAR; PG8_WAIT_L(0); PG8_MMA(0, 0, At, B0); PG8_BAR; PG8_SCHED;
;             PG8_LDB(B1, 0, 1); PG8_STAGE(PG8_SB(0, 0), b2, voffB);
;             PG8_BAR; PG8_WAIT_L(0); PG8_MMA(0, 1, At, B1); PG8_BAR;
;             PG8_LDA(At, 0, 1); PG8_STAGE(PG8_SA(0, 0), a2, voffA);
;             PG8_BAR; PG8_WAIT_L(0); PG8_MMA(1, 0, At, B0); PG8_BAR; PG8_SCHED;
.LBB0_120:
	s_add_i32 s44, s2, 2
	s_add_u32 s10, s8, 0x100
	s_addc_u32 s11, s9, 0
	s_add_i32 s35, 0, 0x10000
	v_add_u32_e32 v156, s35, v145
	ds_read_b128 v[140:143], v156
	ds_read_b128 v[148:151], v156 offset:1024
	ds_read_b128 v[152:155], v156 offset:2048
	ds_read_b128 v[156:159], v156 offset:3072
	s_cmp_eq_u32 s41, s2
	s_cselect_b32 s2, s6, s10
	s_cselect_b32 s3, s7, s11
	s_cselect_b32 s13, s19, s43
	s_cselect_b32 s12, s18, s42
	v_lshl_add_u64 v[192:193], s[8:9], 0, v[136:137]
	s_add_i32 m0, s21, 0xc000
	ds_read_b128 v[160:163], v147
	ds_read_b128 v[164:167], v147 offset:1024
	ds_read_b128 v[168:171], v147 offset:2048
	ds_read_b128 v[172:175], v147 offset:3072
	ds_read_b128 v[176:179], v147 offset:4096
	ds_read_b128 v[180:183], v147 offset:5120
	ds_read_b128 v[184:187], v147 offset:6144
	ds_read_b128 v[188:191], v147 offset:7168
	global_load_lds_dwordx4 v[192:193], off
	v_lshl_add_u64 v[192:193], s[8:9], 0, v[138:139]
	s_add_i32 m0, s21, 0xe000
	s_nop 0
	global_load_lds_dwordx4 v[192:193], off
	s_waitcnt lgkmcnt(8)
	s_barrier
	s_waitcnt lgkmcnt(0)
	v_mfma_f32_16x16x32_bf16 v[126:129], v[140:143], v[160:163], v[126:129]
	v_mfma_f32_16x16x32_bf16 v[122:125], v[152:155], v[160:163], v[122:125]
	v_mfma_f32_16x16x32_bf16 v[110:113], v[140:143], v[168:171], v[110:113]
	v_mfma_f32_16x16x32_bf16 v[106:109], v[152:155], v[168:171], v[106:109]
	v_mfma_f32_16x16x32_bf16 v[94:97], v[140:143], v[176:179], v[94:97]
	v_mfma_f32_16x16x32_bf16 v[90:93], v[152:155], v[176:179], v[90:93]
	v_mfma_f32_16x16x32_bf16 v[78:81], v[140:143], v[184:187], v[78:81]
	v_mfma_f32_16x16x32_bf16 v[74:77], v[152:155], v[184:187], v[74:77]
	v_mfma_f32_16x16x32_bf16 v[126:129], v[148:151], v[164:167], v[126:129]
	v_mfma_f32_16x16x32_bf16 v[122:125], v[156:159], v[164:167], v[122:125]
	v_mfma_f32_16x16x32_bf16 v[110:113], v[148:151], v[172:175], v[110:113]
	v_mfma_f32_16x16x32_bf16 v[106:109], v[156:159], v[172:175], v[106:109]
	v_mfma_f32_16x16x32_bf16 v[94:97], v[148:151], v[180:183], v[94:97]
	v_mfma_f32_16x16x32_bf16 v[90:93], v[156:159], v[180:183], v[90:93]
	v_mfma_f32_16x16x32_bf16 v[78:81], v[148:151], v[188:191], v[78:81]
	v_mfma_f32_16x16x32_bf16 v[74:77], v[156:159], v[188:191], v[74:77]
	s_barrier
	s_add_i32 s45, 0, 0x14000
	v_add_u32_e32 v208, s45, v145
	s_add_i32 s8, s35, s20
	ds_read_b128 v[192:195], v208
	ds_read_b128 v[196:199], v208 offset:1024
	ds_read_b128 v[220:223], v208 offset:2048
	ds_read_b128 v[224:227], v208 offset:3072
	v_lshl_add_u64 v[208:209], s[12:13], 0, v[64:65]
	s_mov_b32 m0, s8
	v_lshl_add_u64 v[210:211], s[12:13], 0, v[134:135]
	global_load_lds_dwordx4 v[208:209], off
	s_add_i32 m0, s8, 0x2000
	s_nop 0
	global_load_lds_dwordx4 v[210:211], off
	s_barrier
	s_waitcnt lgkmcnt(0)
	v_mfma_f32_16x16x32_bf16 v[118:121], v[192:195], v[160:163], v[118:121]
	v_mfma_f32_16x16x32_bf16 v[114:117], v[220:223], v[160:163], v[114:117]
	v_mfma_f32_16x16x32_bf16 v[102:105], v[192:195], v[168:171], v[102:105]
	v_mfma_f32_16x16x32_bf16 v[98:101], v[220:223], v[168:171], v[98:101]
	v_mfma_f32_16x16x32_bf16 v[86:89], v[192:195], v[176:179], v[86:89]
	v_mfma_f32_16x16x32_bf16 v[82:85], v[220:223], v[176:179], v[82:85]
	v_mfma_f32_16x16x32_bf16 v[70:73], v[192:195], v[184:187], v[70:73]
	v_mfma_f32_16x16x32_bf16 v[66:69], v[220:223], v[184:187], v[66:69]
	v_mfma_f32_16x16x32_bf16 v[118:121], v[196:199], v[164:167], v[118:121]
	v_mfma_f32_16x16x32_bf16 v[114:117], v[224:227], v[164:167], v[114:117]
	v_mfma_f32_16x16x32_bf16 v[102:105], v[196:199], v[172:175], v[102:105]
	v_mfma_f32_16x16x32_bf16 v[98:101], v[224:227], v[172:175], v[98:101]
	v_mfma_f32_16x16x32_bf16 v[86:89], v[196:199], v[180:183], v[86:89]
	v_mfma_f32_16x16x32_bf16 v[82:85], v[224:227], v[180:183], v[82:85]
	v_mfma_f32_16x16x32_bf16 v[70:73], v[196:199], v[188:191], v[70:73]
	v_mfma_f32_16x16x32_bf16 v[66:69], v[224:227], v[188:191], v[66:69]
	s_barrier
	s_mov_b32 m0, s21
	v_lshl_add_u64 v[212:213], s[2:3], 0, v[130:131]
	ds_read_b128 v[160:163], v147 offset:16384
	ds_read_b128 v[164:167], v147 offset:17408
	ds_read_b128 v[168:171], v147 offset:18432
	ds_read_b128 v[172:175], v147 offset:19456
	ds_read_b128 v[176:179], v147 offset:20480
	ds_read_b128 v[180:183], v147 offset:21504
	ds_read_b128 v[184:187], v147 offset:22528
	ds_read_b128 v[188:191], v147 offset:23552
	global_load_lds_dwordx4 v[212:213], off
	v_lshl_add_u64 v[214:215], s[2:3], 0, v[132:133]
	s_mov_b32 m0, s22
	s_nop 0
	global_load_lds_dwordx4 v[214:215], off
	s_barrier
	s_waitcnt lgkmcnt(0)
	v_mfma_f32_16x16x32_bf16 v[60:63], v[140:143], v[160:163], v[60:63]
	v_mfma_f32_16x16x32_bf16 v[56:59], v[152:155], v[160:163], v[56:59]
	v_mfma_f32_16x16x32_bf16 v[44:47], v[140:143], v[168:171], v[44:47]
	v_mfma_f32_16x16x32_bf16 v[40:43], v[152:155], v[168:171], v[40:43]
	v_mfma_f32_16x16x32_bf16 v[28:31], v[140:143], v[176:179], v[28:31]
	v_mfma_f32_16x16x32_bf16 v[24:27], v[152:155], v[176:179], v[24:27]
	v_mfma_f32_16x16x32_bf16 v[12:15], v[140:143], v[184:187], v[12:15]
	v_mfma_f32_16x16x32_bf16 v[8:11], v[152:155], v[184:187], v[8:11]
	v_mfma_f32_16x16x32_bf16 v[60:63], v[148:151], v[164:167], v[60:63]
	v_mfma_f32_16x16x32_bf16 v[56:59], v[156:159], v[164:167], v[56:59]
	v_mfma_f32_16x16x32_bf16 v[44:47], v[148:151], v[172:175], v[44:47]
	v_mfma_f32_16x16x32_bf16 v[40:43], v[156:159], v[172:175], v[40:43]
	v_mfma_f32_16x16x32_bf16 v[28:31], v[148:151], v[180:183], v[28:31]
	v_mfma_f32_16x16x32_bf16 v[24:27], v[156:159], v[180:183], v[24:27]
	v_mfma_f32_16x16x32_bf16 v[12:15], v[148:151], v[188:191], v[12:15]
	v_mfma_f32_16x16x32_bf16 v[8:11], v[156:159], v[188:191], v[8:11]
	s_barrier
; #define PG8_STAGE(bufoff, gbase, voff) do { _Pragma("unroll") for (int _i = 0; _i < 2; ++_i) \
;         __builtin_amdgcn_global_load_lds((const unsigned*)((const char*)(gbase) + (voff)[_i]), (LAS unsigned*)(lds + (bufoff) + ldsw + _i * 8192), 16, 0, 0); } while (0)
; #define PG8_LDA(dst, b, h) do { _Pragma("unroll") for (int m = 0; m < 4; ++m) _Pragma("unroll") for (int k = 0; k < 2; ++k) dst[m][k] = *(const LAS bf16x8*)(lds + PG8_SA(b, h) + aoff + m * 2048 + k * 1024); } while (0)
; #define PG8_LDB(dst, b, h) do { _Pragma("unroll") for (int n = 0; n < 2; ++n) _Pragma("unroll") for (int k = 0; k < 2; ++k) dst[n][k] = *(const LAS bf16x8*)(lds + PG8_SB(b, h) + boff + n * 2048 + k * 1024); } while (0)
; #define PG8_MMA(ai, bj, At, Bt) do { __builtin_amdgcn_s_setprio(1); _Pragma("unroll") for (int m = 0; m < 4; ++m) _Pragma("unroll") for (int n = 0; n < 2; ++n) _Pragma("unroll") for (int k = 0; k < 2; ++k) \
;         acc[ai][bj][m][n] = __builtin_amdgcn_mfma_f32_16x16x32_bf16(Bt[n][k], At[m][k], acc[ai][bj][m][n], 0, 0, 0); __builtin_amdgcn_s_setprio(0); } while (0)
; #define PG8_WAIT_V(n) asm volatile("s_waitcnt vmcnt(" #n ")" ::: "memory")
; #define PG8_WAIT_L(n) asm volatile("s_waitcnt lgkmcnt(" #n ")" ::: "memory")
; #define PG8_BAR __builtin_amdgcn_s_barrier()
; #define PG8_SCHED __builtin_amdgcn_sched_barrier(0)
;     ...
;             PG8_STAGE(PG8_SB(0, 1), b2 + hstep, voffB);
;             PG8_WAIT_V(6); PG8_BAR; PG8_MMA(1, 1, At, B1); PG8_BAR;
;             PG8_LDB(B0, 1, 0); PG8_SCHED; PG8_LDA(At, 1, 0); PG8_STAGE(PG8_SA(0, 1), a2 + hstep, voffA);
;             PG8_WAIT_L(8); PG8_BAR; PG8_WAIT_L(0); PG8_MMA(0, 0, At, B0); PG8_BAR; PG8_SCHED;
;             PG8_LDB(B1, 1, 1); PG8_STAGE(PG8_SB(1, 0), b3, voffB);
;             PG8_BAR; PG8_WAIT_L(0); PG8_MMA(0, 1, At, B1); PG8_BAR;
;             PG8_LDA(At, 1, 1); PG8_STAGE(PG8_SA(1, 0), a3, voffA);
;             PG8_BAR; PG8_WAIT_L(0); PG8_MMA(1, 0, At, B0); PG8_BAR; PG8_SCHED;
	s_add_u32 s8, s12, 0x84000
	s_addc_u32 s9, s13, 0
	s_add_i32 s35, s45, s20
	v_lshl_add_u64 v[140:141], s[8:9], 0, v[64:65]
	s_mov_b32 m0, s35
	s_nop 0
	global_load_lds_dwordx4 v[140:141], off
	v_lshl_add_u64 v[140:141], s[8:9], 0, v[134:135]
	s_add_i32 m0, s35, 0x2000
	s_nop 0
	global_load_lds_dwordx4 v[140:141], off
	s_waitcnt vmcnt(6)
	s_barrier
	v_mfma_f32_16x16x32_bf16 v[52:55], v[192:195], v[160:163], v[52:55]
	v_mfma_f32_16x16x32_bf16 v[48:51], v[220:223], v[160:163], v[48:51]
	v_mfma_f32_16x16x32_bf16 v[36:39], v[192:195], v[168:171], v[36:39]
	v_mfma_f32_16x16x32_bf16 v[32:35], v[220:223], v[168:171], v[32:35]
	v_mfma_f32_16x16x32_bf16 v[20:23], v[192:195], v[176:179], v[20:23]
	v_mfma_f32_16x16x32_bf16 v[16:19], v[220:223], v[176:179], v[16:19]
	v_mfma_f32_16x16x32_bf16 v[4:7], v[192:195], v[184:187], v[4:7]
	v_mfma_f32_16x16x32_bf16 v[0:3], v[220:223], v[184:187], v[0:3]
	v_mfma_f32_16x16x32_bf16 v[52:55], v[196:199], v[164:167], v[52:55]
	v_mfma_f32_16x16x32_bf16 v[48:51], v[224:227], v[164:167], v[48:51]
	v_mfma_f32_16x16x32_bf16 v[36:39], v[196:199], v[172:175], v[36:39]
	v_mfma_f32_16x16x32_bf16 v[32:35], v[224:227], v[172:175], v[32:35]
	v_mfma_f32_16x16x32_bf16 v[20:23], v[196:199], v[180:183], v[20:23]
	v_mfma_f32_16x16x32_bf16 v[16:19], v[224:227], v[180:183], v[16:19]
	v_mfma_f32_16x16x32_bf16 v[4:7], v[196:199], v[188:191], v[4:7]
	v_mfma_f32_16x16x32_bf16 v[0:3], v[224:227], v[188:191], v[0:3]
	s_barrier
	s_add_i32 s8, 0, 0x18000
	v_add_u32_e32 v156, s8, v145
	ds_read_b128 v[140:143], v156
	ds_read_b128 v[148:151], v156 offset:1024
	ds_read_b128 v[152:155], v156 offset:2048
	ds_read_b128 v[156:159], v156 offset:3072
	s_add_u32 s2, s2, 0x84000
	s_addc_u32 s3, s3, 0
	s_mov_b32 m0, s23
	v_lshl_add_u64 v[192:193], s[2:3], 0, v[130:131]
	ds_read_b128 v[160:163], v147 offset:32768
	ds_read_b128 v[164:167], v147 offset:33792
	ds_read_b128 v[168:171], v147 offset:34816
	ds_read_b128 v[172:175], v147 offset:35840
	ds_read_b128 v[176:179], v147 offset:36864
	ds_read_b128 v[180:183], v147 offset:37888
	ds_read_b128 v[184:187], v147 offset:38912
	ds_read_b128 v[188:191], v147 offset:39936
	global_load_lds_dwordx4 v[192:193], off
	v_lshl_add_u64 v[192:193], s[2:3], 0, v[132:133]
	s_mov_b32 m0, s24
	s_nop 0
	global_load_lds_dwordx4 v[192:193], off
	s_waitcnt lgkmcnt(8)
	s_barrier
	s_waitcnt lgkmcnt(0)
	v_mfma_f32_16x16x32_bf16 v[126:129], v[140:143], v[160:163], v[126:129]
	v_mfma_f32_16x16x32_bf16 v[122:125], v[152:155], v[160:163], v[122:125]
	v_mfma_f32_16x16x32_bf16 v[110:113], v[140:143], v[168:171], v[110:113]
	v_mfma_f32_16x16x32_bf16 v[106:109], v[152:155], v[168:171], v[106:109]
	v_mfma_f32_16x16x32_bf16 v[94:97], v[140:143], v[176:179], v[94:97]
	v_mfma_f32_16x16x32_bf16 v[90:93], v[152:155], v[176:179], v[90:93]
	v_mfma_f32_16x16x32_bf16 v[78:81], v[140:143], v[184:187], v[78:81]
	v_mfma_f32_16x16x32_bf16 v[74:77], v[152:155], v[184:187], v[74:77]
	v_mfma_f32_16x16x32_bf16 v[126:129], v[148:151], v[164:167], v[126:129]
	v_mfma_f32_16x16x32_bf16 v[122:125], v[156:159], v[164:167], v[122:125]
	v_mfma_f32_16x16x32_bf16 v[110:113], v[148:151], v[172:175], v[110:113]
	v_mfma_f32_16x16x32_bf16 v[106:109], v[156:159], v[172:175], v[106:109]
	v_mfma_f32_16x16x32_bf16 v[94:97], v[148:151], v[180:183], v[94:97]
	v_mfma_f32_16x16x32_bf16 v[90:93], v[156:159], v[180:183], v[90:93]
	v_mfma_f32_16x16x32_bf16 v[78:81], v[148:151], v[188:191], v[78:81]
	v_mfma_f32_16x16x32_bf16 v[74:77], v[156:159], v[188:191], v[74:77]
	s_barrier
	s_add_i32 s9, 0, 0x1c000
	s_add_i32 s2, s8, s20
	v_add_u32_e32 v219, s9, v145
	v_lshl_add_u64 v[208:209], v[208:209], 0, s[16:17]
	s_mov_b32 m0, s2
	ds_read_b128 v[192:195], v219
	ds_read_b128 v[196:199], v219 offset:1024
	ds_read_b128 v[220:223], v219 offset:2048
	ds_read_b128 v[224:227], v219 offset:3072
	global_load_lds_dwordx4 v[208:209], off
	v_lshl_add_u64 v[208:209], v[210:211], 0, s[16:17]
	s_add_i32 m0, s2, 0x2000
	s_nop 0
	global_load_lds_dwordx4 v[208:209], off
	s_barrier
	s_waitcnt lgkmcnt(0)
	v_mfma_f32_16x16x32_bf16 v[118:121], v[192:195], v[160:163], v[118:121]
	v_mfma_f32_16x16x32_bf16 v[114:117], v[220:223], v[160:163], v[114:117]
	v_mfma_f32_16x16x32_bf16 v[102:105], v[192:195], v[168:171], v[102:105]
	v_mfma_f32_16x16x32_bf16 v[98:101], v[220:223], v[168:171], v[98:101]
	v_mfma_f32_16x16x32_bf16 v[86:89], v[192:195], v[176:179], v[86:89]
	v_mfma_f32_16x16x32_bf16 v[82:85], v[220:223], v[176:179], v[82:85]
	v_mfma_f32_16x16x32_bf16 v[70:73], v[192:195], v[184:187], v[70:73]
	v_mfma_f32_16x16x32_bf16 v[66:69], v[220:223], v[184:187], v[66:69]
	v_mfma_f32_16x16x32_bf16 v[118:121], v[196:199], v[164:167], v[118:121]
	v_mfma_f32_16x16x32_bf16 v[114:117], v[224:227], v[164:167], v[114:117]
	v_mfma_f32_16x16x32_bf16 v[102:105], v[196:199], v[172:175], v[102:105]
	v_mfma_f32_16x16x32_bf16 v[98:101], v[224:227], v[172:175], v[98:101]
	v_mfma_f32_16x16x32_bf16 v[86:89], v[196:199], v[180:183], v[86:89]
	v_mfma_f32_16x16x32_bf16 v[82:85], v[224:227], v[180:183], v[82:85]
	v_mfma_f32_16x16x32_bf16 v[70:73], v[196:199], v[188:191], v[70:73]
	v_mfma_f32_16x16x32_bf16 v[66:69], v[224:227], v[188:191], v[66:69]
	s_barrier
	s_mov_b32 m0, s25
	v_lshl_add_u64 v[208:209], v[212:213], 0, s[16:17]
	ds_read_b128 v[160:163], v147 offset:49152
	ds_read_b128 v[164:167], v147 offset:50176
	ds_read_b128 v[168:171], v147 offset:51200
	ds_read_b128 v[172:175], v147 offset:52224
	ds_read_b128 v[176:179], v147 offset:53248
	ds_read_b128 v[180:183], v147 offset:54272
	ds_read_b128 v[184:187], v147 offset:55296
	ds_read_b128 v[188:191], v147 offset:56320
	global_load_lds_dwordx4 v[208:209], off
	v_lshl_add_u64 v[208:209], v[214:215], 0, s[16:17]
	s_mov_b32 m0, s26
	s_nop 0
	global_load_lds_dwordx4 v[208:209], off
	s_barrier
; __device__ __forceinline__ unsigned cvt_pk_bf16(float lo, float hi) { unsigned r; asm volatile("v_cvt_pk_bf16_f32 %0, %1, %2" : "=v"(r) : "v"(lo), "v"(hi)); return r; }
; #define PG8_STAGE(bufoff, gbase, voff) do { _Pragma("unroll") for (int _i = 0; _i < 2; ++_i) \
;         __builtin_amdgcn_global_load_lds((const unsigned*)((const char*)(gbase) + (voff)[_i]), (LAS unsigned*)(lds + (bufoff) + ldsw + _i * 8192), 16, 0, 0); } while (0)
; #define PG8_MMA(ai, bj, At, Bt) do { __builtin_amdgcn_s_setprio(1); _Pragma("unroll") for (int m = 0; m < 4; ++m) _Pragma("unroll") for (int n = 0; n < 2; ++n) _Pragma("unroll") for (int k = 0; k < 2; ++k) \
;         acc[ai][bj][m][n] = __builtin_amdgcn_mfma_f32_16x16x32_bf16(Bt[n][k], At[m][k], acc[ai][bj][m][n], 0, 0, 0); __builtin_amdgcn_s_setprio(0); } while (0)
; #define PG8_WAIT_V(n) asm volatile("s_waitcnt vmcnt(" #n ")" ::: "memory")
; #define PG8_WAIT_L(n) asm volatile("s_waitcnt lgkmcnt(" #n ")" ::: "memory")
; #define PG8_BAR __builtin_amdgcn_s_barrier()
; #define PG8_SCHED __builtin_amdgcn_sched_barrier(0)
;     __device__ __forceinline__ void operator()(const f32x4 (&acc)[2][2][4][2], const Unit& u, int wr, int wc, int fr, int fq) const {
;         const int row0 = u.pm * BM + wr * 64 + fr, col0 = u.pn * BM + wc * 32 + 8 * fq;
; #pragma unroll
;         for (int ai = 0; ai < 2; ++ai)
; #pragma unroll
;             for (int m = 0; m < 4; ++m) { bf16_t* rowp = O + (size_t)(row0 + ai * HALF + m * 16) * LDF + col0;
; #pragma unroll
;                 for (int bj = 0; bj < 2; ++bj) { f32x4 v0 = acc[ai][bj][m][0], v1 = acc[ai][bj][m][1];
; #pragma unroll
;                     for (int j = 0; j < 4; ++j) { const float a = fmaxf(v0[j], 0.f), b = fmaxf(v1[j], 0.f); v0[j] = a * a; v1[j] = b * b; }
;                     u32x4 w; w.x = cvt_pk_bf16(v0[0], v0[1]); w.y = cvt_pk_bf16(v0[2], v0[3]); w.z = cvt_pk_bf16(v1[0], v1[1]); w.w = cvt_pk_bf16(v1[2], v1[3]);
;                     *(u32x4*)(rowp + bj * HALF) = w; } }
;     ...
;             PG8_BAR; PG8_WAIT_L(0); PG8_MMA(1, 0, At, B0); PG8_BAR; PG8_SCHED;
;             PG8_STAGE(PG8_SB(1, 1), b3 + hstep, voffB);
;             PG8_WAIT_V(6); PG8_BAR; PG8_MMA(1, 1, At, B1); PG8_BAR;
;         }
	s_waitcnt lgkmcnt(0)
	v_mfma_f32_16x16x32_bf16 v[60:63], v[140:143], v[160:163], v[60:63]
	v_mfma_f32_16x16x32_bf16 v[56:59], v[152:155], v[160:163], v[56:59]
	v_mfma_f32_16x16x32_bf16 v[44:47], v[140:143], v[168:171], v[44:47]
	v_mfma_f32_16x16x32_bf16 v[40:43], v[152:155], v[168:171], v[40:43]
	v_mfma_f32_16x16x32_bf16 v[28:31], v[140:143], v[176:179], v[28:31]
	v_mfma_f32_16x16x32_bf16 v[24:27], v[152:155], v[176:179], v[24:27]
	v_mfma_f32_16x16x32_bf16 v[12:15], v[140:143], v[184:187], v[12:15]
	v_mfma_f32_16x16x32_bf16 v[8:11], v[152:155], v[184:187], v[8:11]
	v_mfma_f32_16x16x32_bf16 v[60:63], v[148:151], v[164:167], v[60:63]
	v_mfma_f32_16x16x32_bf16 v[56:59], v[156:159], v[164:167], v[56:59]
	v_mfma_f32_16x16x32_bf16 v[44:47], v[148:151], v[172:175], v[44:47]
	v_mfma_f32_16x16x32_bf16 v[40:43], v[156:159], v[172:175], v[40:43]
	v_mfma_f32_16x16x32_bf16 v[28:31], v[148:151], v[180:183], v[28:31]
	v_mfma_f32_16x16x32_bf16 v[24:27], v[156:159], v[180:183], v[24:27]
	v_mfma_f32_16x16x32_bf16 v[12:15], v[148:151], v[188:191], v[12:15]
	v_mfma_f32_16x16x32_bf16 v[8:11], v[156:159], v[188:191], v[8:11]
	s_barrier
	s_add_u32 s2, s12, 0x84080
	s_addc_u32 s3, s13, 0
	s_add_i32 s8, s9, s20
	v_lshl_add_u64 v[140:141], s[2:3], 0, v[64:65]
	s_mov_b32 m0, s8
	s_nop 0
	global_load_lds_dwordx4 v[140:141], off
	v_lshl_add_u64 v[140:141], s[2:3], 0, v[134:135]
	s_add_i32 m0, s8, 0x2000
	s_nop 0
	global_load_lds_dwordx4 v[140:141], off
	s_waitcnt vmcnt(6)
	s_barrier
	v_mfma_f32_16x16x32_bf16 v[52:55], v[192:195], v[160:163], v[52:55]
	v_mfma_f32_16x16x32_bf16 v[48:51], v[220:223], v[160:163], v[48:51]
	v_mfma_f32_16x16x32_bf16 v[36:39], v[192:195], v[168:171], v[36:39]
	v_mfma_f32_16x16x32_bf16 v[32:35], v[220:223], v[168:171], v[32:35]
	v_mfma_f32_16x16x32_bf16 v[20:23], v[192:195], v[176:179], v[20:23]
	v_mfma_f32_16x16x32_bf16 v[16:19], v[220:223], v[176:179], v[16:19]
	v_mfma_f32_16x16x32_bf16 v[4:7], v[192:195], v[184:187], v[4:7]
	v_mfma_f32_16x16x32_bf16 v[0:3], v[220:223], v[184:187], v[0:3]
	v_mfma_f32_16x16x32_bf16 v[52:55], v[196:199], v[164:167], v[52:55]
	v_mfma_f32_16x16x32_bf16 v[48:51], v[224:227], v[164:167], v[48:51]
	v_mfma_f32_16x16x32_bf16 v[36:39], v[196:199], v[172:175], v[36:39]
	v_mfma_f32_16x16x32_bf16 v[32:35], v[224:227], v[172:175], v[32:35]
	v_mfma_f32_16x16x32_bf16 v[20:23], v[196:199], v[180:183], v[20:23]
	v_mfma_f32_16x16x32_bf16 v[16:19], v[224:227], v[180:183], v[16:19]
	v_mfma_f32_16x16x32_bf16 v[4:7], v[196:199], v[188:191], v[4:7]
	v_mfma_f32_16x16x32_bf16 v[0:3], v[224:227], v[188:191], v[0:3]
	s_barrier
	s_add_u32 s42, s42, 0x100
	s_addc_u32 s43, s43, 0
	s_cmp_ge_u32 s44, s40
	s_mov_b64 s[8:9], s[10:11]
	s_mov_b32 s2, s44
	s_cbranch_scc0 .LBB0_120
	v_max_f32_e32 v122, 0, v122
	v_lshl_or_b32 v142, s37, 8, v146
	v_mul_f32_e32 v151, v122, v122
	v_max_f32_e32 v122, v127, v127
	v_max_f32_e32 v123, 0, v123
	v_max_f32_e32 v124, 0, v124
	v_lshl_add_u32 v150, s38, 8, v144
	v_ashrrev_i32_e32 v143, 31, v142
	v_mov_b64_e32 v[140:141], s[80:81]
	s_movk_i32 s8, 0x4080
	v_max_f32_e32 v122, 0, v122
	v_mul_f32_e32 v127, v123, v123
	v_max_f32_e32 v123, v128, v128
	v_mul_f32_e32 v128, v124, v124
	v_max_f32_e32 v124, v129, v129
	v_mad_i64_i32 v[148:149], s[2:3], v150, s8, v[140:141]
	v_lshlrev_b64 v[142:143], 1, v[142:143]
	v_max_f32_e32 v126, 0, v126
	v_mul_f32_e32 v122, v122, v122
	v_max_f32_e32 v123, 0, v123
	v_max_f32_e32 v124, 0, v124
	v_max_f32_e32 v125, 0, v125
	v_lshl_add_u64 v[148:149], v[148:149], 0, v[142:143]
	v_mul_f32_e32 v126, v126, v126
	v_mul_f32_e32 v123, v123, v123
	v_mul_f32_e32 v124, v124, v124
	v_mul_f32_e32 v125, v125, v125
	v_cvt_pk_bf16_f32 v122, v126, v122
	v_max_f32_e32 v114, 0, v114
	v_max_f32_e32 v115, 0, v115
	v_max_f32_e32 v116, 0, v116
	v_cvt_pk_bf16_f32 v123, v123, v124
	v_cvt_pk_bf16_f32 v124, v151, v127
	v_cvt_pk_bf16_f32 v125, v128, v125
	global_store_dwordx4 v[148:149], v[122:125], off
	s_nop 1
	v_mul_f32_e32 v122, v114, v114
	v_max_f32_e32 v114, v119, v119
	v_mul_f32_e32 v119, v115, v115
	v_max_f32_e32 v115, v120, v120
	v_mul_f32_e32 v120, v116, v116
	v_max_f32_e32 v116, v121, v121
	v_max_f32_e32 v114, 0, v114
	v_max_f32_e32 v115, 0, v115
	v_max_f32_e32 v116, 0, v116
	v_max_f32_e32 v118, 0, v118
	v_mul_f32_e32 v114, v114, v114
	v_mul_f32_e32 v115, v115, v115
	v_max_f32_e32 v117, 0, v117
	v_mul_f32_e32 v116, v116, v116
	v_mul_f32_e32 v118, v118, v118
	v_mul_f32_e32 v117, v117, v117
	v_cvt_pk_bf16_f32 v114, v118, v114
	v_cvt_pk_bf16_f32 v115, v115, v116
	v_cvt_pk_bf16_f32 v116, v122, v119
	v_max_f32_e32 v106, 0, v106
	v_cvt_pk_bf16_f32 v117, v120, v117
	global_store_dwordx4 v[148:149], v[114:117], off offset:256
	s_nop 1
	v_max_f32_e32 v107, 0, v107
	v_max_f32_e32 v108, 0, v108
	v_mul_f32_e32 v116, v106, v106
	v_max_f32_e32 v106, v111, v111
	v_or_b32_e32 v114, 16, v150
	v_max_f32_e32 v106, 0, v106
	v_mul_f32_e32 v111, v107, v107
	v_max_f32_e32 v107, v112, v112
	v_mul_f32_e32 v112, v108, v108
	v_max_f32_e32 v108, v113, v113
	v_mad_i64_i32 v[114:115], s[2:3], v114, s8, v[140:141]
	v_max_f32_e32 v110, 0, v110
	v_mul_f32_e32 v106, v106, v106
	v_max_f32_e32 v107, 0, v107
	v_max_f32_e32 v108, 0, v108
	v_max_f32_e32 v109, 0, v109
	v_lshl_add_u64 v[114:115], v[114:115], 0, v[142:143]
	v_mul_f32_e32 v110, v110, v110
	v_mul_f32_e32 v107, v107, v107
	v_mul_f32_e32 v108, v108, v108
	v_mul_f32_e32 v109, v109, v109
	v_cvt_pk_bf16_f32 v106, v110, v106
	v_max_f32_e32 v98, 0, v98
	v_max_f32_e32 v99, 0, v99
	v_max_f32_e32 v100, 0, v100
	v_cvt_pk_bf16_f32 v107, v107, v108
	v_cvt_pk_bf16_f32 v108, v116, v111
	v_cvt_pk_bf16_f32 v109, v112, v109
	global_store_dwordx4 v[114:115], v[106:109], off
	s_nop 1
; __device__ __forceinline__ unsigned cvt_pk_bf16(float lo, float hi) { unsigned r; asm volatile("v_cvt_pk_bf16_f32 %0, %1, %2" : "=v"(r) : "v"(lo), "v"(hi)); return r; }
;     __device__ __forceinline__ void operator()(const f32x4 (&acc)[2][2][4][2], const Unit& u, int wr, int wc, int fr, int fq) const {
;         const int row0 = u.pm * BM + wr * 64 + fr, col0 = u.pn * BM + wc * 32 + 8 * fq;
; #pragma unroll
;         for (int ai = 0; ai < 2; ++ai)
; #pragma unroll
;             for (int m = 0; m < 4; ++m) { bf16_t* rowp = O + (size_t)(row0 + ai * HALF + m * 16) * LDF + col0;
; #pragma unroll
;                 for (int bj = 0; bj < 2; ++bj) { f32x4 v0 = acc[ai][bj][m][0], v1 = acc[ai][bj][m][1];
; #pragma unroll
;                     for (int j = 0; j < 4; ++j) { const float a = fmaxf(v0[j], 0.f), b = fmaxf(v1[j], 0.f); v0[j] = a * a; v1[j] = b * b; }
;                     u32x4 w; w.x = cvt_pk_bf16(v0[0], v0[1]); w.y = cvt_pk_bf16(v0[2], v0[3]); w.z = cvt_pk_bf16(v1[0], v1[1]); w.w = cvt_pk_bf16(v1[2], v1[3]);
;                     *(u32x4*)(rowp + bj * HALF) = w; } }
	v_mul_f32_e32 v106, v98, v98
	v_max_f32_e32 v98, v103, v103
	v_mul_f32_e32 v103, v99, v99
	v_max_f32_e32 v99, v104, v104
	v_mul_f32_e32 v104, v100, v100
	v_max_f32_e32 v100, v105, v105
	v_max_f32_e32 v98, 0, v98
	v_max_f32_e32 v99, 0, v99
	v_max_f32_e32 v100, 0, v100
	v_max_f32_e32 v102, 0, v102
	v_mul_f32_e32 v98, v98, v98
	v_mul_f32_e32 v99, v99, v99
	v_max_f32_e32 v101, 0, v101
	v_mul_f32_e32 v100, v100, v100
	v_mul_f32_e32 v102, v102, v102
	v_mul_f32_e32 v101, v101, v101
	v_cvt_pk_bf16_f32 v98, v102, v98
	v_cvt_pk_bf16_f32 v99, v99, v100
	v_cvt_pk_bf16_f32 v100, v106, v103
	v_max_f32_e32 v90, 0, v90
	v_cvt_pk_bf16_f32 v101, v104, v101
	global_store_dwordx4 v[114:115], v[98:101], off offset:256
	s_nop 1
	v_max_f32_e32 v91, 0, v91
	v_max_f32_e32 v92, 0, v92
	v_mul_f32_e32 v100, v90, v90
	v_max_f32_e32 v90, v95, v95
	v_or_b32_e32 v98, 32, v150
	v_max_f32_e32 v90, 0, v90
	v_mul_f32_e32 v95, v91, v91
	v_max_f32_e32 v91, v96, v96
	v_mul_f32_e32 v96, v92, v92
	v_max_f32_e32 v92, v97, v97
	v_mad_i64_i32 v[98:99], s[2:3], v98, s8, v[140:141]
	v_max_f32_e32 v94, 0, v94
	v_mul_f32_e32 v90, v90, v90
	v_max_f32_e32 v91, 0, v91
	v_max_f32_e32 v92, 0, v92
	v_max_f32_e32 v93, 0, v93
	v_lshl_add_u64 v[98:99], v[98:99], 0, v[142:143]
	v_mul_f32_e32 v94, v94, v94
	v_mul_f32_e32 v91, v91, v91
	v_mul_f32_e32 v92, v92, v92
	v_mul_f32_e32 v93, v93, v93
	v_cvt_pk_bf16_f32 v90, v94, v90
	v_max_f32_e32 v82, 0, v82
	v_max_f32_e32 v83, 0, v83
	v_max_f32_e32 v84, 0, v84
	v_cvt_pk_bf16_f32 v91, v91, v92
	v_cvt_pk_bf16_f32 v92, v100, v95
	v_cvt_pk_bf16_f32 v93, v96, v93
	global_store_dwordx4 v[98:99], v[90:93], off
	s_nop 1
	v_mul_f32_e32 v90, v82, v82
	v_max_f32_e32 v82, v87, v87
	v_mul_f32_e32 v87, v83, v83
	v_max_f32_e32 v83, v88, v88
	v_mul_f32_e32 v88, v84, v84
	v_max_f32_e32 v84, v89, v89
	v_max_f32_e32 v82, 0, v82
	v_max_f32_e32 v83, 0, v83
	v_max_f32_e32 v84, 0, v84
	v_max_f32_e32 v86, 0, v86
	v_mul_f32_e32 v82, v82, v82
	v_mul_f32_e32 v83, v83, v83
	v_max_f32_e32 v85, 0, v85
	v_mul_f32_e32 v84, v84, v84
	v_mul_f32_e32 v86, v86, v86
	v_mul_f32_e32 v85, v85, v85
	v_cvt_pk_bf16_f32 v82, v86, v82
	v_cvt_pk_bf16_f32 v83, v83, v84
	v_cvt_pk_bf16_f32 v84, v90, v87
	v_max_f32_e32 v74, 0, v74
	v_cvt_pk_bf16_f32 v85, v88, v85
	global_store_dwordx4 v[98:99], v[82:85], off offset:256
	s_nop 1
	v_max_f32_e32 v75, 0, v75
	v_max_f32_e32 v76, 0, v76
	v_mul_f32_e32 v84, v74, v74
	v_max_f32_e32 v74, v79, v79
	v_or_b32_e32 v82, 48, v150
	v_max_f32_e32 v74, 0, v74
	v_mul_f32_e32 v79, v75, v75
	v_max_f32_e32 v75, v80, v80
	v_mul_f32_e32 v80, v76, v76
	v_max_f32_e32 v76, v81, v81
	v_mad_i64_i32 v[82:83], s[2:3], v82, s8, v[140:141]
	v_max_f32_e32 v78, 0, v78
	v_mul_f32_e32 v74, v74, v74
	v_max_f32_e32 v75, 0, v75
	v_max_f32_e32 v76, 0, v76
	v_max_f32_e32 v77, 0, v77
	v_lshl_add_u64 v[82:83], v[82:83], 0, v[142:143]
	v_mul_f32_e32 v78, v78, v78
	v_mul_f32_e32 v75, v75, v75
	v_mul_f32_e32 v76, v76, v76
	v_mul_f32_e32 v77, v77, v77
	v_cvt_pk_bf16_f32 v74, v78, v74
	v_max_f32_e32 v66, 0, v66
	v_max_f32_e32 v67, 0, v67
	v_max_f32_e32 v68, 0, v68
	v_cvt_pk_bf16_f32 v75, v75, v76
	v_cvt_pk_bf16_f32 v76, v84, v79
	v_cvt_pk_bf16_f32 v77, v80, v77
	global_store_dwordx4 v[82:83], v[74:77], off
	s_nop 1
	v_mul_f32_e32 v74, v66, v66
	v_max_f32_e32 v66, v71, v71
	v_mul_f32_e32 v71, v67, v67
	v_max_f32_e32 v67, v72, v72
	v_mul_f32_e32 v72, v68, v68
	v_max_f32_e32 v68, v73, v73
	v_max_f32_e32 v66, 0, v66
	v_max_f32_e32 v67, 0, v67
	v_max_f32_e32 v68, 0, v68
	v_max_f32_e32 v70, 0, v70
	v_mul_f32_e32 v66, v66, v66
	v_mul_f32_e32 v67, v67, v67
	v_max_f32_e32 v69, 0, v69
	v_mul_f32_e32 v68, v68, v68
	v_mul_f32_e32 v70, v70, v70
	v_mul_f32_e32 v69, v69, v69
	v_cvt_pk_bf16_f32 v66, v70, v66
	v_cvt_pk_bf16_f32 v67, v67, v68
	v_cvt_pk_bf16_f32 v68, v74, v71
	v_max_f32_e32 v56, 0, v56
	v_cvt_pk_bf16_f32 v69, v72, v69
	global_store_dwordx4 v[82:83], v[66:69], off offset:256
	s_nop 1
	v_max_f32_e32 v57, 0, v57
	v_max_f32_e32 v58, 0, v58
	v_mul_f32_e32 v68, v56, v56
	v_max_f32_e32 v56, v61, v61
	v_add_u32_e32 v66, 0x80, v150
	v_max_f32_e32 v56, 0, v56
	v_mul_f32_e32 v61, v57, v57
	v_max_f32_e32 v57, v62, v62
	v_mul_f32_e32 v62, v58, v58
	v_max_f32_e32 v58, v63, v63
	v_mad_i64_i32 v[66:67], s[2:3], v66, s8, v[140:141]
	v_max_f32_e32 v60, 0, v60
	v_mul_f32_e32 v56, v56, v56
	v_max_f32_e32 v57, 0, v57
	v_max_f32_e32 v58, 0, v58
	v_max_f32_e32 v59, 0, v59
	v_lshl_add_u64 v[66:67], v[66:67], 0, v[142:143]
	v_mul_f32_e32 v60, v60, v60
	v_mul_f32_e32 v57, v57, v57
	v_mul_f32_e32 v58, v58, v58
	v_mul_f32_e32 v59, v59, v59
	v_cvt_pk_bf16_f32 v56, v60, v56
	v_max_f32_e32 v48, 0, v48
	v_max_f32_e32 v49, 0, v49
	v_max_f32_e32 v50, 0, v50
	v_cvt_pk_bf16_f32 v57, v57, v58
	v_cvt_pk_bf16_f32 v58, v68, v61
	v_cvt_pk_bf16_f32 v59, v62, v59
	global_store_dwordx4 v[66:67], v[56:59], off
	s_nop 1
	v_mul_f32_e32 v56, v48, v48
	v_max_f32_e32 v48, v53, v53
	v_mul_f32_e32 v53, v49, v49
	v_max_f32_e32 v49, v54, v54
	v_mul_f32_e32 v54, v50, v50
	v_max_f32_e32 v50, v55, v55
	v_max_f32_e32 v48, 0, v48
	v_max_f32_e32 v49, 0, v49
	v_max_f32_e32 v50, 0, v50
	v_max_f32_e32 v52, 0, v52
	v_mul_f32_e32 v48, v48, v48
	v_mul_f32_e32 v49, v49, v49
	v_max_f32_e32 v51, 0, v51
	v_mul_f32_e32 v50, v50, v50
	v_mul_f32_e32 v52, v52, v52
	v_mul_f32_e32 v51, v51, v51
	v_cvt_pk_bf16_f32 v48, v52, v48
; __device__ __forceinline__ unsigned cvt_pk_bf16(float lo, float hi) { unsigned r; asm volatile("v_cvt_pk_bf16_f32 %0, %1, %2" : "=v"(r) : "v"(lo), "v"(hi)); return r; }
; #define PG8_WAIT_V(n) asm volatile("s_waitcnt vmcnt(" #n ")" ::: "memory")
; #define PG8_BAR __builtin_amdgcn_s_barrier()
;     __device__ __forceinline__ void operator()(const f32x4 (&acc)[2][2][4][2], const Unit& u, int wr, int wc, int fr, int fq) const {
;     ...
;             for (int m = 0; m < 4; ++m) { bf16_t* rowp = O + (size_t)(row0 + ai * HALF + m * 16) * LDF + col0;
; #pragma unroll
;                 for (int bj = 0; bj < 2; ++bj) { f32x4 v0 = acc[ai][bj][m][0], v1 = acc[ai][bj][m][1];
; #pragma unroll
;                     for (int j = 0; j < 4; ++j) { const float a = fmaxf(v0[j], 0.f), b = fmaxf(v1[j], 0.f); v0[j] = a * a; v1[j] = b * b; }
;                     u32x4 w; w.x = cvt_pk_bf16(v0[0], v0[1]); w.y = cvt_pk_bf16(v0[2], v0[3]); w.z = cvt_pk_bf16(v1[0], v1[1]); w.w = cvt_pk_bf16(v1[2], v1[3]);
;                     *(u32x4*)(rowp + bj * HALF) = w; } }
;     ...
;         cur = nxt; cA = nA; cB = nB; ++ui;
;     }
;     PG8_WAIT_V(0);
;     if (wr == 0) PG8_BAR;
;     PG8_BAR;
	v_cvt_pk_bf16_f32 v49, v49, v50
	v_cvt_pk_bf16_f32 v50, v56, v53
	v_max_f32_e32 v40, 0, v40
	v_cvt_pk_bf16_f32 v51, v54, v51
	global_store_dwordx4 v[66:67], v[48:51], off offset:256
	s_nop 1
	v_max_f32_e32 v41, 0, v41
	v_max_f32_e32 v42, 0, v42
	v_mul_f32_e32 v50, v40, v40
	v_max_f32_e32 v40, v45, v45
	v_add_u32_e32 v48, 0x90, v150
	v_max_f32_e32 v40, 0, v40
	v_mul_f32_e32 v45, v41, v41
	v_max_f32_e32 v41, v46, v46
	v_mul_f32_e32 v46, v42, v42
	v_max_f32_e32 v42, v47, v47
	v_mad_i64_i32 v[48:49], s[2:3], v48, s8, v[140:141]
	v_max_f32_e32 v44, 0, v44
	v_mul_f32_e32 v40, v40, v40
	v_max_f32_e32 v41, 0, v41
	v_max_f32_e32 v42, 0, v42
	v_max_f32_e32 v43, 0, v43
	v_lshl_add_u64 v[48:49], v[48:49], 0, v[142:143]
	v_mul_f32_e32 v44, v44, v44
	v_mul_f32_e32 v41, v41, v41
	v_mul_f32_e32 v42, v42, v42
	v_mul_f32_e32 v43, v43, v43
	v_cvt_pk_bf16_f32 v40, v44, v40
	v_max_f32_e32 v32, 0, v32
	v_max_f32_e32 v33, 0, v33
	v_max_f32_e32 v34, 0, v34
	v_cvt_pk_bf16_f32 v41, v41, v42
	v_cvt_pk_bf16_f32 v42, v50, v45
	v_cvt_pk_bf16_f32 v43, v46, v43
	global_store_dwordx4 v[48:49], v[40:43], off
	s_nop 1
	v_mul_f32_e32 v40, v32, v32
	v_max_f32_e32 v32, v37, v37
	v_mul_f32_e32 v37, v33, v33
	v_max_f32_e32 v33, v38, v38
	v_mul_f32_e32 v38, v34, v34
	v_max_f32_e32 v34, v39, v39
	v_max_f32_e32 v32, 0, v32
	v_max_f32_e32 v33, 0, v33
	v_max_f32_e32 v34, 0, v34
	v_max_f32_e32 v36, 0, v36
	v_mul_f32_e32 v32, v32, v32
	v_mul_f32_e32 v33, v33, v33
	v_max_f32_e32 v35, 0, v35
	v_mul_f32_e32 v34, v34, v34
	v_mul_f32_e32 v36, v36, v36
	v_mul_f32_e32 v35, v35, v35
	v_cvt_pk_bf16_f32 v32, v36, v32
	v_cvt_pk_bf16_f32 v33, v33, v34
	v_cvt_pk_bf16_f32 v34, v40, v37
	v_max_f32_e32 v24, 0, v24
	v_cvt_pk_bf16_f32 v35, v38, v35
	global_store_dwordx4 v[48:49], v[32:35], off offset:256
	s_nop 1
	v_max_f32_e32 v25, 0, v25
	v_max_f32_e32 v26, 0, v26
	v_mul_f32_e32 v34, v24, v24
	v_max_f32_e32 v24, v29, v29
	v_add_u32_e32 v32, 0xa0, v150
	v_max_f32_e32 v24, 0, v24
	v_mul_f32_e32 v29, v25, v25
	v_max_f32_e32 v25, v30, v30
	v_mul_f32_e32 v30, v26, v26
	v_max_f32_e32 v26, v31, v31
	v_mad_i64_i32 v[32:33], s[2:3], v32, s8, v[140:141]
	v_max_f32_e32 v28, 0, v28
	v_mul_f32_e32 v24, v24, v24
	v_max_f32_e32 v25, 0, v25
	v_max_f32_e32 v26, 0, v26
	v_max_f32_e32 v27, 0, v27
	v_lshl_add_u64 v[32:33], v[32:33], 0, v[142:143]
	v_mul_f32_e32 v28, v28, v28
	v_mul_f32_e32 v25, v25, v25
	v_mul_f32_e32 v26, v26, v26
	v_mul_f32_e32 v27, v27, v27
	v_cvt_pk_bf16_f32 v24, v28, v24
	v_max_f32_e32 v16, 0, v16
	v_max_f32_e32 v17, 0, v17
	v_max_f32_e32 v18, 0, v18
	v_cvt_pk_bf16_f32 v25, v25, v26
	v_cvt_pk_bf16_f32 v26, v34, v29
	v_cvt_pk_bf16_f32 v27, v30, v27
	global_store_dwordx4 v[32:33], v[24:27], off
	s_nop 1
	v_mul_f32_e32 v24, v16, v16
	v_max_f32_e32 v16, v21, v21
	v_mul_f32_e32 v21, v17, v17
	v_max_f32_e32 v17, v22, v22
	v_mul_f32_e32 v22, v18, v18
	v_max_f32_e32 v18, v23, v23
	v_max_f32_e32 v16, 0, v16
	v_max_f32_e32 v17, 0, v17
	v_max_f32_e32 v18, 0, v18
	v_max_f32_e32 v20, 0, v20
	v_mul_f32_e32 v16, v16, v16
	v_mul_f32_e32 v17, v17, v17
	v_max_f32_e32 v19, 0, v19
	v_mul_f32_e32 v18, v18, v18
	v_mul_f32_e32 v20, v20, v20
	v_mul_f32_e32 v19, v19, v19
	v_cvt_pk_bf16_f32 v16, v20, v16
	v_cvt_pk_bf16_f32 v17, v17, v18
	v_cvt_pk_bf16_f32 v18, v24, v21
	v_max_f32_e32 v8, 0, v8
	v_cvt_pk_bf16_f32 v19, v22, v19
	global_store_dwordx4 v[32:33], v[16:19], off offset:256
	s_nop 1
	v_max_f32_e32 v9, 0, v9
	v_max_f32_e32 v10, 0, v10
	v_mul_f32_e32 v18, v8, v8
	v_max_f32_e32 v8, v13, v13
	v_add_u32_e32 v16, 0xb0, v150
	v_max_f32_e32 v8, 0, v8
	v_mul_f32_e32 v13, v9, v9
	v_max_f32_e32 v9, v14, v14
	v_mul_f32_e32 v14, v10, v10
	v_max_f32_e32 v10, v15, v15
	v_mad_i64_i32 v[16:17], s[2:3], v16, s8, v[140:141]
	v_max_f32_e32 v12, 0, v12
	v_mul_f32_e32 v8, v8, v8
	v_max_f32_e32 v9, 0, v9
	v_max_f32_e32 v10, 0, v10
	v_max_f32_e32 v11, 0, v11
	v_lshl_add_u64 v[16:17], v[16:17], 0, v[142:143]
	v_mul_f32_e32 v12, v12, v12
	v_mul_f32_e32 v9, v9, v9
	v_mul_f32_e32 v10, v10, v10
	v_mul_f32_e32 v11, v11, v11
	v_cvt_pk_bf16_f32 v8, v12, v8
	v_max_f32_e32 v0, 0, v0
	v_max_f32_e32 v1, 0, v1
	v_max_f32_e32 v2, 0, v2
	v_cvt_pk_bf16_f32 v9, v9, v10
	v_cvt_pk_bf16_f32 v10, v18, v13
	v_cvt_pk_bf16_f32 v11, v14, v11
	global_store_dwordx4 v[16:17], v[8:11], off
	s_nop 1
	v_mul_f32_e32 v8, v0, v0
	v_max_f32_e32 v0, v5, v5
	v_mul_f32_e32 v5, v1, v1
	v_max_f32_e32 v1, v6, v6
	v_mul_f32_e32 v6, v2, v2
	v_max_f32_e32 v2, v7, v7
	v_max_f32_e32 v0, 0, v0
	v_max_f32_e32 v1, 0, v1
	v_max_f32_e32 v2, 0, v2
	v_max_f32_e32 v3, 0, v3
	v_max_f32_e32 v4, 0, v4
	v_mul_f32_e32 v0, v0, v0
	v_mul_f32_e32 v1, v1, v1
	v_mul_f32_e32 v2, v2, v2
	v_mul_f32_e32 v3, v3, v3
	s_and_b64 vcc, exec, s[4:5]
	s_mov_b32 s38, s34
	s_mov_b32 s37, s36
	s_mov_b32 s40, s39
	s_mov_b64 s[10:11], s[18:19]
	s_mov_b64 s[8:9], s[6:7]
	s_mov_b32 s18, s33
	v_readlane_b32 s35, v251, 41
	v_mul_f32_e32 v4, v4, v4
	v_cvt_pk_bf16_f32 v0, v4, v0
	v_cvt_pk_bf16_f32 v1, v1, v2
	v_cvt_pk_bf16_f32 v2, v8, v5
	v_cvt_pk_bf16_f32 v3, v6, v3
	global_store_dwordx4 v[16:17], v[0:3], off offset:256
	s_nop 1
	s_cbranch_vccz .LBB0_96
	s_waitcnt vmcnt(0)
	v_readlane_b32 s40, v251, 24
	v_readlane_b32 s28, v252, 58
	s_cmpk_gt_u32 s15, 0xff
	s_movk_i32 s27, 0x1000
	v_readlane_b32 s41, v251, 25
	v_readlane_b32 s29, v252, 59
	s_cbranch_scc1 .LBB0_124
	s_barrier

; #define PG8_STAGE(bufoff, gbase, voff) do { _Pragma("unroll") for (int _i = 0; _i < 2; ++_i) \
;         __builtin_amdgcn_global_load_lds((const unsigned*)((const char*)(gbase) + (voff)[_i]), (LAS unsigned*)(lds + (bufoff) + ldsw + _i * 8192), 16, 0, 0); } while (0)
; #define PG8_LDA(dst, b, h) do { _Pragma("unroll") for (int m = 0; m < 4; ++m) _Pragma("unroll") for (int k = 0; k < 2; ++k) dst[m][k] = *(const LAS bf16x8*)(lds + PG8_SA(b, h) + aoff + m * 2048 + k * 1024); } while (0)
; #define PG8_LDB(dst, b, h) do { _Pragma("unroll") for (int n = 0; n < 2; ++n) _Pragma("unroll") for (int k = 0; k < 2; ++k) dst[n][k] = *(const LAS bf16x8*)(lds + PG8_SB(b, h) + boff + n * 2048 + k * 1024); } while (0)
; #define PG8_MMA(ai, bj, At, Bt) do { __builtin_amdgcn_s_setprio(1); _Pragma("unroll") for (int m = 0; m < 4; ++m) _Pragma("unroll") for (int n = 0; n < 2; ++n) _Pragma("unroll") for (int k = 0; k < 2; ++k) \
;         acc[ai][bj][m][n] = __builtin_amdgcn_mfma_f32_16x16x32_bf16(Bt[n][k], At[m][k], acc[ai][bj][m][n], 0, 0, 0); __builtin_amdgcn_s_setprio(0); } while (0)
; #define PG8_WAIT_L(n) asm volatile("s_waitcnt lgkmcnt(" #n ")" ::: "memory")
; #define PG8_BAR __builtin_amdgcn_s_barrier()
; #define PG8_SCHED __builtin_amdgcn_sched_barrier(0)
;     ...
;             const char* a1 = cA + (size_t)(t + 1) * kstep;
;             const char* a2 = last ? nA : cA + (size_t)(t + 2) * kstep; const char* b2 = last ? nB : cB + (size_t)(t + 2) * kstep;
;             const char* a3 = a2 + kstep; const char* b3 = b2 + kstep;
;             PG8_LDB(B0, 0, 0); PG8_SCHED; PG8_LDA(At, 0, 0); PG8_STAGE(PG8_SA(1, 1), a1 + hstep, voffA);
;             PG8_WAIT_L(8); PG8_BAR; PG8_WAIT_L(0); PG8_MMA(0, 0, At, B0); PG8_BAR; PG8_SCHED;
;             PG8_LDB(B1, 0, 1); PG8_STAGE(PG8_SB(0, 0), b2, voffB);
;             PG8_BAR; PG8_WAIT_L(0); PG8_MMA(0, 1, At, B1); PG8_BAR;
;             PG8_LDA(At, 0, 1); PG8_STAGE(PG8_SA(0, 0), a2, voffA);
;             PG8_BAR; PG8_WAIT_L(0); PG8_MMA(1, 0, At, B0); PG8_BAR; PG8_SCHED;
.LBB0_146:
	s_add_u32 s2, s8, 0xe515c080
	s_addc_u32 s3, s9, -1
	s_cmp_lg_u32 s27, 28
	s_cselect_b32 s10, s2, 0
	s_cselect_b32 s11, s3, 0
	s_add_u32 s2, s6, s10
	s_addc_u32 s3, s7, s11
	s_add_i32 s28, 0, 0x10000
	v_add_u32_e32 v156, s28, v142
	ds_read_b128 v[144:147], v156
	ds_read_b128 v[148:151], v156 offset:1024
	ds_read_b128 v[152:155], v156 offset:2048
	ds_read_b128 v[156:159], v156 offset:3072
	s_add_u32 s10, s4, s10
	s_addc_u32 s11, s5, s11
	v_lshl_add_u64 v[192:193], v[136:137], 0, s[8:9]
	s_add_i32 m0, s20, 0xc000
	ds_read_b128 v[160:163], v143
	ds_read_b128 v[164:167], v143 offset:1024
	ds_read_b128 v[168:171], v143 offset:2048
	ds_read_b128 v[172:175], v143 offset:3072
	ds_read_b128 v[176:179], v143 offset:4096
	ds_read_b128 v[180:183], v143 offset:5120
	ds_read_b128 v[184:187], v143 offset:6144
	ds_read_b128 v[188:191], v143 offset:7168
	global_load_lds_dwordx4 v[192:193], off
	v_lshl_add_u64 v[192:193], v[138:139], 0, s[8:9]
	s_add_i32 m0, s20, 0xe000
	s_nop 0
	global_load_lds_dwordx4 v[192:193], off
	s_waitcnt lgkmcnt(8)
	s_barrier
	s_waitcnt lgkmcnt(0)
	v_mfma_f32_16x16x32_bf16 v[126:129], v[144:147], v[160:163], v[126:129]
	v_mfma_f32_16x16x32_bf16 v[122:125], v[152:155], v[160:163], v[122:125]
	v_mfma_f32_16x16x32_bf16 v[110:113], v[144:147], v[168:171], v[110:113]
	v_mfma_f32_16x16x32_bf16 v[106:109], v[152:155], v[168:171], v[106:109]
	v_mfma_f32_16x16x32_bf16 v[94:97], v[144:147], v[176:179], v[94:97]
	v_mfma_f32_16x16x32_bf16 v[90:93], v[152:155], v[176:179], v[90:93]
	v_mfma_f32_16x16x32_bf16 v[78:81], v[144:147], v[184:187], v[78:81]
	v_mfma_f32_16x16x32_bf16 v[74:77], v[152:155], v[184:187], v[74:77]
	v_mfma_f32_16x16x32_bf16 v[126:129], v[148:151], v[164:167], v[126:129]
	v_mfma_f32_16x16x32_bf16 v[122:125], v[156:159], v[164:167], v[122:125]
	v_mfma_f32_16x16x32_bf16 v[110:113], v[148:151], v[172:175], v[110:113]
	v_mfma_f32_16x16x32_bf16 v[106:109], v[156:159], v[172:175], v[106:109]
	v_mfma_f32_16x16x32_bf16 v[94:97], v[148:151], v[180:183], v[94:97]
	v_mfma_f32_16x16x32_bf16 v[90:93], v[156:159], v[180:183], v[90:93]
	v_mfma_f32_16x16x32_bf16 v[78:81], v[148:151], v[188:191], v[78:81]
	v_mfma_f32_16x16x32_bf16 v[74:77], v[156:159], v[188:191], v[74:77]
	s_barrier
	s_add_i32 s31, 0, 0x14000
	s_add_i32 s28, s28, s15
	v_add_u32_e32 v208, s31, v142
	v_lshl_add_u64 v[228:229], s[10:11], 0, v[64:65]
	s_mov_b32 m0, s28
	ds_read_b128 v[192:195], v208
	ds_read_b128 v[196:199], v208 offset:1024
	ds_read_b128 v[220:223], v208 offset:2048
	ds_read_b128 v[224:227], v208 offset:3072
	global_load_lds_dwordx4 v[228:229], off
	v_lshl_add_u64 v[230:231], s[10:11], 0, v[130:131]
	s_add_i32 m0, s28, 0x2000
	s_nop 0
	global_load_lds_dwordx4 v[230:231], off
	s_barrier
	s_waitcnt lgkmcnt(0)
	v_mfma_f32_16x16x32_bf16 v[118:121], v[192:195], v[160:163], v[118:121]
	v_mfma_f32_16x16x32_bf16 v[114:117], v[220:223], v[160:163], v[114:117]
	v_mfma_f32_16x16x32_bf16 v[102:105], v[192:195], v[168:171], v[102:105]
	v_mfma_f32_16x16x32_bf16 v[98:101], v[220:223], v[168:171], v[98:101]
	v_mfma_f32_16x16x32_bf16 v[86:89], v[192:195], v[176:179], v[86:89]
	v_mfma_f32_16x16x32_bf16 v[82:85], v[220:223], v[176:179], v[82:85]
	v_mfma_f32_16x16x32_bf16 v[70:73], v[192:195], v[184:187], v[70:73]
	v_mfma_f32_16x16x32_bf16 v[66:69], v[220:223], v[184:187], v[66:69]
	v_mfma_f32_16x16x32_bf16 v[118:121], v[196:199], v[164:167], v[118:121]
	v_mfma_f32_16x16x32_bf16 v[114:117], v[224:227], v[164:167], v[114:117]
	v_mfma_f32_16x16x32_bf16 v[102:105], v[196:199], v[172:175], v[102:105]
	v_mfma_f32_16x16x32_bf16 v[98:101], v[224:227], v[172:175], v[98:101]
	v_mfma_f32_16x16x32_bf16 v[86:89], v[196:199], v[180:183], v[86:89]
	v_mfma_f32_16x16x32_bf16 v[82:85], v[224:227], v[180:183], v[82:85]
	v_mfma_f32_16x16x32_bf16 v[70:73], v[196:199], v[188:191], v[70:73]
	v_mfma_f32_16x16x32_bf16 v[66:69], v[224:227], v[188:191], v[66:69]
	s_barrier
	s_mov_b32 m0, s20
	v_lshl_add_u64 v[232:233], s[2:3], 0, v[134:135]
	ds_read_b128 v[160:163], v143 offset:16384
	ds_read_b128 v[164:167], v143 offset:17408
	ds_read_b128 v[168:171], v143 offset:18432
	ds_read_b128 v[172:175], v143 offset:19456
	ds_read_b128 v[176:179], v143 offset:20480
	ds_read_b128 v[180:183], v143 offset:21504
	ds_read_b128 v[184:187], v143 offset:22528
	ds_read_b128 v[188:191], v143 offset:23552
	global_load_lds_dwordx4 v[232:233], off
	v_lshl_add_u64 v[234:235], s[2:3], 0, v[132:133]
	s_mov_b32 m0, s21
	s_nop 0
	global_load_lds_dwordx4 v[234:235], off
	s_barrier
	s_waitcnt lgkmcnt(0)
	v_mfma_f32_16x16x32_bf16 v[60:63], v[144:147], v[160:163], v[60:63]
	v_mfma_f32_16x16x32_bf16 v[56:59], v[152:155], v[160:163], v[56:59]
	v_mfma_f32_16x16x32_bf16 v[44:47], v[144:147], v[168:171], v[44:47]
	v_mfma_f32_16x16x32_bf16 v[40:43], v[152:155], v[168:171], v[40:43]
	v_mfma_f32_16x16x32_bf16 v[28:31], v[144:147], v[176:179], v[28:31]
	v_mfma_f32_16x16x32_bf16 v[24:27], v[152:155], v[176:179], v[24:27]
	v_mfma_f32_16x16x32_bf16 v[12:15], v[144:147], v[184:187], v[12:15]
	v_mfma_f32_16x16x32_bf16 v[8:11], v[152:155], v[184:187], v[8:11]
	v_mfma_f32_16x16x32_bf16 v[60:63], v[148:151], v[164:167], v[60:63]
	v_mfma_f32_16x16x32_bf16 v[56:59], v[156:159], v[164:167], v[56:59]
	v_mfma_f32_16x16x32_bf16 v[44:47], v[148:151], v[172:175], v[44:47]
	v_mfma_f32_16x16x32_bf16 v[40:43], v[156:159], v[172:175], v[40:43]
	v_mfma_f32_16x16x32_bf16 v[28:31], v[148:151], v[180:183], v[28:31]
	v_mfma_f32_16x16x32_bf16 v[24:27], v[156:159], v[180:183], v[24:27]
	v_mfma_f32_16x16x32_bf16 v[12:15], v[148:151], v[188:191], v[12:15]
	v_mfma_f32_16x16x32_bf16 v[8:11], v[156:159], v[188:191], v[8:11]
	s_barrier
; #define PG8_STAGE(bufoff, gbase, voff) do { _Pragma("unroll") for (int _i = 0; _i < 2; ++_i) \
;         __builtin_amdgcn_global_load_lds((const unsigned*)((const char*)(gbase) + (voff)[_i]), (LAS unsigned*)(lds + (bufoff) + ldsw + _i * 8192), 16, 0, 0); } while (0)
; #define PG8_LDA(dst, b, h) do { _Pragma("unroll") for (int m = 0; m < 4; ++m) _Pragma("unroll") for (int k = 0; k < 2; ++k) dst[m][k] = *(const LAS bf16x8*)(lds + PG8_SA(b, h) + aoff + m * 2048 + k * 1024); } while (0)
; #define PG8_LDB(dst, b, h) do { _Pragma("unroll") for (int n = 0; n < 2; ++n) _Pragma("unroll") for (int k = 0; k < 2; ++k) dst[n][k] = *(const LAS bf16x8*)(lds + PG8_SB(b, h) + boff + n * 2048 + k * 1024); } while (0)
; #define PG8_MMA(ai, bj, At, Bt) do { __builtin_amdgcn_s_setprio(1); _Pragma("unroll") for (int m = 0; m < 4; ++m) _Pragma("unroll") for (int n = 0; n < 2; ++n) _Pragma("unroll") for (int k = 0; k < 2; ++k) \
;         acc[ai][bj][m][n] = __builtin_amdgcn_mfma_f32_16x16x32_bf16(Bt[n][k], At[m][k], acc[ai][bj][m][n], 0, 0, 0); __builtin_amdgcn_s_setprio(0); } while (0)
; #define PG8_WAIT_V(n) asm volatile("s_waitcnt vmcnt(" #n ")" ::: "memory")
; #define PG8_WAIT_L(n) asm volatile("s_waitcnt lgkmcnt(" #n ")" ::: "memory")
; #define PG8_BAR __builtin_amdgcn_s_barrier()
; #define PG8_SCHED __builtin_amdgcn_sched_barrier(0)
;     ...
;             PG8_STAGE(PG8_SB(0, 1), b2 + hstep, voffB);
;             PG8_WAIT_V(6); PG8_BAR; PG8_MMA(1, 1, At, B1); PG8_BAR;
;             PG8_LDB(B0, 1, 0); PG8_SCHED; PG8_LDA(At, 1, 0); PG8_STAGE(PG8_SA(0, 1), a2 + hstep, voffA);
;             PG8_WAIT_L(8); PG8_BAR; PG8_WAIT_L(0); PG8_MMA(0, 0, At, B0); PG8_BAR; PG8_SCHED;
;             PG8_LDB(B1, 1, 1); PG8_STAGE(PG8_SB(1, 0), b3, voffB);
;             PG8_BAR; PG8_WAIT_L(0); PG8_MMA(0, 1, At, B1); PG8_BAR;
;             PG8_LDA(At, 1, 1); PG8_STAGE(PG8_SA(1, 0), a3, voffA);
;             PG8_BAR; PG8_WAIT_L(0); PG8_MMA(1, 0, At, B0); PG8_BAR; PG8_SCHED;
	s_add_u32 s28, s10, 0x84000
	s_addc_u32 s29, s11, 0
	s_add_i32 s31, s31, s15
	v_lshl_add_u64 v[144:145], s[28:29], 0, v[64:65]
	s_mov_b32 m0, s31
	s_nop 0
	global_load_lds_dwordx4 v[144:145], off
	v_lshl_add_u64 v[144:145], s[28:29], 0, v[130:131]
	s_add_i32 m0, s31, 0x2000
	s_nop 0
	global_load_lds_dwordx4 v[144:145], off
	s_waitcnt vmcnt(6)
	s_barrier
	v_mfma_f32_16x16x32_bf16 v[52:55], v[192:195], v[160:163], v[52:55]
	v_mfma_f32_16x16x32_bf16 v[48:51], v[220:223], v[160:163], v[48:51]
	v_mfma_f32_16x16x32_bf16 v[36:39], v[192:195], v[168:171], v[36:39]
	v_mfma_f32_16x16x32_bf16 v[32:35], v[220:223], v[168:171], v[32:35]
	v_mfma_f32_16x16x32_bf16 v[20:23], v[192:195], v[176:179], v[20:23]
	v_mfma_f32_16x16x32_bf16 v[16:19], v[220:223], v[176:179], v[16:19]
	v_mfma_f32_16x16x32_bf16 v[4:7], v[192:195], v[184:187], v[4:7]
	v_mfma_f32_16x16x32_bf16 v[0:3], v[220:223], v[184:187], v[0:3]
	v_mfma_f32_16x16x32_bf16 v[52:55], v[196:199], v[164:167], v[52:55]
	v_mfma_f32_16x16x32_bf16 v[48:51], v[224:227], v[164:167], v[48:51]
	v_mfma_f32_16x16x32_bf16 v[36:39], v[196:199], v[172:175], v[36:39]
	v_mfma_f32_16x16x32_bf16 v[32:35], v[224:227], v[172:175], v[32:35]
	v_mfma_f32_16x16x32_bf16 v[20:23], v[196:199], v[180:183], v[20:23]
	v_mfma_f32_16x16x32_bf16 v[16:19], v[224:227], v[180:183], v[16:19]
	v_mfma_f32_16x16x32_bf16 v[4:7], v[196:199], v[188:191], v[4:7]
	v_mfma_f32_16x16x32_bf16 v[0:3], v[224:227], v[188:191], v[0:3]
	s_barrier
	s_add_i32 s28, 0, 0x18000
	v_add_u32_e32 v156, s28, v142
	ds_read_b128 v[144:147], v156
	ds_read_b128 v[148:151], v156 offset:1024
	ds_read_b128 v[152:155], v156 offset:2048
	ds_read_b128 v[156:159], v156 offset:3072
	s_add_u32 s2, s2, 0x84000
	s_addc_u32 s3, s3, 0
	s_mov_b32 m0, s22
	v_lshl_add_u64 v[192:193], s[2:3], 0, v[134:135]
	ds_read_b128 v[160:163], v143 offset:32768
	ds_read_b128 v[164:167], v143 offset:33792
	ds_read_b128 v[168:171], v143 offset:34816
	ds_read_b128 v[172:175], v143 offset:35840
	ds_read_b128 v[176:179], v143 offset:36864
	ds_read_b128 v[180:183], v143 offset:37888
	ds_read_b128 v[184:187], v143 offset:38912
	ds_read_b128 v[188:191], v143 offset:39936
	global_load_lds_dwordx4 v[192:193], off
	v_lshl_add_u64 v[192:193], s[2:3], 0, v[132:133]
	s_mov_b32 m0, s23
	s_nop 0
	global_load_lds_dwordx4 v[192:193], off
	s_waitcnt lgkmcnt(8)
	s_barrier
	s_waitcnt lgkmcnt(0)
	v_mfma_f32_16x16x32_bf16 v[126:129], v[144:147], v[160:163], v[126:129]
	v_mfma_f32_16x16x32_bf16 v[122:125], v[152:155], v[160:163], v[122:125]
	v_mfma_f32_16x16x32_bf16 v[110:113], v[144:147], v[168:171], v[110:113]
	v_mfma_f32_16x16x32_bf16 v[106:109], v[152:155], v[168:171], v[106:109]
	v_mfma_f32_16x16x32_bf16 v[94:97], v[144:147], v[176:179], v[94:97]
	v_mfma_f32_16x16x32_bf16 v[90:93], v[152:155], v[176:179], v[90:93]
	v_mfma_f32_16x16x32_bf16 v[78:81], v[144:147], v[184:187], v[78:81]
	v_mfma_f32_16x16x32_bf16 v[74:77], v[152:155], v[184:187], v[74:77]
	v_mfma_f32_16x16x32_bf16 v[126:129], v[148:151], v[164:167], v[126:129]
	v_mfma_f32_16x16x32_bf16 v[122:125], v[156:159], v[164:167], v[122:125]
	v_mfma_f32_16x16x32_bf16 v[110:113], v[148:151], v[172:175], v[110:113]
	v_mfma_f32_16x16x32_bf16 v[106:109], v[156:159], v[172:175], v[106:109]
	v_mfma_f32_16x16x32_bf16 v[94:97], v[148:151], v[180:183], v[94:97]
	v_mfma_f32_16x16x32_bf16 v[90:93], v[156:159], v[180:183], v[90:93]
	v_mfma_f32_16x16x32_bf16 v[78:81], v[148:151], v[188:191], v[78:81]
	v_mfma_f32_16x16x32_bf16 v[74:77], v[156:159], v[188:191], v[74:77]
	s_barrier
	s_add_i32 s29, 0, 0x1c000
	s_add_i32 s2, s28, s15
	v_add_u32_e32 v208, s29, v142
	v_lshl_add_u64 v[228:229], v[228:229], 0, s[16:17]
	s_mov_b32 m0, s2
	ds_read_b128 v[192:195], v208
	ds_read_b128 v[196:199], v208 offset:1024
	ds_read_b128 v[220:223], v208 offset:2048
	ds_read_b128 v[224:227], v208 offset:3072
	global_load_lds_dwordx4 v[228:229], off
	v_lshl_add_u64 v[228:229], v[230:231], 0, s[16:17]
	s_add_i32 m0, s2, 0x2000
	s_nop 0
	global_load_lds_dwordx4 v[228:229], off
	s_barrier
	s_waitcnt lgkmcnt(0)
	v_mfma_f32_16x16x32_bf16 v[118:121], v[192:195], v[160:163], v[118:121]
	v_mfma_f32_16x16x32_bf16 v[114:117], v[220:223], v[160:163], v[114:117]
	v_mfma_f32_16x16x32_bf16 v[102:105], v[192:195], v[168:171], v[102:105]
	v_mfma_f32_16x16x32_bf16 v[98:101], v[220:223], v[168:171], v[98:101]
	v_mfma_f32_16x16x32_bf16 v[86:89], v[192:195], v[176:179], v[86:89]
	v_mfma_f32_16x16x32_bf16 v[82:85], v[220:223], v[176:179], v[82:85]
	v_mfma_f32_16x16x32_bf16 v[70:73], v[192:195], v[184:187], v[70:73]
	v_mfma_f32_16x16x32_bf16 v[66:69], v[220:223], v[184:187], v[66:69]
	v_mfma_f32_16x16x32_bf16 v[118:121], v[196:199], v[164:167], v[118:121]
	v_mfma_f32_16x16x32_bf16 v[114:117], v[224:227], v[164:167], v[114:117]
	v_mfma_f32_16x16x32_bf16 v[102:105], v[196:199], v[172:175], v[102:105]
	v_mfma_f32_16x16x32_bf16 v[98:101], v[224:227], v[172:175], v[98:101]
	v_mfma_f32_16x16x32_bf16 v[86:89], v[196:199], v[180:183], v[86:89]
	v_mfma_f32_16x16x32_bf16 v[82:85], v[224:227], v[180:183], v[82:85]
	v_mfma_f32_16x16x32_bf16 v[70:73], v[196:199], v[188:191], v[70:73]
	v_mfma_f32_16x16x32_bf16 v[66:69], v[224:227], v[188:191], v[66:69]
	s_barrier
	s_mov_b32 m0, s25
	v_lshl_add_u64 v[228:229], v[232:233], 0, s[16:17]
	ds_read_b128 v[160:163], v143 offset:49152
	ds_read_b128 v[164:167], v143 offset:50176
	ds_read_b128 v[168:171], v143 offset:51200
	ds_read_b128 v[172:175], v143 offset:52224
	ds_read_b128 v[176:179], v143 offset:53248
	ds_read_b128 v[180:183], v143 offset:54272
	ds_read_b128 v[184:187], v143 offset:55296
	ds_read_b128 v[188:191], v143 offset:56320
	global_load_lds_dwordx4 v[228:229], off
	v_lshl_add_u64 v[228:229], v[234:235], 0, s[16:17]
	s_mov_b32 m0, s26
	s_nop 0
	global_load_lds_dwordx4 v[228:229], off
	s_barrier
; __device__ __forceinline__ unsigned cvt_pk_bf16(float lo, float hi) { unsigned r; asm volatile("v_cvt_pk_bf16_f32 %0, %1, %2" : "=v"(r) : "v"(lo), "v"(hi)); return r; }
; #define PG8_STAGE(bufoff, gbase, voff) do { _Pragma("unroll") for (int _i = 0; _i < 2; ++_i) \
;         __builtin_amdgcn_global_load_lds((const unsigned*)((const char*)(gbase) + (voff)[_i]), (LAS unsigned*)(lds + (bufoff) + ldsw + _i * 8192), 16, 0, 0); } while (0)
; #define PG8_MMA(ai, bj, At, Bt) do { __builtin_amdgcn_s_setprio(1); _Pragma("unroll") for (int m = 0; m < 4; ++m) _Pragma("unroll") for (int n = 0; n < 2; ++n) _Pragma("unroll") for (int k = 0; k < 2; ++k) \
;         acc[ai][bj][m][n] = __builtin_amdgcn_mfma_f32_16x16x32_bf16(Bt[n][k], At[m][k], acc[ai][bj][m][n], 0, 0, 0); __builtin_amdgcn_s_setprio(0); } while (0)
; #define PG8_WAIT_V(n) asm volatile("s_waitcnt vmcnt(" #n ")" ::: "memory")
; #define PG8_WAIT_L(n) asm volatile("s_waitcnt lgkmcnt(" #n ")" ::: "memory")
;     __device__ __forceinline__ void operator()(const f32x4 (&acc)[2][2][4][2], const Unit& u, int wr, int wc, int fr, int fq) const {
;         const int row0 = u.pm * BM + wr * 64 + fr, col0 = u.pn * BM + wc * 32 + 8 * fq;
; #pragma unroll
;         for (int ai = 0; ai < 2; ++ai)
; #pragma unroll
;             for (int m = 0; m < 4; ++m) { bf16_t* rowp = O + (size_t)(row0 + ai * HALF + m * 16) * LDF + col0;
; #pragma unroll
;                 for (int bj = 0; bj < 2; ++bj) { f32x4 v0 = acc[ai][bj][m][0], v1 = acc[ai][bj][m][1];
; #pragma unroll
;                     for (int j = 0; j < 4; ++j) { const float a = fmaxf(v0[j], 0.f), b = fmaxf(v1[j], 0.f); v0[j] = a * a; v1[j] = b * b; }
;                     u32x4 w; w.x = cvt_pk_bf16(v0[0], v0[1]); w.y = cvt_pk_bf16(v0[2], v0[3]); w.z = cvt_pk_bf16(v1[0], v1[1]); w.w = cvt_pk_bf16(v1[2], v1[3]);
;                     *(u32x4*)(rowp + bj * HALF) = w; } }
;     ...
;             PG8_BAR; PG8_WAIT_L(0); PG8_MMA(1, 0, At, B0); PG8_BAR; PG8_SCHED;
;             PG8_STAGE(PG8_SB(1, 1), b3 + hstep, voffB);
;             PG8_WAIT_V(6); PG8_BAR; PG8_MMA(1, 1, At, B1); PG8_BAR;
;         }
;         if constexpr (Epi::FUSE_LN) {
;             if (E.fuse && cur.ks < 0) { if (wr == 0) PG8_BAR; E.fused(acc, cur, wr, wc, fr, fq, lds); if (wr == 1) PG8_BAR; }
;             else E(acc, cur, wr, wc, fr, fq);
;         } else E(acc, cur, wr, wc, fr, fq);
;         if (!has_next) break;
	s_waitcnt lgkmcnt(0)
	v_mfma_f32_16x16x32_bf16 v[60:63], v[144:147], v[160:163], v[60:63]
	v_mfma_f32_16x16x32_bf16 v[56:59], v[152:155], v[160:163], v[56:59]
	v_mfma_f32_16x16x32_bf16 v[44:47], v[144:147], v[168:171], v[44:47]
	v_mfma_f32_16x16x32_bf16 v[40:43], v[152:155], v[168:171], v[40:43]
	v_mfma_f32_16x16x32_bf16 v[28:31], v[144:147], v[176:179], v[28:31]
	v_mfma_f32_16x16x32_bf16 v[24:27], v[152:155], v[176:179], v[24:27]
	v_mfma_f32_16x16x32_bf16 v[12:15], v[144:147], v[184:187], v[12:15]
	v_mfma_f32_16x16x32_bf16 v[8:11], v[152:155], v[184:187], v[8:11]
	v_mfma_f32_16x16x32_bf16 v[60:63], v[148:151], v[164:167], v[60:63]
	v_mfma_f32_16x16x32_bf16 v[56:59], v[156:159], v[164:167], v[56:59]
	v_mfma_f32_16x16x32_bf16 v[44:47], v[148:151], v[172:175], v[44:47]
	v_mfma_f32_16x16x32_bf16 v[40:43], v[156:159], v[172:175], v[40:43]
	v_mfma_f32_16x16x32_bf16 v[28:31], v[148:151], v[180:183], v[28:31]
	v_mfma_f32_16x16x32_bf16 v[24:27], v[156:159], v[180:183], v[24:27]
	v_mfma_f32_16x16x32_bf16 v[12:15], v[148:151], v[188:191], v[12:15]
	v_mfma_f32_16x16x32_bf16 v[8:11], v[156:159], v[188:191], v[8:11]
	s_barrier
	s_add_u32 s2, s10, 0x84080
	s_addc_u32 s3, s11, 0
	s_add_i32 s10, s29, s15
	v_lshl_add_u64 v[144:145], s[2:3], 0, v[64:65]
	s_mov_b32 m0, s10
	s_nop 0
	global_load_lds_dwordx4 v[144:145], off
	v_lshl_add_u64 v[144:145], s[2:3], 0, v[130:131]
	s_add_i32 m0, s10, 0x2000
	s_nop 0
	global_load_lds_dwordx4 v[144:145], off
	s_waitcnt vmcnt(6)
	s_barrier
	v_mfma_f32_16x16x32_bf16 v[52:55], v[192:195], v[160:163], v[52:55]
	v_mfma_f32_16x16x32_bf16 v[48:51], v[220:223], v[160:163], v[48:51]
	v_mfma_f32_16x16x32_bf16 v[36:39], v[192:195], v[168:171], v[36:39]
	v_mfma_f32_16x16x32_bf16 v[32:35], v[220:223], v[168:171], v[32:35]
	v_mfma_f32_16x16x32_bf16 v[20:23], v[192:195], v[176:179], v[20:23]
	v_mfma_f32_16x16x32_bf16 v[16:19], v[220:223], v[176:179], v[16:19]
	v_mfma_f32_16x16x32_bf16 v[4:7], v[192:195], v[184:187], v[4:7]
	v_mfma_f32_16x16x32_bf16 v[0:3], v[220:223], v[184:187], v[0:3]
	v_mfma_f32_16x16x32_bf16 v[52:55], v[196:199], v[164:167], v[52:55]
	v_mfma_f32_16x16x32_bf16 v[48:51], v[224:227], v[164:167], v[48:51]
	v_mfma_f32_16x16x32_bf16 v[36:39], v[196:199], v[172:175], v[36:39]
	v_mfma_f32_16x16x32_bf16 v[32:35], v[224:227], v[172:175], v[32:35]
	v_mfma_f32_16x16x32_bf16 v[20:23], v[196:199], v[180:183], v[20:23]
	v_mfma_f32_16x16x32_bf16 v[16:19], v[224:227], v[180:183], v[16:19]
	v_mfma_f32_16x16x32_bf16 v[4:7], v[196:199], v[188:191], v[4:7]
	v_mfma_f32_16x16x32_bf16 v[0:3], v[224:227], v[188:191], v[0:3]
	s_barrier
	s_add_i32 s27, s27, 2
	s_add_u32 s8, s8, 0x100
	s_addc_u32 s9, s9, 0
	s_cmp_gt_u32 s27, 29
	s_cbranch_scc0 .LBB0_146
	s_lshl_b32 s2, s19, 8
	v_max_f32_e32 v122, 0, v122
	s_or_b32 s2, s24, s2
	v_mul_f32_e32 v135, v122, v122
	v_max_f32_e32 v122, v127, v127
	v_max_f32_e32 v123, 0, v123
	v_max_f32_e32 v124, 0, v124
	v_lshl_add_u32 v134, s18, 8, v141
	v_or_b32_e32 v64, s2, v140
	v_mov_b64_e32 v[130:131], s[80:81]
	s_movk_i32 s4, 0x4080
	v_max_f32_e32 v122, 0, v122
	v_mul_f32_e32 v127, v123, v123
	v_max_f32_e32 v123, v128, v128
	v_mul_f32_e32 v128, v124, v124
	v_max_f32_e32 v124, v129, v129
	v_mad_i64_i32 v[132:133], s[2:3], v134, s4, v[130:131]
	v_lshlrev_b32_e32 v64, 1, v64
	v_max_f32_e32 v126, 0, v126
	v_mul_f32_e32 v122, v122, v122
	v_max_f32_e32 v123, 0, v123
	v_max_f32_e32 v124, 0, v124
	v_max_f32_e32 v125, 0, v125
	v_lshl_add_u64 v[132:133], v[132:133], 0, v[64:65]
	v_mul_f32_e32 v126, v126, v126
	v_mul_f32_e32 v123, v123, v123
	v_mul_f32_e32 v124, v124, v124
	v_mul_f32_e32 v125, v125, v125
	v_cvt_pk_bf16_f32 v122, v126, v122
	v_max_f32_e32 v114, 0, v114
	v_max_f32_e32 v115, 0, v115
	v_max_f32_e32 v116, 0, v116
	v_cvt_pk_bf16_f32 v123, v123, v124
	v_cvt_pk_bf16_f32 v124, v135, v127
	v_cvt_pk_bf16_f32 v125, v128, v125
	global_store_dwordx4 v[132:133], v[122:125], off
	s_nop 1
	v_mul_f32_e32 v122, v114, v114
	v_max_f32_e32 v114, v119, v119
	v_mul_f32_e32 v119, v115, v115
	v_max_f32_e32 v115, v120, v120
	v_mul_f32_e32 v120, v116, v116
	v_max_f32_e32 v116, v121, v121
	v_max_f32_e32 v114, 0, v114
	v_max_f32_e32 v115, 0, v115
	v_max_f32_e32 v116, 0, v116
	v_max_f32_e32 v118, 0, v118
	v_mul_f32_e32 v114, v114, v114
	v_mul_f32_e32 v115, v115, v115
	v_max_f32_e32 v117, 0, v117
	v_mul_f32_e32 v116, v116, v116
	v_mul_f32_e32 v118, v118, v118
	v_mul_f32_e32 v117, v117, v117
	v_cvt_pk_bf16_f32 v114, v118, v114
	v_cvt_pk_bf16_f32 v115, v115, v116
	v_cvt_pk_bf16_f32 v116, v122, v119
	v_max_f32_e32 v106, 0, v106
	v_cvt_pk_bf16_f32 v117, v120, v117
	global_store_dwordx4 v[132:133], v[114:117], off offset:256
	s_nop 1
	v_max_f32_e32 v107, 0, v107
	v_max_f32_e32 v108, 0, v108
	v_mul_f32_e32 v116, v106, v106
	v_max_f32_e32 v106, v111, v111
	v_or_b32_e32 v114, 16, v134
	v_max_f32_e32 v106, 0, v106
	v_mul_f32_e32 v111, v107, v107
	v_max_f32_e32 v107, v112, v112
	v_mul_f32_e32 v112, v108, v108
	v_max_f32_e32 v108, v113, v113
	v_mad_i64_i32 v[114:115], s[2:3], v114, s4, v[130:131]
	v_max_f32_e32 v110, 0, v110
	v_mul_f32_e32 v106, v106, v106
	v_max_f32_e32 v107, 0, v107
	v_max_f32_e32 v108, 0, v108
	v_max_f32_e32 v109, 0, v109
	v_lshl_add_u64 v[114:115], v[114:115], 0, v[64:65]
	v_mul_f32_e32 v110, v110, v110
	v_mul_f32_e32 v107, v107, v107
	v_mul_f32_e32 v108, v108, v108
	v_mul_f32_e32 v109, v109, v109
	v_cvt_pk_bf16_f32 v106, v110, v106
	v_max_f32_e32 v98, 0, v98
	v_max_f32_e32 v99, 0, v99
	v_max_f32_e32 v100, 0, v100
	v_cvt_pk_bf16_f32 v107, v107, v108
	v_cvt_pk_bf16_f32 v108, v116, v111
	v_cvt_pk_bf16_f32 v109, v112, v109
	global_store_dwordx4 v[114:115], v[106:109], off
	s_nop 1
	v_mul_f32_e32 v106, v98, v98
; __device__ __forceinline__ unsigned cvt_pk_bf16(float lo, float hi) { unsigned r; asm volatile("v_cvt_pk_bf16_f32 %0, %1, %2" : "=v"(r) : "v"(lo), "v"(hi)); return r; }
;     __device__ __forceinline__ void operator()(const f32x4 (&acc)[2][2][4][2], const Unit& u, int wr, int wc, int fr, int fq) const {
;         const int row0 = u.pm * BM + wr * 64 + fr, col0 = u.pn * BM + wc * 32 + 8 * fq;
; #pragma unroll
;         for (int ai = 0; ai < 2; ++ai)
; #pragma unroll
;             for (int m = 0; m < 4; ++m) { bf16_t* rowp = O + (size_t)(row0 + ai * HALF + m * 16) * LDF + col0;
; #pragma unroll
;                 for (int bj = 0; bj < 2; ++bj) { f32x4 v0 = acc[ai][bj][m][0], v1 = acc[ai][bj][m][1];
; #pragma unroll
;                     for (int j = 0; j < 4; ++j) { const float a = fmaxf(v0[j], 0.f), b = fmaxf(v1[j], 0.f); v0[j] = a * a; v1[j] = b * b; }
;                     u32x4 w; w.x = cvt_pk_bf16(v0[0], v0[1]); w.y = cvt_pk_bf16(v0[2], v0[3]); w.z = cvt_pk_bf16(v1[0], v1[1]); w.w = cvt_pk_bf16(v1[2], v1[3]);
;                     *(u32x4*)(rowp + bj * HALF) = w; } }
	v_max_f32_e32 v98, v103, v103
	v_mul_f32_e32 v103, v99, v99
	v_max_f32_e32 v99, v104, v104
	v_mul_f32_e32 v104, v100, v100
	v_max_f32_e32 v100, v105, v105
	v_max_f32_e32 v98, 0, v98
	v_max_f32_e32 v99, 0, v99
	v_max_f32_e32 v100, 0, v100
	v_max_f32_e32 v102, 0, v102
	v_mul_f32_e32 v98, v98, v98
	v_mul_f32_e32 v99, v99, v99
	v_max_f32_e32 v101, 0, v101
	v_mul_f32_e32 v100, v100, v100
	v_mul_f32_e32 v102, v102, v102
	v_mul_f32_e32 v101, v101, v101
	v_cvt_pk_bf16_f32 v98, v102, v98
	v_cvt_pk_bf16_f32 v99, v99, v100
	v_cvt_pk_bf16_f32 v100, v106, v103
	v_max_f32_e32 v90, 0, v90
	v_cvt_pk_bf16_f32 v101, v104, v101
	global_store_dwordx4 v[114:115], v[98:101], off offset:256
	s_nop 1
	v_max_f32_e32 v91, 0, v91
	v_max_f32_e32 v92, 0, v92
	v_mul_f32_e32 v100, v90, v90
	v_max_f32_e32 v90, v95, v95
	v_or_b32_e32 v98, 32, v134
	v_max_f32_e32 v90, 0, v90
	v_mul_f32_e32 v95, v91, v91
	v_max_f32_e32 v91, v96, v96
	v_mul_f32_e32 v96, v92, v92
	v_max_f32_e32 v92, v97, v97
	v_mad_i64_i32 v[98:99], s[2:3], v98, s4, v[130:131]
	v_max_f32_e32 v94, 0, v94
	v_mul_f32_e32 v90, v90, v90
	v_max_f32_e32 v91, 0, v91
	v_max_f32_e32 v92, 0, v92
	v_max_f32_e32 v93, 0, v93
	v_lshl_add_u64 v[98:99], v[98:99], 0, v[64:65]
	v_mul_f32_e32 v94, v94, v94
	v_mul_f32_e32 v91, v91, v91
	v_mul_f32_e32 v92, v92, v92
	v_mul_f32_e32 v93, v93, v93
	v_cvt_pk_bf16_f32 v90, v94, v90
	v_max_f32_e32 v82, 0, v82
	v_max_f32_e32 v83, 0, v83
	v_max_f32_e32 v84, 0, v84
	v_cvt_pk_bf16_f32 v91, v91, v92
	v_cvt_pk_bf16_f32 v92, v100, v95
	v_cvt_pk_bf16_f32 v93, v96, v93
	global_store_dwordx4 v[98:99], v[90:93], off
	s_nop 1
	v_mul_f32_e32 v90, v82, v82
	v_max_f32_e32 v82, v87, v87
	v_mul_f32_e32 v87, v83, v83
	v_max_f32_e32 v83, v88, v88
	v_mul_f32_e32 v88, v84, v84
	v_max_f32_e32 v84, v89, v89
	v_max_f32_e32 v82, 0, v82
	v_max_f32_e32 v83, 0, v83
	v_max_f32_e32 v84, 0, v84
	v_max_f32_e32 v86, 0, v86
	v_mul_f32_e32 v82, v82, v82
	v_mul_f32_e32 v83, v83, v83
	v_max_f32_e32 v85, 0, v85
	v_mul_f32_e32 v84, v84, v84
	v_mul_f32_e32 v86, v86, v86
	v_mul_f32_e32 v85, v85, v85
	v_cvt_pk_bf16_f32 v82, v86, v82
	v_cvt_pk_bf16_f32 v83, v83, v84
	v_cvt_pk_bf16_f32 v84, v90, v87
	v_max_f32_e32 v74, 0, v74
	v_cvt_pk_bf16_f32 v85, v88, v85
	global_store_dwordx4 v[98:99], v[82:85], off offset:256
	s_nop 1
	v_max_f32_e32 v75, 0, v75
	v_max_f32_e32 v76, 0, v76
	v_mul_f32_e32 v84, v74, v74
	v_max_f32_e32 v74, v79, v79
	v_or_b32_e32 v82, 48, v134
	v_max_f32_e32 v74, 0, v74
	v_mul_f32_e32 v79, v75, v75
	v_max_f32_e32 v75, v80, v80
	v_mul_f32_e32 v80, v76, v76
	v_max_f32_e32 v76, v81, v81
	v_mad_i64_i32 v[82:83], s[2:3], v82, s4, v[130:131]
	v_max_f32_e32 v78, 0, v78
	v_mul_f32_e32 v74, v74, v74
	v_max_f32_e32 v75, 0, v75
	v_max_f32_e32 v76, 0, v76
	v_max_f32_e32 v77, 0, v77
	v_lshl_add_u64 v[82:83], v[82:83], 0, v[64:65]
	v_mul_f32_e32 v78, v78, v78
	v_mul_f32_e32 v75, v75, v75
	v_mul_f32_e32 v76, v76, v76
	v_mul_f32_e32 v77, v77, v77
	v_cvt_pk_bf16_f32 v74, v78, v74
	v_max_f32_e32 v66, 0, v66
	v_max_f32_e32 v67, 0, v67
	v_max_f32_e32 v68, 0, v68
	v_cvt_pk_bf16_f32 v75, v75, v76
	v_cvt_pk_bf16_f32 v76, v84, v79
	v_cvt_pk_bf16_f32 v77, v80, v77
	global_store_dwordx4 v[82:83], v[74:77], off
	s_nop 1
	v_mul_f32_e32 v74, v66, v66
	v_max_f32_e32 v66, v71, v71
	v_mul_f32_e32 v71, v67, v67
	v_max_f32_e32 v67, v72, v72
	v_mul_f32_e32 v72, v68, v68
	v_max_f32_e32 v68, v73, v73
	v_max_f32_e32 v66, 0, v66
	v_max_f32_e32 v67, 0, v67
	v_max_f32_e32 v68, 0, v68
	v_max_f32_e32 v70, 0, v70
	v_mul_f32_e32 v66, v66, v66
	v_mul_f32_e32 v67, v67, v67
	v_max_f32_e32 v69, 0, v69
	v_mul_f32_e32 v68, v68, v68
	v_mul_f32_e32 v70, v70, v70
	v_mul_f32_e32 v69, v69, v69
	v_cvt_pk_bf16_f32 v66, v70, v66
	v_cvt_pk_bf16_f32 v67, v67, v68
	v_cvt_pk_bf16_f32 v68, v74, v71
	v_max_f32_e32 v56, 0, v56
	v_cvt_pk_bf16_f32 v69, v72, v69
	global_store_dwordx4 v[82:83], v[66:69], off offset:256
	s_nop 1
	v_max_f32_e32 v57, 0, v57
	v_max_f32_e32 v58, 0, v58
	v_mul_f32_e32 v68, v56, v56
	v_max_f32_e32 v56, v61, v61
	v_add_u32_e32 v66, 0x80, v134
	v_max_f32_e32 v56, 0, v56
	v_mul_f32_e32 v61, v57, v57
	v_max_f32_e32 v57, v62, v62
	v_mul_f32_e32 v62, v58, v58
	v_max_f32_e32 v58, v63, v63
	v_mad_i64_i32 v[66:67], s[2:3], v66, s4, v[130:131]
	v_max_f32_e32 v60, 0, v60
	v_mul_f32_e32 v56, v56, v56
	v_max_f32_e32 v57, 0, v57
	v_max_f32_e32 v58, 0, v58
	v_max_f32_e32 v59, 0, v59
	v_lshl_add_u64 v[66:67], v[66:67], 0, v[64:65]
	v_mul_f32_e32 v60, v60, v60
	v_mul_f32_e32 v57, v57, v57
	v_mul_f32_e32 v58, v58, v58
	v_mul_f32_e32 v59, v59, v59
	v_cvt_pk_bf16_f32 v56, v60, v56
	v_max_f32_e32 v48, 0, v48
	v_max_f32_e32 v49, 0, v49
	v_max_f32_e32 v50, 0, v50
	v_cvt_pk_bf16_f32 v57, v57, v58
	v_cvt_pk_bf16_f32 v58, v68, v61
	v_cvt_pk_bf16_f32 v59, v62, v59
	global_store_dwordx4 v[66:67], v[56:59], off
	s_nop 1
	v_mul_f32_e32 v56, v48, v48
	v_max_f32_e32 v48, v53, v53
	v_mul_f32_e32 v53, v49, v49
	v_max_f32_e32 v49, v54, v54
	v_mul_f32_e32 v54, v50, v50
	v_max_f32_e32 v50, v55, v55
	v_max_f32_e32 v48, 0, v48
	v_max_f32_e32 v49, 0, v49
	v_max_f32_e32 v50, 0, v50
	v_max_f32_e32 v52, 0, v52
	v_mul_f32_e32 v48, v48, v48
	v_mul_f32_e32 v49, v49, v49
; __device__ __forceinline__ unsigned cvt_pk_bf16(float lo, float hi) { unsigned r; asm volatile("v_cvt_pk_bf16_f32 %0, %1, %2" : "=v"(r) : "v"(lo), "v"(hi)); return r; }
; #define PG8_WAIT_V(n) asm volatile("s_waitcnt vmcnt(" #n ")" ::: "memory")
; #define PG8_BAR __builtin_amdgcn_s_barrier()
;     __device__ __forceinline__ void operator()(const f32x4 (&acc)[2][2][4][2], const Unit& u, int wr, int wc, int fr, int fq) const {
;         const int row0 = u.pm * BM + wr * 64 + fr, col0 = u.pn * BM + wc * 32 + 8 * fq;
; #pragma unroll
;         for (int ai = 0; ai < 2; ++ai)
; #pragma unroll
;             for (int m = 0; m < 4; ++m) { bf16_t* rowp = O + (size_t)(row0 + ai * HALF + m * 16) * LDF + col0;
; #pragma unroll
;                 for (int bj = 0; bj < 2; ++bj) { f32x4 v0 = acc[ai][bj][m][0], v1 = acc[ai][bj][m][1];
; #pragma unroll
;                     for (int j = 0; j < 4; ++j) { const float a = fmaxf(v0[j], 0.f), b = fmaxf(v1[j], 0.f); v0[j] = a * a; v1[j] = b * b; }
;                     u32x4 w; w.x = cvt_pk_bf16(v0[0], v0[1]); w.y = cvt_pk_bf16(v0[2], v0[3]); w.z = cvt_pk_bf16(v1[0], v1[1]); w.w = cvt_pk_bf16(v1[2], v1[3]);
;                     *(u32x4*)(rowp + bj * HALF) = w; } }
;     ...
;     PG8_WAIT_V(0);
;     if (wr == 0) PG8_BAR;
;     PG8_BAR;
	v_max_f32_e32 v51, 0, v51
	v_mul_f32_e32 v50, v50, v50
	v_mul_f32_e32 v52, v52, v52
	v_mul_f32_e32 v51, v51, v51
	v_cvt_pk_bf16_f32 v48, v52, v48
	v_cvt_pk_bf16_f32 v49, v49, v50
	v_cvt_pk_bf16_f32 v50, v56, v53
	v_max_f32_e32 v40, 0, v40
	v_cvt_pk_bf16_f32 v51, v54, v51
	global_store_dwordx4 v[66:67], v[48:51], off offset:256
	s_nop 1
	v_max_f32_e32 v41, 0, v41
	v_max_f32_e32 v42, 0, v42
	v_mul_f32_e32 v50, v40, v40
	v_max_f32_e32 v40, v45, v45
	v_add_u32_e32 v48, 0x90, v134
	v_max_f32_e32 v40, 0, v40
	v_mul_f32_e32 v45, v41, v41
	v_max_f32_e32 v41, v46, v46
	v_mul_f32_e32 v46, v42, v42
	v_max_f32_e32 v42, v47, v47
	v_mad_i64_i32 v[48:49], s[2:3], v48, s4, v[130:131]
	v_max_f32_e32 v44, 0, v44
	v_mul_f32_e32 v40, v40, v40
	v_max_f32_e32 v41, 0, v41
	v_max_f32_e32 v42, 0, v42
	v_max_f32_e32 v43, 0, v43
	v_lshl_add_u64 v[48:49], v[48:49], 0, v[64:65]
	v_mul_f32_e32 v44, v44, v44
	v_mul_f32_e32 v41, v41, v41
	v_mul_f32_e32 v42, v42, v42
	v_mul_f32_e32 v43, v43, v43
	v_cvt_pk_bf16_f32 v40, v44, v40
	v_max_f32_e32 v32, 0, v32
	v_max_f32_e32 v33, 0, v33
	v_max_f32_e32 v34, 0, v34
	v_cvt_pk_bf16_f32 v41, v41, v42
	v_cvt_pk_bf16_f32 v42, v50, v45
	v_cvt_pk_bf16_f32 v43, v46, v43
	global_store_dwordx4 v[48:49], v[40:43], off
	s_nop 1
	v_mul_f32_e32 v40, v32, v32
	v_max_f32_e32 v32, v37, v37
	v_mul_f32_e32 v37, v33, v33
	v_max_f32_e32 v33, v38, v38
	v_mul_f32_e32 v38, v34, v34
	v_max_f32_e32 v34, v39, v39
	v_max_f32_e32 v32, 0, v32
	v_max_f32_e32 v33, 0, v33
	v_max_f32_e32 v34, 0, v34
	v_max_f32_e32 v36, 0, v36
	v_mul_f32_e32 v32, v32, v32
	v_mul_f32_e32 v33, v33, v33
	v_max_f32_e32 v35, 0, v35
	v_mul_f32_e32 v34, v34, v34
	v_mul_f32_e32 v36, v36, v36
	v_mul_f32_e32 v35, v35, v35
	v_cvt_pk_bf16_f32 v32, v36, v32
	v_cvt_pk_bf16_f32 v33, v33, v34
	v_cvt_pk_bf16_f32 v34, v40, v37
	v_max_f32_e32 v24, 0, v24
	v_cvt_pk_bf16_f32 v35, v38, v35
	global_store_dwordx4 v[48:49], v[32:35], off offset:256
	s_nop 1
	v_max_f32_e32 v25, 0, v25
	v_max_f32_e32 v26, 0, v26
	v_mul_f32_e32 v34, v24, v24
	v_max_f32_e32 v24, v29, v29
	v_add_u32_e32 v32, 0xa0, v134
	v_max_f32_e32 v24, 0, v24
	v_mul_f32_e32 v29, v25, v25
	v_max_f32_e32 v25, v30, v30
	v_mul_f32_e32 v30, v26, v26
	v_max_f32_e32 v26, v31, v31
	v_mad_i64_i32 v[32:33], s[2:3], v32, s4, v[130:131]
	v_max_f32_e32 v28, 0, v28
	v_mul_f32_e32 v24, v24, v24
	v_max_f32_e32 v25, 0, v25
	v_max_f32_e32 v26, 0, v26
	v_max_f32_e32 v27, 0, v27
	v_lshl_add_u64 v[32:33], v[32:33], 0, v[64:65]
	v_mul_f32_e32 v28, v28, v28
	v_mul_f32_e32 v25, v25, v25
	v_mul_f32_e32 v26, v26, v26
	v_mul_f32_e32 v27, v27, v27
	v_cvt_pk_bf16_f32 v24, v28, v24
	v_max_f32_e32 v16, 0, v16
	v_max_f32_e32 v17, 0, v17
	v_max_f32_e32 v18, 0, v18
	v_cvt_pk_bf16_f32 v25, v25, v26
	v_cvt_pk_bf16_f32 v26, v34, v29
	v_cvt_pk_bf16_f32 v27, v30, v27
	global_store_dwordx4 v[32:33], v[24:27], off
	s_nop 1
	v_mul_f32_e32 v24, v16, v16
	v_max_f32_e32 v16, v21, v21
	v_mul_f32_e32 v21, v17, v17
	v_max_f32_e32 v17, v22, v22
	v_mul_f32_e32 v22, v18, v18
	v_max_f32_e32 v18, v23, v23
	v_max_f32_e32 v16, 0, v16
	v_max_f32_e32 v17, 0, v17
	v_max_f32_e32 v18, 0, v18
	v_max_f32_e32 v20, 0, v20
	v_mul_f32_e32 v16, v16, v16
	v_mul_f32_e32 v17, v17, v17
	v_max_f32_e32 v19, 0, v19
	v_mul_f32_e32 v18, v18, v18
	v_mul_f32_e32 v20, v20, v20
	v_mul_f32_e32 v19, v19, v19
	v_cvt_pk_bf16_f32 v16, v20, v16
	v_cvt_pk_bf16_f32 v17, v17, v18
	v_cvt_pk_bf16_f32 v18, v24, v21
	v_max_f32_e32 v8, 0, v8
	v_cvt_pk_bf16_f32 v19, v22, v19
	global_store_dwordx4 v[32:33], v[16:19], off offset:256
	s_nop 1
	v_max_f32_e32 v9, 0, v9
	v_max_f32_e32 v10, 0, v10
	v_mul_f32_e32 v18, v8, v8
	v_max_f32_e32 v8, v13, v13
	v_add_u32_e32 v16, 0xb0, v134
	v_max_f32_e32 v8, 0, v8
	v_mul_f32_e32 v13, v9, v9
	v_max_f32_e32 v9, v14, v14
	v_mul_f32_e32 v14, v10, v10
	v_max_f32_e32 v10, v15, v15
	v_mad_i64_i32 v[16:17], s[2:3], v16, s4, v[130:131]
	v_max_f32_e32 v12, 0, v12
	v_mul_f32_e32 v8, v8, v8
	v_max_f32_e32 v9, 0, v9
	v_max_f32_e32 v10, 0, v10
	v_max_f32_e32 v11, 0, v11
	v_lshl_add_u64 v[16:17], v[16:17], 0, v[64:65]
	v_mul_f32_e32 v12, v12, v12
	v_mul_f32_e32 v9, v9, v9
	v_mul_f32_e32 v10, v10, v10
	v_mul_f32_e32 v11, v11, v11
	v_cvt_pk_bf16_f32 v8, v12, v8
	v_max_f32_e32 v0, 0, v0
	v_max_f32_e32 v1, 0, v1
	v_max_f32_e32 v2, 0, v2
	v_cvt_pk_bf16_f32 v9, v9, v10
	v_cvt_pk_bf16_f32 v10, v18, v13
	v_cvt_pk_bf16_f32 v11, v14, v11
	global_store_dwordx4 v[16:17], v[8:11], off
	s_nop 1
	v_mul_f32_e32 v8, v0, v0
	v_max_f32_e32 v0, v5, v5
	v_mul_f32_e32 v5, v1, v1
	v_max_f32_e32 v1, v6, v6
	v_mul_f32_e32 v6, v2, v2
	v_max_f32_e32 v2, v7, v7
	v_max_f32_e32 v0, 0, v0
	v_max_f32_e32 v1, 0, v1
	v_max_f32_e32 v2, 0, v2
	v_max_f32_e32 v3, 0, v3
	v_max_f32_e32 v4, 0, v4
	v_mul_f32_e32 v0, v0, v0
	v_mul_f32_e32 v1, v1, v1
	v_mul_f32_e32 v2, v2, v2
	v_mul_f32_e32 v3, v3, v3
	v_mul_f32_e32 v4, v4, v4
	v_cvt_pk_bf16_f32 v0, v4, v0
	v_cvt_pk_bf16_f32 v1, v1, v2
	v_cvt_pk_bf16_f32 v2, v8, v5
	v_cvt_pk_bf16_f32 v3, v6, v3
	global_store_dwordx4 v[16:17], v[0:3], off offset:256
	s_nop 1
	s_waitcnt vmcnt(0)
	s_cmpk_lt_u32 s14, 0x100
	s_movk_i32 s27, 0x1000
	s_cbranch_scc0 .LBB0_149
	s_barrier

; #define PG8_STAGE(bufoff, gbase, voff) do { _Pragma("unroll") for (int _i = 0; _i < 2; ++_i) \
;         __builtin_amdgcn_global_load_lds((const unsigned*)((const char*)(gbase) + (voff)[_i]), (LAS unsigned*)(lds + (bufoff) + ldsw + _i * 8192), 16, 0, 0); } while (0)
; #define PG8_LDA(dst, b, h) do { _Pragma("unroll") for (int m = 0; m < 4; ++m) _Pragma("unroll") for (int k = 0; k < 2; ++k) dst[m][k] = *(const LAS bf16x8*)(lds + PG8_SA(b, h) + aoff + m * 2048 + k * 1024); } while (0)
; #define PG8_LDB(dst, b, h) do { _Pragma("unroll") for (int n = 0; n < 2; ++n) _Pragma("unroll") for (int k = 0; k < 2; ++k) dst[n][k] = *(const LAS bf16x8*)(lds + PG8_SB(b, h) + boff + n * 2048 + k * 1024); } while (0)
; #define PG8_MMA(ai, bj, At, Bt) do { __builtin_amdgcn_s_setprio(1); _Pragma("unroll") for (int m = 0; m < 4; ++m) _Pragma("unroll") for (int n = 0; n < 2; ++n) _Pragma("unroll") for (int k = 0; k < 2; ++k) \
;         acc[ai][bj][m][n] = __builtin_amdgcn_mfma_f32_16x16x32_bf16(Bt[n][k], At[m][k], acc[ai][bj][m][n], 0, 0, 0); __builtin_amdgcn_s_setprio(0); } while (0)
; #define PG8_WAIT_L(n) asm volatile("s_waitcnt lgkmcnt(" #n ")" ::: "memory")
; #define PG8_BAR __builtin_amdgcn_s_barrier()
; #define PG8_SCHED __builtin_amdgcn_sched_barrier(0)
;     ...
;             const char* a1 = cA + (size_t)(t + 1) * kstep;
;             const char* a2 = last ? nA : cA + (size_t)(t + 2) * kstep; const char* b2 = last ? nB : cB + (size_t)(t + 2) * kstep;
;             const char* a3 = a2 + kstep; const char* b3 = b2 + kstep;
;             PG8_LDB(B0, 0, 0); PG8_SCHED; PG8_LDA(At, 0, 0); PG8_STAGE(PG8_SA(1, 1), a1 + hstep, voffA);
;             PG8_WAIT_L(8); PG8_BAR; PG8_WAIT_L(0); PG8_MMA(0, 0, At, B0); PG8_BAR; PG8_SCHED;
;             PG8_LDB(B1, 0, 1); PG8_STAGE(PG8_SB(0, 0), b2, voffB);
;             PG8_BAR; PG8_WAIT_L(0); PG8_MMA(0, 1, At, B1); PG8_BAR;
;             PG8_LDA(At, 0, 1); PG8_STAGE(PG8_SA(0, 0), a2, voffA);
;             PG8_BAR; PG8_WAIT_L(0); PG8_MMA(1, 0, At, B0); PG8_BAR; PG8_SCHED;
.LBB0_475:
	s_or_b32 s94, s12, 1
	s_add_i32 s12, s12, 2
	s_mov_b32 s13, s95
	s_lshl_b64 s[2:3], s[12:13], 7
	s_add_u32 s7, s24, s2
	s_addc_u32 s13, s25, s3
	s_and_b64 vcc, s[44:45], exec
	s_cselect_b32 vcc_hi, s85, s13
	s_cselect_b32 vcc_lo, s84, s7
	s_add_u32 s7, s42, s2
	s_addc_u32 s13, s43, s3
	s_add_i32 s35, 0, 0x10000
	v_add_u32_e32 v64, s35, v220
	ds_read_b128 v[134:137], v64
	ds_read_b128 v[138:141], v64 offset:1024
	ds_read_b128 v[142:145], v64 offset:2048
	ds_read_b128 v[146:149], v64 offset:3072
	s_and_b64 s[2:3], s[44:45], exec
	s_cselect_b32 s45, s9, s13
	s_cselect_b32 s44, s8, s7
	s_lshl_b64 s[2:3], s[94:95], 7
	s_add_u32 s2, s47, s2
	s_addc_u32 s3, s89, s3
	v_lshl_add_u64 v[182:183], s[2:3], 0, v[130:131]
	s_add_i32 m0, s19, 0xc000
	ds_read_b128 v[150:153], v229
	ds_read_b128 v[154:157], v229 offset:1024
	ds_read_b128 v[158:161], v229 offset:2048
	ds_read_b128 v[162:165], v229 offset:3072
	ds_read_b128 v[166:169], v229 offset:4096
	ds_read_b128 v[170:173], v229 offset:5120
	ds_read_b128 v[174:177], v229 offset:6144
	ds_read_b128 v[178:181], v229 offset:7168
	global_load_lds_dwordx4 v[182:183], off
	v_lshl_add_u64 v[182:183], s[2:3], 0, v[132:133]
	s_add_i32 m0, s19, 0xe000
	s_nop 0
	global_load_lds_dwordx4 v[182:183], off
	s_waitcnt lgkmcnt(8)
	s_barrier
	s_waitcnt lgkmcnt(0)
	v_mfma_f32_16x16x32_bf16 v[118:121], v[134:137], v[150:153], v[118:121]
	v_mfma_f32_16x16x32_bf16 v[114:117], v[142:145], v[150:153], v[114:117]
	v_mfma_f32_16x16x32_bf16 v[102:105], v[134:137], v[158:161], v[102:105]
	v_mfma_f32_16x16x32_bf16 v[98:101], v[142:145], v[158:161], v[98:101]
	v_mfma_f32_16x16x32_bf16 v[86:89], v[134:137], v[166:169], v[86:89]
	v_mfma_f32_16x16x32_bf16 v[82:85], v[142:145], v[166:169], v[82:85]
	v_mfma_f32_16x16x32_bf16 v[70:73], v[134:137], v[174:177], v[70:73]
	v_mfma_f32_16x16x32_bf16 v[66:69], v[142:145], v[174:177], v[66:69]
	v_mfma_f32_16x16x32_bf16 v[118:121], v[138:141], v[154:157], v[118:121]
	v_mfma_f32_16x16x32_bf16 v[114:117], v[146:149], v[154:157], v[114:117]
	v_mfma_f32_16x16x32_bf16 v[102:105], v[138:141], v[162:165], v[102:105]
	v_mfma_f32_16x16x32_bf16 v[98:101], v[146:149], v[162:165], v[98:101]
	v_mfma_f32_16x16x32_bf16 v[86:89], v[138:141], v[170:173], v[86:89]
	v_mfma_f32_16x16x32_bf16 v[82:85], v[146:149], v[170:173], v[82:85]
	v_mfma_f32_16x16x32_bf16 v[70:73], v[138:141], v[178:181], v[70:73]
	v_mfma_f32_16x16x32_bf16 v[66:69], v[146:149], v[178:181], v[66:69]
	s_barrier
	s_add_i32 s7, 0, 0x14000
	s_add_i32 s2, s35, s18
	v_add_u32_e32 v64, s7, v220
	v_lshl_add_u64 v[198:199], s[44:45], 0, v[130:131]
	s_mov_b32 m0, s2
	ds_read_b128 v[182:185], v64
	ds_read_b128 v[186:189], v64 offset:1024
	ds_read_b128 v[190:193], v64 offset:2048
	ds_read_b128 v[194:197], v64 offset:3072
	global_load_lds_dwordx4 v[198:199], off
	v_lshl_add_u64 v[246:247], s[44:45], 0, v[132:133]
	s_add_i32 m0, s2, 0x2000
	s_nop 0
	global_load_lds_dwordx4 v[246:247], off
	s_barrier
	s_waitcnt lgkmcnt(0)
	v_mfma_f32_16x16x32_bf16 v[126:129], v[182:185], v[150:153], v[126:129]
	v_mfma_f32_16x16x32_bf16 v[122:125], v[190:193], v[150:153], v[122:125]
	v_mfma_f32_16x16x32_bf16 v[110:113], v[182:185], v[158:161], v[110:113]
	v_mfma_f32_16x16x32_bf16 v[106:109], v[190:193], v[158:161], v[106:109]
	v_mfma_f32_16x16x32_bf16 v[94:97], v[182:185], v[166:169], v[94:97]
	v_mfma_f32_16x16x32_bf16 v[90:93], v[190:193], v[166:169], v[90:93]
	v_mfma_f32_16x16x32_bf16 v[78:81], v[182:185], v[174:177], v[78:81]
	v_mfma_f32_16x16x32_bf16 v[74:77], v[190:193], v[174:177], v[74:77]
	v_mfma_f32_16x16x32_bf16 v[126:129], v[186:189], v[154:157], v[126:129]
	v_mfma_f32_16x16x32_bf16 v[122:125], v[194:197], v[154:157], v[122:125]
	v_mfma_f32_16x16x32_bf16 v[110:113], v[186:189], v[162:165], v[110:113]
	v_mfma_f32_16x16x32_bf16 v[106:109], v[194:197], v[162:165], v[106:109]
	v_mfma_f32_16x16x32_bf16 v[94:97], v[186:189], v[170:173], v[94:97]
	v_mfma_f32_16x16x32_bf16 v[90:93], v[194:197], v[170:173], v[90:93]
	v_mfma_f32_16x16x32_bf16 v[78:81], v[186:189], v[178:181], v[78:81]
	v_mfma_f32_16x16x32_bf16 v[74:77], v[194:197], v[178:181], v[74:77]
	s_barrier
	s_mov_b32 m0, s19
	v_lshl_add_u64 v[212:213], vcc, 0, v[130:131]
	ds_read_b128 v[150:153], v229 offset:16384
	ds_read_b128 v[154:157], v229 offset:17408
	ds_read_b128 v[158:161], v229 offset:18432
	ds_read_b128 v[162:165], v229 offset:19456
	ds_read_b128 v[166:169], v229 offset:20480
	ds_read_b128 v[170:173], v229 offset:21504
	ds_read_b128 v[174:177], v229 offset:22528
	ds_read_b128 v[178:181], v229 offset:23552
	global_load_lds_dwordx4 v[212:213], off
	v_lshl_add_u64 v[208:209], vcc, 0, v[132:133]
	s_mov_b32 m0, s21
	s_nop 0
	global_load_lds_dwordx4 v[208:209], off
	s_barrier
	s_waitcnt lgkmcnt(0)
	v_mfma_f32_16x16x32_bf16 v[52:55], v[134:137], v[150:153], v[52:55]
	v_mfma_f32_16x16x32_bf16 v[48:51], v[142:145], v[150:153], v[48:51]
	v_mfma_f32_16x16x32_bf16 v[36:39], v[134:137], v[158:161], v[36:39]
	v_mfma_f32_16x16x32_bf16 v[32:35], v[142:145], v[158:161], v[32:35]
	v_mfma_f32_16x16x32_bf16 v[20:23], v[134:137], v[166:169], v[20:23]
	v_mfma_f32_16x16x32_bf16 v[16:19], v[142:145], v[166:169], v[16:19]
	v_mfma_f32_16x16x32_bf16 v[4:7], v[134:137], v[174:177], v[4:7]
	v_mfma_f32_16x16x32_bf16 v[0:3], v[142:145], v[174:177], v[0:3]
	v_mfma_f32_16x16x32_bf16 v[52:55], v[138:141], v[154:157], v[52:55]
	v_mfma_f32_16x16x32_bf16 v[48:51], v[146:149], v[154:157], v[48:51]
	v_mfma_f32_16x16x32_bf16 v[36:39], v[138:141], v[162:165], v[36:39]
	v_mfma_f32_16x16x32_bf16 v[32:35], v[146:149], v[162:165], v[32:35]
	v_mfma_f32_16x16x32_bf16 v[20:23], v[138:141], v[170:173], v[20:23]
	v_mfma_f32_16x16x32_bf16 v[16:19], v[146:149], v[170:173], v[16:19]
	v_mfma_f32_16x16x32_bf16 v[4:7], v[138:141], v[178:181], v[4:7]
	v_mfma_f32_16x16x32_bf16 v[0:3], v[146:149], v[178:181], v[0:3]
	s_barrier
; #define PG8_STAGE(bufoff, gbase, voff) do { _Pragma("unroll") for (int _i = 0; _i < 2; ++_i) \
;         __builtin_amdgcn_global_load_lds((const unsigned*)((const char*)(gbase) + (voff)[_i]), (LAS unsigned*)(lds + (bufoff) + ldsw + _i * 8192), 16, 0, 0); } while (0)
; #define PG8_LDA(dst, b, h) do { _Pragma("unroll") for (int m = 0; m < 4; ++m) _Pragma("unroll") for (int k = 0; k < 2; ++k) dst[m][k] = *(const LAS bf16x8*)(lds + PG8_SA(b, h) + aoff + m * 2048 + k * 1024); } while (0)
; #define PG8_LDB(dst, b, h) do { _Pragma("unroll") for (int n = 0; n < 2; ++n) _Pragma("unroll") for (int k = 0; k < 2; ++k) dst[n][k] = *(const LAS bf16x8*)(lds + PG8_SB(b, h) + boff + n * 2048 + k * 1024); } while (0)
; #define PG8_MMA(ai, bj, At, Bt) do { __builtin_amdgcn_s_setprio(1); _Pragma("unroll") for (int m = 0; m < 4; ++m) _Pragma("unroll") for (int n = 0; n < 2; ++n) _Pragma("unroll") for (int k = 0; k < 2; ++k) \
;         acc[ai][bj][m][n] = __builtin_amdgcn_mfma_f32_16x16x32_bf16(Bt[n][k], At[m][k], acc[ai][bj][m][n], 0, 0, 0); __builtin_amdgcn_s_setprio(0); } while (0)
; #define PG8_WAIT_V(n) asm volatile("s_waitcnt vmcnt(" #n ")" ::: "memory")
; #define PG8_WAIT_L(n) asm volatile("s_waitcnt lgkmcnt(" #n ")" ::: "memory")
; #define PG8_BAR __builtin_amdgcn_s_barrier()
; #define PG8_SCHED __builtin_amdgcn_sched_barrier(0)
;     ...
;             PG8_STAGE(PG8_SB(0, 1), b2 + hstep, voffB);
;             PG8_WAIT_V(6); PG8_BAR; PG8_MMA(1, 1, At, B1); PG8_BAR;
;             PG8_LDB(B0, 1, 0); PG8_SCHED; PG8_LDA(At, 1, 0); PG8_STAGE(PG8_SA(0, 1), a2 + hstep, voffA);
;             PG8_WAIT_L(8); PG8_BAR; PG8_WAIT_L(0); PG8_MMA(0, 0, At, B0); PG8_BAR; PG8_SCHED;
;             PG8_LDB(B1, 1, 1); PG8_STAGE(PG8_SB(1, 0), b3, voffB);
;             PG8_BAR; PG8_WAIT_L(0); PG8_MMA(0, 1, At, B1); PG8_BAR;
	s_add_u32 s2, s44, s82
	s_addc_u32 s3, s45, 0
	s_add_i32 s7, s7, s18
	v_lshl_add_u64 v[210:211], s[2:3], 0, v[130:131]
	s_mov_b32 m0, s7
	v_lshl_add_u64 v[214:215], s[2:3], 0, v[132:133]
	global_load_lds_dwordx4 v[210:211], off
	s_add_i32 m0, s7, 0x2000
	s_nop 0
	global_load_lds_dwordx4 v[214:215], off
	s_waitcnt vmcnt(6)
	s_barrier
	v_mfma_f32_16x16x32_bf16 v[60:63], v[182:185], v[150:153], v[60:63]
	v_mfma_f32_16x16x32_bf16 v[56:59], v[190:193], v[150:153], v[56:59]
	v_mfma_f32_16x16x32_bf16 v[44:47], v[182:185], v[158:161], v[44:47]
	v_mfma_f32_16x16x32_bf16 v[40:43], v[190:193], v[158:161], v[40:43]
	v_mfma_f32_16x16x32_bf16 v[28:31], v[182:185], v[166:169], v[28:31]
	v_mfma_f32_16x16x32_bf16 v[24:27], v[190:193], v[166:169], v[24:27]
	v_mfma_f32_16x16x32_bf16 v[12:15], v[182:185], v[174:177], v[12:15]
	v_mfma_f32_16x16x32_bf16 v[8:11], v[190:193], v[174:177], v[8:11]
	v_mfma_f32_16x16x32_bf16 v[60:63], v[186:189], v[154:157], v[60:63]
	v_mfma_f32_16x16x32_bf16 v[56:59], v[194:197], v[154:157], v[56:59]
	v_mfma_f32_16x16x32_bf16 v[44:47], v[186:189], v[162:165], v[44:47]
	v_mfma_f32_16x16x32_bf16 v[40:43], v[194:197], v[162:165], v[40:43]
	v_mfma_f32_16x16x32_bf16 v[28:31], v[186:189], v[170:173], v[28:31]
	v_mfma_f32_16x16x32_bf16 v[24:27], v[194:197], v[170:173], v[24:27]
	v_mfma_f32_16x16x32_bf16 v[12:15], v[186:189], v[178:181], v[12:15]
	v_mfma_f32_16x16x32_bf16 v[8:11], v[194:197], v[178:181], v[8:11]
	s_barrier
	s_add_i32 s7, 0, 0x18000
	v_add_u32_e32 v64, s7, v220
	ds_read_b128 v[134:137], v64
	ds_read_b128 v[138:141], v64 offset:1024
	ds_read_b128 v[142:145], v64 offset:2048
	ds_read_b128 v[146:149], v64 offset:3072
	s_add_u32 s2, vcc_lo, s82
	s_addc_u32 s3, vcc_hi, 0
	s_mov_b32 m0, s31
	v_lshl_add_u64 v[182:183], s[2:3], 0, v[130:131]
	ds_read_b128 v[150:153], v229 offset:32768
	ds_read_b128 v[154:157], v229 offset:33792
	ds_read_b128 v[158:161], v229 offset:34816
	ds_read_b128 v[162:165], v229 offset:35840
	ds_read_b128 v[166:169], v229 offset:36864
	ds_read_b128 v[170:173], v229 offset:37888
	ds_read_b128 v[174:177], v229 offset:38912
	ds_read_b128 v[178:181], v229 offset:39936
	global_load_lds_dwordx4 v[182:183], off
	v_lshl_add_u64 v[182:183], s[2:3], 0, v[132:133]
	s_mov_b32 m0, s83
	s_nop 0
	global_load_lds_dwordx4 v[182:183], off
	s_waitcnt lgkmcnt(8)
	s_barrier
	s_waitcnt lgkmcnt(0)
	v_mfma_f32_16x16x32_bf16 v[118:121], v[134:137], v[150:153], v[118:121]
	v_mfma_f32_16x16x32_bf16 v[114:117], v[142:145], v[150:153], v[114:117]
	v_mfma_f32_16x16x32_bf16 v[102:105], v[134:137], v[158:161], v[102:105]
	v_mfma_f32_16x16x32_bf16 v[98:101], v[142:145], v[158:161], v[98:101]
	v_mfma_f32_16x16x32_bf16 v[86:89], v[134:137], v[166:169], v[86:89]
	v_mfma_f32_16x16x32_bf16 v[82:85], v[142:145], v[166:169], v[82:85]
	v_mfma_f32_16x16x32_bf16 v[70:73], v[134:137], v[174:177], v[70:73]
	v_mfma_f32_16x16x32_bf16 v[66:69], v[142:145], v[174:177], v[66:69]
	v_mfma_f32_16x16x32_bf16 v[118:121], v[138:141], v[154:157], v[118:121]
	v_mfma_f32_16x16x32_bf16 v[114:117], v[146:149], v[154:157], v[114:117]
	v_mfma_f32_16x16x32_bf16 v[102:105], v[138:141], v[162:165], v[102:105]
	v_mfma_f32_16x16x32_bf16 v[98:101], v[146:149], v[162:165], v[98:101]
	v_mfma_f32_16x16x32_bf16 v[86:89], v[138:141], v[170:173], v[86:89]
	v_mfma_f32_16x16x32_bf16 v[82:85], v[146:149], v[170:173], v[82:85]
	v_mfma_f32_16x16x32_bf16 v[70:73], v[138:141], v[178:181], v[70:73]
	v_mfma_f32_16x16x32_bf16 v[66:69], v[146:149], v[178:181], v[66:69]
	s_barrier
	s_add_i32 s2, 0, 0x1c000
	s_add_i32 s3, s7, s18
	v_add_u32_e32 v64, s2, v220
	v_lshl_add_u64 v[198:199], v[198:199], 0, s[16:17]
	s_mov_b32 m0, s3
	ds_read_b128 v[182:185], v64
	ds_read_b128 v[186:189], v64 offset:1024
	ds_read_b128 v[190:193], v64 offset:2048
	ds_read_b128 v[194:197], v64 offset:3072
	global_load_lds_dwordx4 v[198:199], off
	v_lshl_add_u64 v[198:199], v[246:247], 0, s[16:17]
	s_add_i32 m0, s3, 0x2000
	s_nop 0
	global_load_lds_dwordx4 v[198:199], off
	s_barrier
; #define PG8_STAGE(bufoff, gbase, voff) do { _Pragma("unroll") for (int _i = 0; _i < 2; ++_i) \
;         __builtin_amdgcn_global_load_lds((const unsigned*)((const char*)(gbase) + (voff)[_i]), (LAS unsigned*)(lds + (bufoff) + ldsw + _i * 8192), 16, 0, 0); } while (0)
; #define PG8_LDA(dst, b, h) do { _Pragma("unroll") for (int m = 0; m < 4; ++m) _Pragma("unroll") for (int k = 0; k < 2; ++k) dst[m][k] = *(const LAS bf16x8*)(lds + PG8_SA(b, h) + aoff + m * 2048 + k * 1024); } while (0)
; #define PG8_MMA(ai, bj, At, Bt) do { __builtin_amdgcn_s_setprio(1); _Pragma("unroll") for (int m = 0; m < 4; ++m) _Pragma("unroll") for (int n = 0; n < 2; ++n) _Pragma("unroll") for (int k = 0; k < 2; ++k) \
;         acc[ai][bj][m][n] = __builtin_amdgcn_mfma_f32_16x16x32_bf16(Bt[n][k], At[m][k], acc[ai][bj][m][n], 0, 0, 0); __builtin_amdgcn_s_setprio(0); } while (0)
; #define PG8_WAIT_V(n) asm volatile("s_waitcnt vmcnt(" #n ")" ::: "memory")
; #define PG8_WAIT_L(n) asm volatile("s_waitcnt lgkmcnt(" #n ")" ::: "memory")
; #define PG8_BAR __builtin_amdgcn_s_barrier()
; #define PG8_SCHED __builtin_amdgcn_sched_barrier(0)
;     ...
;             PG8_BAR; PG8_WAIT_L(0); PG8_MMA(0, 1, At, B1); PG8_BAR;
;             PG8_LDA(At, 1, 1); PG8_STAGE(PG8_SA(1, 0), a3, voffA);
;             PG8_BAR; PG8_WAIT_L(0); PG8_MMA(1, 0, At, B0); PG8_BAR; PG8_SCHED;
;             PG8_STAGE(PG8_SB(1, 1), b3 + hstep, voffB);
;             PG8_WAIT_V(6); PG8_BAR; PG8_MMA(1, 1, At, B1); PG8_BAR;
;         }
	s_waitcnt lgkmcnt(0)
	v_mfma_f32_16x16x32_bf16 v[126:129], v[182:185], v[150:153], v[126:129]
	v_mfma_f32_16x16x32_bf16 v[122:125], v[190:193], v[150:153], v[122:125]
	v_mfma_f32_16x16x32_bf16 v[110:113], v[182:185], v[158:161], v[110:113]
	v_mfma_f32_16x16x32_bf16 v[106:109], v[190:193], v[158:161], v[106:109]
	v_mfma_f32_16x16x32_bf16 v[94:97], v[182:185], v[166:169], v[94:97]
	v_mfma_f32_16x16x32_bf16 v[90:93], v[190:193], v[166:169], v[90:93]
	v_mfma_f32_16x16x32_bf16 v[78:81], v[182:185], v[174:177], v[78:81]
	v_mfma_f32_16x16x32_bf16 v[74:77], v[190:193], v[174:177], v[74:77]
	v_mfma_f32_16x16x32_bf16 v[126:129], v[186:189], v[154:157], v[126:129]
	v_mfma_f32_16x16x32_bf16 v[122:125], v[194:197], v[154:157], v[122:125]
	v_mfma_f32_16x16x32_bf16 v[110:113], v[186:189], v[162:165], v[110:113]
	v_mfma_f32_16x16x32_bf16 v[106:109], v[194:197], v[162:165], v[106:109]
	v_mfma_f32_16x16x32_bf16 v[94:97], v[186:189], v[170:173], v[94:97]
	v_mfma_f32_16x16x32_bf16 v[90:93], v[194:197], v[170:173], v[90:93]
	v_mfma_f32_16x16x32_bf16 v[78:81], v[186:189], v[178:181], v[78:81]
	v_mfma_f32_16x16x32_bf16 v[74:77], v[194:197], v[178:181], v[74:77]
	s_barrier
	s_mov_b32 m0, s36
	v_lshl_add_u64 v[198:199], v[212:213], 0, s[16:17]
	ds_read_b128 v[150:153], v229 offset:49152
	ds_read_b128 v[154:157], v229 offset:50176
	ds_read_b128 v[158:161], v229 offset:51200
	ds_read_b128 v[162:165], v229 offset:52224
	ds_read_b128 v[166:169], v229 offset:53248
	ds_read_b128 v[170:173], v229 offset:54272
	ds_read_b128 v[174:177], v229 offset:55296
	ds_read_b128 v[178:181], v229 offset:56320
	global_load_lds_dwordx4 v[198:199], off
	v_lshl_add_u64 v[198:199], v[208:209], 0, s[16:17]
	s_mov_b32 m0, s37
	s_nop 0
	global_load_lds_dwordx4 v[198:199], off
	s_barrier
	s_waitcnt lgkmcnt(0)
	v_mfma_f32_16x16x32_bf16 v[52:55], v[134:137], v[150:153], v[52:55]
	v_mfma_f32_16x16x32_bf16 v[48:51], v[142:145], v[150:153], v[48:51]
	v_mfma_f32_16x16x32_bf16 v[36:39], v[134:137], v[158:161], v[36:39]
	v_mfma_f32_16x16x32_bf16 v[32:35], v[142:145], v[158:161], v[32:35]
	v_mfma_f32_16x16x32_bf16 v[20:23], v[134:137], v[166:169], v[20:23]
	v_mfma_f32_16x16x32_bf16 v[16:19], v[142:145], v[166:169], v[16:19]
	v_mfma_f32_16x16x32_bf16 v[4:7], v[134:137], v[174:177], v[4:7]
	v_mfma_f32_16x16x32_bf16 v[0:3], v[142:145], v[174:177], v[0:3]
	v_mfma_f32_16x16x32_bf16 v[52:55], v[138:141], v[154:157], v[52:55]
	v_mfma_f32_16x16x32_bf16 v[48:51], v[146:149], v[154:157], v[48:51]
	v_mfma_f32_16x16x32_bf16 v[36:39], v[138:141], v[162:165], v[36:39]
	v_mfma_f32_16x16x32_bf16 v[32:35], v[146:149], v[162:165], v[32:35]
	v_mfma_f32_16x16x32_bf16 v[20:23], v[138:141], v[170:173], v[20:23]
	v_mfma_f32_16x16x32_bf16 v[16:19], v[146:149], v[170:173], v[16:19]
	v_mfma_f32_16x16x32_bf16 v[4:7], v[138:141], v[178:181], v[4:7]
	v_mfma_f32_16x16x32_bf16 v[0:3], v[146:149], v[178:181], v[0:3]
	s_barrier
	s_add_i32 s2, s2, s18
	v_lshl_add_u64 v[134:135], v[210:211], 0, s[16:17]
	s_mov_b32 m0, s2
	s_nop 0
	global_load_lds_dwordx4 v[134:135], off
	v_lshl_add_u64 v[134:135], v[214:215], 0, s[16:17]
	s_add_i32 m0, s2, 0x2000
	s_nop 0
	global_load_lds_dwordx4 v[134:135], off
	s_waitcnt vmcnt(6)
	s_barrier
	v_mfma_f32_16x16x32_bf16 v[60:63], v[182:185], v[150:153], v[60:63]
	v_mfma_f32_16x16x32_bf16 v[56:59], v[190:193], v[150:153], v[56:59]
	v_mfma_f32_16x16x32_bf16 v[44:47], v[182:185], v[158:161], v[44:47]
	v_mfma_f32_16x16x32_bf16 v[40:43], v[190:193], v[158:161], v[40:43]
	v_mfma_f32_16x16x32_bf16 v[28:31], v[182:185], v[166:169], v[28:31]
	v_mfma_f32_16x16x32_bf16 v[24:27], v[190:193], v[166:169], v[24:27]
	v_mfma_f32_16x16x32_bf16 v[12:15], v[182:185], v[174:177], v[12:15]
	v_mfma_f32_16x16x32_bf16 v[8:11], v[190:193], v[174:177], v[8:11]
	v_mfma_f32_16x16x32_bf16 v[60:63], v[186:189], v[154:157], v[60:63]
	v_mfma_f32_16x16x32_bf16 v[56:59], v[194:197], v[154:157], v[56:59]
	v_mfma_f32_16x16x32_bf16 v[44:47], v[186:189], v[162:165], v[44:47]
	v_mfma_f32_16x16x32_bf16 v[40:43], v[194:197], v[162:165], v[40:43]
	v_mfma_f32_16x16x32_bf16 v[28:31], v[186:189], v[170:173], v[28:31]
	v_mfma_f32_16x16x32_bf16 v[24:27], v[194:197], v[170:173], v[24:27]
	v_mfma_f32_16x16x32_bf16 v[12:15], v[186:189], v[178:181], v[12:15]
	v_mfma_f32_16x16x32_bf16 v[8:11], v[194:197], v[178:181], v[8:11]
	s_barrier
	s_cmp_ge_u32 s12, s6
	s_cbranch_scc1 .LBB0_482

; #define PG8_STAGE(bufoff, gbase, voff) do { _Pragma("unroll") for (int _i = 0; _i < 2; ++_i) \
;         __builtin_amdgcn_global_load_lds((const unsigned*)((const char*)(gbase) + (voff)[_i]), (LAS unsigned*)(lds + (bufoff) + ldsw + _i * 8192), 16, 0, 0); } while (0)
; #define PG8_LDA(dst, b, h) do { _Pragma("unroll") for (int m = 0; m < 4; ++m) _Pragma("unroll") for (int k = 0; k < 2; ++k) dst[m][k] = *(const LAS bf16x8*)(lds + PG8_SA(b, h) + aoff + m * 2048 + k * 1024); } while (0)
; #define PG8_LDB(dst, b, h) do { _Pragma("unroll") for (int n = 0; n < 2; ++n) _Pragma("unroll") for (int k = 0; k < 2; ++k) dst[n][k] = *(const LAS bf16x8*)(lds + PG8_SB(b, h) + boff + n * 2048 + k * 1024); } while (0)
; #define PG8_MMA(ai, bj, At, Bt) do { __builtin_amdgcn_s_setprio(1); _Pragma("unroll") for (int m = 0; m < 4; ++m) _Pragma("unroll") for (int n = 0; n < 2; ++n) _Pragma("unroll") for (int k = 0; k < 2; ++k) \
;         acc[ai][bj][m][n] = __builtin_amdgcn_mfma_f32_16x16x32_bf16(Bt[n][k], At[m][k], acc[ai][bj][m][n], 0, 0, 0); __builtin_amdgcn_s_setprio(0); } while (0)
; #define PG8_WAIT_L(n) asm volatile("s_waitcnt lgkmcnt(" #n ")" ::: "memory")
; #define PG8_BAR __builtin_amdgcn_s_barrier()
; #define PG8_SCHED __builtin_amdgcn_sched_barrier(0)
;     ...
;             const char* a1 = cA + (size_t)(t + 1) * kstep;
;             const char* a2 = last ? nA : cA + (size_t)(t + 2) * kstep; const char* b2 = last ? nB : cB + (size_t)(t + 2) * kstep;
;             const char* a3 = a2 + kstep; const char* b3 = b2 + kstep;
;             PG8_LDB(B0, 0, 0); PG8_SCHED; PG8_LDA(At, 0, 0); PG8_STAGE(PG8_SA(1, 1), a1 + hstep, voffA);
;             PG8_WAIT_L(8); PG8_BAR; PG8_WAIT_L(0); PG8_MMA(0, 0, At, B0); PG8_BAR; PG8_SCHED;
;             PG8_LDB(B1, 0, 1); PG8_STAGE(PG8_SB(0, 0), b2, voffB);
;             PG8_BAR; PG8_WAIT_L(0); PG8_MMA(0, 1, At, B1); PG8_BAR;
;             PG8_LDA(At, 0, 1); PG8_STAGE(PG8_SA(0, 0), a2, voffA);
;             PG8_BAR; PG8_WAIT_L(0); PG8_MMA(1, 0, At, B0); PG8_BAR; PG8_SCHED;
.LBB0_1275:
	s_add_u32 s2, s6, 0xe767c080
	s_addc_u32 s3, s7, -1
	s_cmp_lg_u32 s23, 28
	s_cselect_b32 s8, s2, 0
	s_cselect_b32 s9, s3, 0
	s_add_u32 s2, s4, s8
	s_addc_u32 s3, s5, s9
	s_add_i32 s24, 0, 0x10000
	v_add_u32_e32 v152, s24, v138
	ds_read_b128 v[140:143], v152
	ds_read_b128 v[144:147], v152 offset:1024
	ds_read_b128 v[148:151], v152 offset:2048
	ds_read_b128 v[152:155], v152 offset:3072
	s_add_u32 s8, s0, s8
	s_addc_u32 s9, s1, s9
	v_lshl_add_u64 v[188:189], v[132:133], 0, s[6:7]
	s_add_i32 m0, s15, 0xc000
	ds_read_b128 v[156:159], v139
	ds_read_b128 v[160:163], v139 offset:1024
	ds_read_b128 v[164:167], v139 offset:2048
	ds_read_b128 v[168:171], v139 offset:3072
	ds_read_b128 v[172:175], v139 offset:4096
	ds_read_b128 v[176:179], v139 offset:5120
	ds_read_b128 v[180:183], v139 offset:6144
	ds_read_b128 v[184:187], v139 offset:7168
	global_load_lds_dwordx4 v[188:189], off
	v_lshl_add_u64 v[188:189], v[134:135], 0, s[6:7]
	s_add_i32 m0, s15, 0xe000
	s_nop 0
	global_load_lds_dwordx4 v[188:189], off
	s_waitcnt lgkmcnt(8)
	s_barrier
	s_waitcnt lgkmcnt(0)
	v_mfma_f32_16x16x32_bf16 v[126:129], v[140:143], v[156:159], v[126:129]
	v_mfma_f32_16x16x32_bf16 v[122:125], v[148:151], v[156:159], v[122:125]
	v_mfma_f32_16x16x32_bf16 v[110:113], v[140:143], v[164:167], v[110:113]
	v_mfma_f32_16x16x32_bf16 v[106:109], v[148:151], v[164:167], v[106:109]
	v_mfma_f32_16x16x32_bf16 v[94:97], v[140:143], v[172:175], v[94:97]
	v_mfma_f32_16x16x32_bf16 v[90:93], v[148:151], v[172:175], v[90:93]
	v_mfma_f32_16x16x32_bf16 v[78:81], v[140:143], v[180:183], v[78:81]
	v_mfma_f32_16x16x32_bf16 v[74:77], v[148:151], v[180:183], v[74:77]
	v_mfma_f32_16x16x32_bf16 v[126:129], v[144:147], v[160:163], v[126:129]
	v_mfma_f32_16x16x32_bf16 v[122:125], v[152:155], v[160:163], v[122:125]
	v_mfma_f32_16x16x32_bf16 v[110:113], v[144:147], v[168:171], v[110:113]
	v_mfma_f32_16x16x32_bf16 v[106:109], v[152:155], v[168:171], v[106:109]
	v_mfma_f32_16x16x32_bf16 v[94:97], v[144:147], v[176:179], v[94:97]
	v_mfma_f32_16x16x32_bf16 v[90:93], v[152:155], v[176:179], v[90:93]
	v_mfma_f32_16x16x32_bf16 v[78:81], v[144:147], v[184:187], v[78:81]
	v_mfma_f32_16x16x32_bf16 v[74:77], v[152:155], v[184:187], v[74:77]
	s_barrier
	s_add_i32 s26, 0, 0x14000
	s_add_i32 s24, s24, s14
	v_add_u32_e32 v208, s26, v138
	v_lshl_add_u64 v[224:225], s[8:9], 0, v[64:65]
	s_mov_b32 m0, s24
	ds_read_b128 v[188:191], v208
	ds_read_b128 v[192:195], v208 offset:1024
	ds_read_b128 v[196:199], v208 offset:2048
	ds_read_b128 v[220:223], v208 offset:3072
	global_load_lds_dwordx4 v[224:225], off
	v_lshl_add_u64 v[226:227], s[8:9], 0, v[130:131]
	s_add_i32 m0, s24, 0x2000
	s_nop 0
	global_load_lds_dwordx4 v[226:227], off
	s_barrier
	s_waitcnt lgkmcnt(0)
	v_mfma_f32_16x16x32_bf16 v[118:121], v[188:191], v[156:159], v[118:121]
	v_mfma_f32_16x16x32_bf16 v[114:117], v[196:199], v[156:159], v[114:117]
	v_mfma_f32_16x16x32_bf16 v[102:105], v[188:191], v[164:167], v[102:105]
	v_mfma_f32_16x16x32_bf16 v[98:101], v[196:199], v[164:167], v[98:101]
	v_mfma_f32_16x16x32_bf16 v[86:89], v[188:191], v[172:175], v[86:89]
	v_mfma_f32_16x16x32_bf16 v[82:85], v[196:199], v[172:175], v[82:85]
	v_mfma_f32_16x16x32_bf16 v[70:73], v[188:191], v[180:183], v[70:73]
	v_mfma_f32_16x16x32_bf16 v[66:69], v[196:199], v[180:183], v[66:69]
	v_mfma_f32_16x16x32_bf16 v[118:121], v[192:195], v[160:163], v[118:121]
	v_mfma_f32_16x16x32_bf16 v[114:117], v[220:223], v[160:163], v[114:117]
	v_mfma_f32_16x16x32_bf16 v[102:105], v[192:195], v[168:171], v[102:105]
	v_mfma_f32_16x16x32_bf16 v[98:101], v[220:223], v[168:171], v[98:101]
	v_mfma_f32_16x16x32_bf16 v[86:89], v[192:195], v[176:179], v[86:89]
	v_mfma_f32_16x16x32_bf16 v[82:85], v[220:223], v[176:179], v[82:85]
	v_mfma_f32_16x16x32_bf16 v[70:73], v[192:195], v[184:187], v[70:73]
	v_mfma_f32_16x16x32_bf16 v[66:69], v[220:223], v[184:187], v[66:69]
	s_barrier
	s_mov_b32 m0, s15
	v_lshl_add_u64 v[228:229], s[2:3], 0, v[64:65]
	ds_read_b128 v[156:159], v139 offset:16384
	ds_read_b128 v[160:163], v139 offset:17408
	ds_read_b128 v[164:167], v139 offset:18432
	ds_read_b128 v[168:171], v139 offset:19456
	ds_read_b128 v[172:175], v139 offset:20480
	ds_read_b128 v[176:179], v139 offset:21504
	ds_read_b128 v[180:183], v139 offset:22528
	ds_read_b128 v[184:187], v139 offset:23552
	global_load_lds_dwordx4 v[228:229], off
	v_lshl_add_u64 v[230:231], s[2:3], 0, v[130:131]
	s_mov_b32 m0, s18
	s_nop 0
	global_load_lds_dwordx4 v[230:231], off
	s_barrier
	s_waitcnt lgkmcnt(0)
	v_mfma_f32_16x16x32_bf16 v[60:63], v[140:143], v[156:159], v[60:63]
	v_mfma_f32_16x16x32_bf16 v[56:59], v[148:151], v[156:159], v[56:59]
	v_mfma_f32_16x16x32_bf16 v[44:47], v[140:143], v[164:167], v[44:47]
	v_mfma_f32_16x16x32_bf16 v[40:43], v[148:151], v[164:167], v[40:43]
	v_mfma_f32_16x16x32_bf16 v[28:31], v[140:143], v[172:175], v[28:31]
	v_mfma_f32_16x16x32_bf16 v[24:27], v[148:151], v[172:175], v[24:27]
	v_mfma_f32_16x16x32_bf16 v[12:15], v[140:143], v[180:183], v[12:15]
	v_mfma_f32_16x16x32_bf16 v[8:11], v[148:151], v[180:183], v[8:11]
	v_mfma_f32_16x16x32_bf16 v[60:63], v[144:147], v[160:163], v[60:63]
	v_mfma_f32_16x16x32_bf16 v[56:59], v[152:155], v[160:163], v[56:59]
	v_mfma_f32_16x16x32_bf16 v[44:47], v[144:147], v[168:171], v[44:47]
	v_mfma_f32_16x16x32_bf16 v[40:43], v[152:155], v[168:171], v[40:43]
	v_mfma_f32_16x16x32_bf16 v[28:31], v[144:147], v[176:179], v[28:31]
	v_mfma_f32_16x16x32_bf16 v[24:27], v[152:155], v[176:179], v[24:27]
	v_mfma_f32_16x16x32_bf16 v[12:15], v[144:147], v[184:187], v[12:15]
	v_mfma_f32_16x16x32_bf16 v[8:11], v[152:155], v[184:187], v[8:11]
	s_barrier
; #define PG8_STAGE(bufoff, gbase, voff) do { _Pragma("unroll") for (int _i = 0; _i < 2; ++_i) \
;         __builtin_amdgcn_global_load_lds((const unsigned*)((const char*)(gbase) + (voff)[_i]), (LAS unsigned*)(lds + (bufoff) + ldsw + _i * 8192), 16, 0, 0); } while (0)
; #define PG8_LDA(dst, b, h) do { _Pragma("unroll") for (int m = 0; m < 4; ++m) _Pragma("unroll") for (int k = 0; k < 2; ++k) dst[m][k] = *(const LAS bf16x8*)(lds + PG8_SA(b, h) + aoff + m * 2048 + k * 1024); } while (0)
; #define PG8_LDB(dst, b, h) do { _Pragma("unroll") for (int n = 0; n < 2; ++n) _Pragma("unroll") for (int k = 0; k < 2; ++k) dst[n][k] = *(const LAS bf16x8*)(lds + PG8_SB(b, h) + boff + n * 2048 + k * 1024); } while (0)
; #define PG8_MMA(ai, bj, At, Bt) do { __builtin_amdgcn_s_setprio(1); _Pragma("unroll") for (int m = 0; m < 4; ++m) _Pragma("unroll") for (int n = 0; n < 2; ++n) _Pragma("unroll") for (int k = 0; k < 2; ++k) \
;         acc[ai][bj][m][n] = __builtin_amdgcn_mfma_f32_16x16x32_bf16(Bt[n][k], At[m][k], acc[ai][bj][m][n], 0, 0, 0); __builtin_amdgcn_s_setprio(0); } while (0)
; #define PG8_WAIT_V(n) asm volatile("s_waitcnt vmcnt(" #n ")" ::: "memory")
; #define PG8_WAIT_L(n) asm volatile("s_waitcnt lgkmcnt(" #n ")" ::: "memory")
; #define PG8_BAR __builtin_amdgcn_s_barrier()
; #define PG8_SCHED __builtin_amdgcn_sched_barrier(0)
;     ...
;             PG8_STAGE(PG8_SB(0, 1), b2 + hstep, voffB);
;             PG8_WAIT_V(6); PG8_BAR; PG8_MMA(1, 1, At, B1); PG8_BAR;
;             PG8_LDB(B0, 1, 0); PG8_SCHED; PG8_LDA(At, 1, 0); PG8_STAGE(PG8_SA(0, 1), a2 + hstep, voffA);
;             PG8_WAIT_L(8); PG8_BAR; PG8_WAIT_L(0); PG8_MMA(0, 0, At, B0); PG8_BAR; PG8_SCHED;
;             PG8_LDB(B1, 1, 1); PG8_STAGE(PG8_SB(1, 0), b3, voffB);
;             PG8_BAR; PG8_WAIT_L(0); PG8_MMA(0, 1, At, B1); PG8_BAR;
	s_add_u32 s24, s8, 0x84000
	s_addc_u32 s25, s9, 0
	s_add_i32 s26, s26, s14
	v_lshl_add_u64 v[140:141], s[24:25], 0, v[64:65]
	s_mov_b32 m0, s26
	s_nop 0
	global_load_lds_dwordx4 v[140:141], off
	v_lshl_add_u64 v[140:141], s[24:25], 0, v[130:131]
	s_add_i32 m0, s26, 0x2000
	s_nop 0
	global_load_lds_dwordx4 v[140:141], off
	s_waitcnt vmcnt(6)
	s_barrier
	v_mfma_f32_16x16x32_bf16 v[52:55], v[188:191], v[156:159], v[52:55]
	v_mfma_f32_16x16x32_bf16 v[48:51], v[196:199], v[156:159], v[48:51]
	v_mfma_f32_16x16x32_bf16 v[36:39], v[188:191], v[164:167], v[36:39]
	v_mfma_f32_16x16x32_bf16 v[32:35], v[196:199], v[164:167], v[32:35]
	v_mfma_f32_16x16x32_bf16 v[20:23], v[188:191], v[172:175], v[20:23]
	v_mfma_f32_16x16x32_bf16 v[16:19], v[196:199], v[172:175], v[16:19]
	v_mfma_f32_16x16x32_bf16 v[4:7], v[188:191], v[180:183], v[4:7]
	v_mfma_f32_16x16x32_bf16 v[0:3], v[196:199], v[180:183], v[0:3]
	v_mfma_f32_16x16x32_bf16 v[52:55], v[192:195], v[160:163], v[52:55]
	v_mfma_f32_16x16x32_bf16 v[48:51], v[220:223], v[160:163], v[48:51]
	v_mfma_f32_16x16x32_bf16 v[36:39], v[192:195], v[168:171], v[36:39]
	v_mfma_f32_16x16x32_bf16 v[32:35], v[220:223], v[168:171], v[32:35]
	v_mfma_f32_16x16x32_bf16 v[20:23], v[192:195], v[176:179], v[20:23]
	v_mfma_f32_16x16x32_bf16 v[16:19], v[220:223], v[176:179], v[16:19]
	v_mfma_f32_16x16x32_bf16 v[4:7], v[192:195], v[184:187], v[4:7]
	v_mfma_f32_16x16x32_bf16 v[0:3], v[220:223], v[184:187], v[0:3]
	s_barrier
	s_add_i32 s24, 0, 0x18000
	v_add_u32_e32 v152, s24, v138
	ds_read_b128 v[140:143], v152
	ds_read_b128 v[144:147], v152 offset:1024
	ds_read_b128 v[148:151], v152 offset:2048
	ds_read_b128 v[152:155], v152 offset:3072
	s_add_u32 s2, s2, 0x84000
	s_addc_u32 s3, s3, 0
	s_mov_b32 m0, s19
	v_lshl_add_u64 v[188:189], s[2:3], 0, v[64:65]
	ds_read_b128 v[156:159], v139 offset:32768
	ds_read_b128 v[160:163], v139 offset:33792
	ds_read_b128 v[164:167], v139 offset:34816
	ds_read_b128 v[168:171], v139 offset:35840
	ds_read_b128 v[172:175], v139 offset:36864
	ds_read_b128 v[176:179], v139 offset:37888
	ds_read_b128 v[180:183], v139 offset:38912
	ds_read_b128 v[184:187], v139 offset:39936
	global_load_lds_dwordx4 v[188:189], off
	v_lshl_add_u64 v[188:189], s[2:3], 0, v[130:131]
	s_mov_b32 m0, s20
	s_nop 0
	global_load_lds_dwordx4 v[188:189], off
	s_waitcnt lgkmcnt(8)
	s_barrier
	s_waitcnt lgkmcnt(0)
	v_mfma_f32_16x16x32_bf16 v[126:129], v[140:143], v[156:159], v[126:129]
	v_mfma_f32_16x16x32_bf16 v[122:125], v[148:151], v[156:159], v[122:125]
	v_mfma_f32_16x16x32_bf16 v[110:113], v[140:143], v[164:167], v[110:113]
	v_mfma_f32_16x16x32_bf16 v[106:109], v[148:151], v[164:167], v[106:109]
	v_mfma_f32_16x16x32_bf16 v[94:97], v[140:143], v[172:175], v[94:97]
	v_mfma_f32_16x16x32_bf16 v[90:93], v[148:151], v[172:175], v[90:93]
	v_mfma_f32_16x16x32_bf16 v[78:81], v[140:143], v[180:183], v[78:81]
	v_mfma_f32_16x16x32_bf16 v[74:77], v[148:151], v[180:183], v[74:77]
	v_mfma_f32_16x16x32_bf16 v[126:129], v[144:147], v[160:163], v[126:129]
	v_mfma_f32_16x16x32_bf16 v[122:125], v[152:155], v[160:163], v[122:125]
	v_mfma_f32_16x16x32_bf16 v[110:113], v[144:147], v[168:171], v[110:113]
	v_mfma_f32_16x16x32_bf16 v[106:109], v[152:155], v[168:171], v[106:109]
	v_mfma_f32_16x16x32_bf16 v[94:97], v[144:147], v[176:179], v[94:97]
	v_mfma_f32_16x16x32_bf16 v[90:93], v[152:155], v[176:179], v[90:93]
	v_mfma_f32_16x16x32_bf16 v[78:81], v[144:147], v[184:187], v[78:81]
	v_mfma_f32_16x16x32_bf16 v[74:77], v[152:155], v[184:187], v[74:77]
	s_barrier
	s_add_i32 s25, 0, 0x1c000
	s_add_i32 s2, s24, s14
	v_add_u32_e32 v208, s25, v138
	v_lshl_add_u64 v[224:225], v[224:225], 0, s[16:17]
	s_mov_b32 m0, s2
	ds_read_b128 v[188:191], v208
	ds_read_b128 v[192:195], v208 offset:1024
	ds_read_b128 v[196:199], v208 offset:2048
	ds_read_b128 v[220:223], v208 offset:3072
	global_load_lds_dwordx4 v[224:225], off
	v_lshl_add_u64 v[224:225], v[226:227], 0, s[16:17]
	s_add_i32 m0, s2, 0x2000
	s_nop 0
	global_load_lds_dwordx4 v[224:225], off
	s_barrier
	s_waitcnt lgkmcnt(0)
	v_mfma_f32_16x16x32_bf16 v[118:121], v[188:191], v[156:159], v[118:121]
	v_mfma_f32_16x16x32_bf16 v[114:117], v[196:199], v[156:159], v[114:117]
	v_mfma_f32_16x16x32_bf16 v[102:105], v[188:191], v[164:167], v[102:105]
	v_mfma_f32_16x16x32_bf16 v[98:101], v[196:199], v[164:167], v[98:101]
	v_mfma_f32_16x16x32_bf16 v[86:89], v[188:191], v[172:175], v[86:89]
	v_mfma_f32_16x16x32_bf16 v[82:85], v[196:199], v[172:175], v[82:85]
	v_mfma_f32_16x16x32_bf16 v[70:73], v[188:191], v[180:183], v[70:73]
	v_mfma_f32_16x16x32_bf16 v[66:69], v[196:199], v[180:183], v[66:69]
	v_mfma_f32_16x16x32_bf16 v[118:121], v[192:195], v[160:163], v[118:121]
	v_mfma_f32_16x16x32_bf16 v[114:117], v[220:223], v[160:163], v[114:117]
	v_mfma_f32_16x16x32_bf16 v[102:105], v[192:195], v[168:171], v[102:105]
	v_mfma_f32_16x16x32_bf16 v[98:101], v[220:223], v[168:171], v[98:101]
	v_mfma_f32_16x16x32_bf16 v[86:89], v[192:195], v[176:179], v[86:89]
	v_mfma_f32_16x16x32_bf16 v[82:85], v[220:223], v[176:179], v[82:85]
	v_mfma_f32_16x16x32_bf16 v[70:73], v[192:195], v[184:187], v[70:73]
	v_mfma_f32_16x16x32_bf16 v[66:69], v[220:223], v[184:187], v[66:69]
	s_barrier
; #define PG8_STAGE(bufoff, gbase, voff) do { _Pragma("unroll") for (int _i = 0; _i < 2; ++_i) \
;         __builtin_amdgcn_global_load_lds((const unsigned*)((const char*)(gbase) + (voff)[_i]), (LAS unsigned*)(lds + (bufoff) + ldsw + _i * 8192), 16, 0, 0); } while (0)
; #define PG8_LDA(dst, b, h) do { _Pragma("unroll") for (int m = 0; m < 4; ++m) _Pragma("unroll") for (int k = 0; k < 2; ++k) dst[m][k] = *(const LAS bf16x8*)(lds + PG8_SA(b, h) + aoff + m * 2048 + k * 1024); } while (0)
; #define PG8_MMA(ai, bj, At, Bt) do { __builtin_amdgcn_s_setprio(1); _Pragma("unroll") for (int m = 0; m < 4; ++m) _Pragma("unroll") for (int n = 0; n < 2; ++n) _Pragma("unroll") for (int k = 0; k < 2; ++k) \
;         acc[ai][bj][m][n] = __builtin_amdgcn_mfma_f32_16x16x32_bf16(Bt[n][k], At[m][k], acc[ai][bj][m][n], 0, 0, 0); __builtin_amdgcn_s_setprio(0); } while (0)
; #define PG8_WAIT_V(n) asm volatile("s_waitcnt vmcnt(" #n ")" ::: "memory")
; #define PG8_WAIT_L(n) asm volatile("s_waitcnt lgkmcnt(" #n ")" ::: "memory")
; #define PG8_BAR __builtin_amdgcn_s_barrier()
; #define PG8_SCHED __builtin_amdgcn_sched_barrier(0)
; __device__ __forceinline__ f32x4 gelu4(const f32x4 x) {
;     const f32x4 t = x * x, a = x * (t * -0.10294324f + -2.3022082f);
;     f32x4 e; e[0] = __builtin_amdgcn_exp2f(a[0]); e[1] = __builtin_amdgcn_exp2f(a[1]); e[2] = __builtin_amdgcn_exp2f(a[2]); e[3] = __builtin_amdgcn_exp2f(a[3]);
;     const f32x4 d = e + 1.0f;
;     f32x4 r; r[0] = __builtin_amdgcn_rcpf(d[0]); r[1] = __builtin_amdgcn_rcpf(d[1]); r[2] = __builtin_amdgcn_rcpf(d[2]); r[3] = __builtin_amdgcn_rcpf(d[3]);
;     return x * r;
; }
;     ...
;             PG8_BAR; PG8_WAIT_L(0); PG8_MMA(0, 1, At, B1); PG8_BAR;
;             PG8_LDA(At, 1, 1); PG8_STAGE(PG8_SA(1, 0), a3, voffA);
;             PG8_BAR; PG8_WAIT_L(0); PG8_MMA(1, 0, At, B0); PG8_BAR; PG8_SCHED;
;             PG8_STAGE(PG8_SB(1, 1), b3 + hstep, voffB);
;             PG8_WAIT_V(6); PG8_BAR; PG8_MMA(1, 1, At, B1); PG8_BAR;
;         }
;         if constexpr (Epi::FUSE_LN) {
;             if (E.fuse && cur.ks < 0) { if (wr == 0) PG8_BAR; E.fused(acc, cur, wr, wc, fr, fq, lds); if (wr == 1) PG8_BAR; }
;             else E(acc, cur, wr, wc, fr, fq);
;         } else E(acc, cur, wr, wc, fr, fq);
;         if (!has_next) break;
	s_mov_b32 m0, s21
	v_lshl_add_u64 v[224:225], v[228:229], 0, s[16:17]
	ds_read_b128 v[156:159], v139 offset:49152
	ds_read_b128 v[160:163], v139 offset:50176
	ds_read_b128 v[164:167], v139 offset:51200
	ds_read_b128 v[168:171], v139 offset:52224
	ds_read_b128 v[172:175], v139 offset:53248
	ds_read_b128 v[176:179], v139 offset:54272
	ds_read_b128 v[180:183], v139 offset:55296
	ds_read_b128 v[184:187], v139 offset:56320
	global_load_lds_dwordx4 v[224:225], off
	v_lshl_add_u64 v[224:225], v[230:231], 0, s[16:17]
	s_mov_b32 m0, s22
	s_nop 0
	global_load_lds_dwordx4 v[224:225], off
	s_barrier
	s_waitcnt lgkmcnt(0)
	v_mfma_f32_16x16x32_bf16 v[60:63], v[140:143], v[156:159], v[60:63]
	v_mfma_f32_16x16x32_bf16 v[56:59], v[148:151], v[156:159], v[56:59]
	v_mfma_f32_16x16x32_bf16 v[44:47], v[140:143], v[164:167], v[44:47]
	v_mfma_f32_16x16x32_bf16 v[40:43], v[148:151], v[164:167], v[40:43]
	v_mfma_f32_16x16x32_bf16 v[28:31], v[140:143], v[172:175], v[28:31]
	v_mfma_f32_16x16x32_bf16 v[24:27], v[148:151], v[172:175], v[24:27]
	v_mfma_f32_16x16x32_bf16 v[12:15], v[140:143], v[180:183], v[12:15]
	v_mfma_f32_16x16x32_bf16 v[8:11], v[148:151], v[180:183], v[8:11]
	v_mfma_f32_16x16x32_bf16 v[60:63], v[144:147], v[160:163], v[60:63]
	v_mfma_f32_16x16x32_bf16 v[56:59], v[152:155], v[160:163], v[56:59]
	v_mfma_f32_16x16x32_bf16 v[44:47], v[144:147], v[168:171], v[44:47]
	v_mfma_f32_16x16x32_bf16 v[40:43], v[152:155], v[168:171], v[40:43]
	v_mfma_f32_16x16x32_bf16 v[28:31], v[144:147], v[176:179], v[28:31]
	v_mfma_f32_16x16x32_bf16 v[24:27], v[152:155], v[176:179], v[24:27]
	v_mfma_f32_16x16x32_bf16 v[12:15], v[144:147], v[184:187], v[12:15]
	v_mfma_f32_16x16x32_bf16 v[8:11], v[152:155], v[184:187], v[8:11]
	s_barrier
	s_add_u32 s2, s8, 0x84080
	s_addc_u32 s3, s9, 0
	s_add_i32 s8, s25, s14
	v_lshl_add_u64 v[140:141], s[2:3], 0, v[64:65]
	s_mov_b32 m0, s8
	s_nop 0
	global_load_lds_dwordx4 v[140:141], off
	v_lshl_add_u64 v[140:141], s[2:3], 0, v[130:131]
	s_add_i32 m0, s8, 0x2000
	s_nop 0
	global_load_lds_dwordx4 v[140:141], off
	s_waitcnt vmcnt(6)
	s_barrier
	v_mfma_f32_16x16x32_bf16 v[52:55], v[188:191], v[156:159], v[52:55]
	v_mfma_f32_16x16x32_bf16 v[48:51], v[196:199], v[156:159], v[48:51]
	v_mfma_f32_16x16x32_bf16 v[36:39], v[188:191], v[164:167], v[36:39]
	v_mfma_f32_16x16x32_bf16 v[32:35], v[196:199], v[164:167], v[32:35]
	v_mfma_f32_16x16x32_bf16 v[20:23], v[188:191], v[172:175], v[20:23]
	v_mfma_f32_16x16x32_bf16 v[16:19], v[196:199], v[172:175], v[16:19]
	v_mfma_f32_16x16x32_bf16 v[4:7], v[188:191], v[180:183], v[4:7]
	v_mfma_f32_16x16x32_bf16 v[0:3], v[196:199], v[180:183], v[0:3]
	v_mfma_f32_16x16x32_bf16 v[52:55], v[192:195], v[160:163], v[52:55]
	v_mfma_f32_16x16x32_bf16 v[48:51], v[220:223], v[160:163], v[48:51]
	v_mfma_f32_16x16x32_bf16 v[36:39], v[192:195], v[168:171], v[36:39]
	v_mfma_f32_16x16x32_bf16 v[32:35], v[220:223], v[168:171], v[32:35]
	v_mfma_f32_16x16x32_bf16 v[20:23], v[192:195], v[176:179], v[20:23]
	v_mfma_f32_16x16x32_bf16 v[16:19], v[220:223], v[176:179], v[16:19]
	v_mfma_f32_16x16x32_bf16 v[4:7], v[192:195], v[184:187], v[4:7]
	v_mfma_f32_16x16x32_bf16 v[0:3], v[220:223], v[184:187], v[0:3]
	s_barrier
	s_add_i32 s23, s23, 2
	s_add_u32 s6, s6, 0x100
	s_addc_u32 s7, s7, 0
	s_cmp_gt_u32 s23, 29
	s_cbranch_scc0 .LBB0_1275
	s_add_i32 s0, s11, -2
	s_cmp_lt_u32 s0, 8
	s_cselect_b64 s[2:3], -1, 0
	s_cmp_gt_u32 s0, 7
	s_cbranch_scc1 .LBB0_1278
	s_mov_b32 s0, 0xc0135761
	v_pk_mul_f32 v[130:131], v[128:129], v[128:129]
	v_pk_mul_f32 v[132:133], v[126:127], v[126:127]
	v_mov_b64_e32 v[134:135], s[0:1]
	s_mov_b32 s0, 0xbdd2d3e8
	v_pk_fma_f32 v[130:131], v[130:131], s[0:1], v[134:135] op_sel_hi:[1,0,0]
	v_pk_fma_f32 v[132:133], v[132:133], s[0:1], v[134:135] op_sel_hi:[1,0,0]
	v_pk_mul_f32 v[130:131], v[128:129], v[130:131]
	v_pk_mul_f32 v[132:133], v[126:127], v[132:133]
	v_exp_f32_e32 v130, v130
	v_exp_f32_e32 v132, v132
	v_exp_f32_e32 v131, v131
	v_exp_f32_e32 v133, v133
	v_pk_add_f32 v[130:131], v[130:131], 1.0 op_sel_hi:[1,0]
	v_pk_add_f32 v[132:133], v[132:133], 1.0 op_sel_hi:[1,0]
	v_rcp_f32_e32 v130, v130
	v_rcp_f32_e32 v132, v132
	v_rcp_f32_e32 v131, v131
	v_rcp_f32_e32 v133, v133
	v_pk_mul_f32 v[128:129], v[128:129], v[130:131]
	v_pk_mul_f32 v[126:127], v[126:127], v[132:133]

; #define PG8_STAGE(bufoff, gbase, voff) do { _Pragma("unroll") for (int _i = 0; _i < 2; ++_i) \
;         __builtin_amdgcn_global_load_lds((const unsigned*)((const char*)(gbase) + (voff)[_i]), (LAS unsigned*)(lds + (bufoff) + ldsw + _i * 8192), 16, 0, 0); } while (0)
; #define PG8_LDA(dst, b, h) do { _Pragma("unroll") for (int m = 0; m < 4; ++m) _Pragma("unroll") for (int k = 0; k < 2; ++k) dst[m][k] = *(const LAS bf16x8*)(lds + PG8_SA(b, h) + aoff + m * 2048 + k * 1024); } while (0)
; #define PG8_LDB(dst, b, h) do { _Pragma("unroll") for (int n = 0; n < 2; ++n) _Pragma("unroll") for (int k = 0; k < 2; ++k) dst[n][k] = *(const LAS bf16x8*)(lds + PG8_SB(b, h) + boff + n * 2048 + k * 1024); } while (0)
; #define PG8_MMA(ai, bj, At, Bt) do { __builtin_amdgcn_s_setprio(1); _Pragma("unroll") for (int m = 0; m < 4; ++m) _Pragma("unroll") for (int n = 0; n < 2; ++n) _Pragma("unroll") for (int k = 0; k < 2; ++k) \
;         acc[ai][bj][m][n] = __builtin_amdgcn_mfma_f32_16x16x32_bf16(Bt[n][k], At[m][k], acc[ai][bj][m][n], 0, 0, 0); __builtin_amdgcn_s_setprio(0); } while (0)
; #define PG8_WAIT_L(n) asm volatile("s_waitcnt lgkmcnt(" #n ")" ::: "memory")
; #define PG8_BAR __builtin_amdgcn_s_barrier()
; #define PG8_SCHED __builtin_amdgcn_sched_barrier(0)
;     ...
;             const char* a1 = cA + (size_t)(t + 1) * kstep;
;             const char* a2 = last ? nA : cA + (size_t)(t + 2) * kstep; const char* b2 = last ? nB : cB + (size_t)(t + 2) * kstep;
;             const char* a3 = a2 + kstep; const char* b3 = b2 + kstep;
;             PG8_LDB(B0, 0, 0); PG8_SCHED; PG8_LDA(At, 0, 0); PG8_STAGE(PG8_SA(1, 1), a1 + hstep, voffA);
;             PG8_WAIT_L(8); PG8_BAR; PG8_WAIT_L(0); PG8_MMA(0, 0, At, B0); PG8_BAR; PG8_SCHED;
;             PG8_LDB(B1, 0, 1); PG8_STAGE(PG8_SB(0, 0), b2, voffB);
;             PG8_BAR; PG8_WAIT_L(0); PG8_MMA(0, 1, At, B1); PG8_BAR;
;             PG8_LDA(At, 0, 1); PG8_STAGE(PG8_SA(0, 0), a2, voffA);
;             PG8_BAR; PG8_WAIT_L(0); PG8_MMA(1, 0, At, B0); PG8_BAR; PG8_SCHED;
.LBB0_1441:
	s_add_u32 s4, s0, 0x100
	s_addc_u32 s5, s1, 0
	s_add_i32 s43, 0, 0x10000
	v_add_u32_e32 v140, s43, v143
	ds_read_b128 v[136:139], v140
	ds_read_b128 v[146:149], v140 offset:1024
	ds_read_b128 v[150:153], v140 offset:2048
	ds_read_b128 v[154:157], v140 offset:3072
	s_cmp_eq_u32 s42, 28
	s_cselect_b32 s3, s21, s5
	s_cselect_b32 s2, s20, s4
	s_cselect_b32 s9, s23, s41
	s_cselect_b32 s8, s22, s40
	v_lshl_add_u64 v[140:141], s[0:1], 0, v[132:133]
	s_add_i32 m0, s12, 0xc000
	ds_read_b128 v[158:161], v145
	ds_read_b128 v[162:165], v145 offset:1024
	ds_read_b128 v[166:169], v145 offset:2048
	ds_read_b128 v[170:173], v145 offset:3072
	ds_read_b128 v[174:177], v145 offset:4096
	ds_read_b128 v[178:181], v145 offset:5120
	ds_read_b128 v[182:185], v145 offset:6144
	ds_read_b128 v[186:189], v145 offset:7168
	global_load_lds_dwordx4 v[140:141], off
	v_lshl_add_u64 v[140:141], s[0:1], 0, v[134:135]
	s_add_i32 m0, s12, 0xe000
	s_nop 0
	global_load_lds_dwordx4 v[140:141], off
	s_waitcnt lgkmcnt(8)
	s_barrier
	s_waitcnt lgkmcnt(0)
	v_mfma_f32_16x16x32_bf16 v[126:129], v[136:139], v[158:161], v[126:129]
	v_mfma_f32_16x16x32_bf16 v[122:125], v[150:153], v[158:161], v[122:125]
	v_mfma_f32_16x16x32_bf16 v[110:113], v[136:139], v[166:169], v[110:113]
	v_mfma_f32_16x16x32_bf16 v[106:109], v[150:153], v[166:169], v[106:109]
	v_mfma_f32_16x16x32_bf16 v[94:97], v[136:139], v[174:177], v[94:97]
	v_mfma_f32_16x16x32_bf16 v[90:93], v[150:153], v[174:177], v[90:93]
	v_mfma_f32_16x16x32_bf16 v[78:81], v[136:139], v[182:185], v[78:81]
	v_mfma_f32_16x16x32_bf16 v[74:77], v[150:153], v[182:185], v[74:77]
	v_mfma_f32_16x16x32_bf16 v[126:129], v[146:149], v[162:165], v[126:129]
	v_mfma_f32_16x16x32_bf16 v[122:125], v[154:157], v[162:165], v[122:125]
	v_mfma_f32_16x16x32_bf16 v[110:113], v[146:149], v[170:173], v[110:113]
	v_mfma_f32_16x16x32_bf16 v[106:109], v[154:157], v[170:173], v[106:109]
	v_mfma_f32_16x16x32_bf16 v[94:97], v[146:149], v[178:181], v[94:97]
	v_mfma_f32_16x16x32_bf16 v[90:93], v[154:157], v[178:181], v[90:93]
	v_mfma_f32_16x16x32_bf16 v[78:81], v[146:149], v[186:189], v[78:81]
	v_mfma_f32_16x16x32_bf16 v[74:77], v[154:157], v[186:189], v[74:77]
	s_barrier
	s_add_i32 s44, 0, 0x14000
	v_add_u32_e32 v140, s44, v143
	s_add_i32 s0, s43, s11
	ds_read_b128 v[190:193], v140
	ds_read_b128 v[194:197], v140 offset:1024
	ds_read_b128 v[220:223], v140 offset:2048
	ds_read_b128 v[224:227], v140 offset:3072
	v_lshl_add_u64 v[140:141], s[8:9], 0, v[64:65]
	s_mov_b32 m0, s0
	v_lshl_add_u64 v[198:199], s[8:9], 0, v[130:131]
	global_load_lds_dwordx4 v[140:141], off
	s_add_i32 m0, s0, 0x2000
	s_nop 0
	global_load_lds_dwordx4 v[198:199], off
	s_barrier
	s_waitcnt lgkmcnt(0)
	v_mfma_f32_16x16x32_bf16 v[118:121], v[190:193], v[158:161], v[118:121]
	v_mfma_f32_16x16x32_bf16 v[114:117], v[220:223], v[158:161], v[114:117]
	v_mfma_f32_16x16x32_bf16 v[102:105], v[190:193], v[166:169], v[102:105]
	v_mfma_f32_16x16x32_bf16 v[98:101], v[220:223], v[166:169], v[98:101]
	v_mfma_f32_16x16x32_bf16 v[86:89], v[190:193], v[174:177], v[86:89]
	v_mfma_f32_16x16x32_bf16 v[82:85], v[220:223], v[174:177], v[82:85]
	v_mfma_f32_16x16x32_bf16 v[70:73], v[190:193], v[182:185], v[70:73]
	v_mfma_f32_16x16x32_bf16 v[66:69], v[220:223], v[182:185], v[66:69]
	v_mfma_f32_16x16x32_bf16 v[118:121], v[194:197], v[162:165], v[118:121]
	v_mfma_f32_16x16x32_bf16 v[114:117], v[224:227], v[162:165], v[114:117]
	v_mfma_f32_16x16x32_bf16 v[102:105], v[194:197], v[170:173], v[102:105]
	v_mfma_f32_16x16x32_bf16 v[98:101], v[224:227], v[170:173], v[98:101]
	v_mfma_f32_16x16x32_bf16 v[86:89], v[194:197], v[178:181], v[86:89]
	v_mfma_f32_16x16x32_bf16 v[82:85], v[224:227], v[178:181], v[82:85]
	v_mfma_f32_16x16x32_bf16 v[70:73], v[194:197], v[186:189], v[70:73]
	v_mfma_f32_16x16x32_bf16 v[66:69], v[224:227], v[186:189], v[66:69]
	s_barrier
	s_mov_b32 m0, s12
	v_lshl_add_u64 v[228:229], s[2:3], 0, v[64:65]
	ds_read_b128 v[158:161], v145 offset:16384
	ds_read_b128 v[162:165], v145 offset:17408
	ds_read_b128 v[166:169], v145 offset:18432
	ds_read_b128 v[170:173], v145 offset:19456
	ds_read_b128 v[174:177], v145 offset:20480
	ds_read_b128 v[178:181], v145 offset:21504
	ds_read_b128 v[182:185], v145 offset:22528
	ds_read_b128 v[186:189], v145 offset:23552
	global_load_lds_dwordx4 v[228:229], off
	v_lshl_add_u64 v[230:231], s[2:3], 0, v[130:131]
	s_mov_b32 m0, s13
	s_nop 0
	global_load_lds_dwordx4 v[230:231], off
	s_barrier
	s_waitcnt lgkmcnt(0)
	v_mfma_f32_16x16x32_bf16 v[60:63], v[136:139], v[158:161], v[60:63]
	v_mfma_f32_16x16x32_bf16 v[56:59], v[150:153], v[158:161], v[56:59]
	v_mfma_f32_16x16x32_bf16 v[44:47], v[136:139], v[166:169], v[44:47]
	v_mfma_f32_16x16x32_bf16 v[40:43], v[150:153], v[166:169], v[40:43]
	v_mfma_f32_16x16x32_bf16 v[28:31], v[136:139], v[174:177], v[28:31]
	v_mfma_f32_16x16x32_bf16 v[24:27], v[150:153], v[174:177], v[24:27]
	v_mfma_f32_16x16x32_bf16 v[12:15], v[136:139], v[182:185], v[12:15]
	v_mfma_f32_16x16x32_bf16 v[8:11], v[150:153], v[182:185], v[8:11]
	v_mfma_f32_16x16x32_bf16 v[60:63], v[146:149], v[162:165], v[60:63]
	v_mfma_f32_16x16x32_bf16 v[56:59], v[154:157], v[162:165], v[56:59]
	v_mfma_f32_16x16x32_bf16 v[44:47], v[146:149], v[170:173], v[44:47]
	v_mfma_f32_16x16x32_bf16 v[40:43], v[154:157], v[170:173], v[40:43]
	v_mfma_f32_16x16x32_bf16 v[28:31], v[146:149], v[178:181], v[28:31]
	v_mfma_f32_16x16x32_bf16 v[24:27], v[154:157], v[178:181], v[24:27]
	v_mfma_f32_16x16x32_bf16 v[12:15], v[146:149], v[186:189], v[12:15]
	v_mfma_f32_16x16x32_bf16 v[8:11], v[154:157], v[186:189], v[8:11]
	s_barrier
; #define PG8_STAGE(bufoff, gbase, voff) do { _Pragma("unroll") for (int _i = 0; _i < 2; ++_i) \
;         __builtin_amdgcn_global_load_lds((const unsigned*)((const char*)(gbase) + (voff)[_i]), (LAS unsigned*)(lds + (bufoff) + ldsw + _i * 8192), 16, 0, 0); } while (0)
; #define PG8_LDA(dst, b, h) do { _Pragma("unroll") for (int m = 0; m < 4; ++m) _Pragma("unroll") for (int k = 0; k < 2; ++k) dst[m][k] = *(const LAS bf16x8*)(lds + PG8_SA(b, h) + aoff + m * 2048 + k * 1024); } while (0)
; #define PG8_LDB(dst, b, h) do { _Pragma("unroll") for (int n = 0; n < 2; ++n) _Pragma("unroll") for (int k = 0; k < 2; ++k) dst[n][k] = *(const LAS bf16x8*)(lds + PG8_SB(b, h) + boff + n * 2048 + k * 1024); } while (0)
; #define PG8_MMA(ai, bj, At, Bt) do { __builtin_amdgcn_s_setprio(1); _Pragma("unroll") for (int m = 0; m < 4; ++m) _Pragma("unroll") for (int n = 0; n < 2; ++n) _Pragma("unroll") for (int k = 0; k < 2; ++k) \
;         acc[ai][bj][m][n] = __builtin_amdgcn_mfma_f32_16x16x32_bf16(Bt[n][k], At[m][k], acc[ai][bj][m][n], 0, 0, 0); __builtin_amdgcn_s_setprio(0); } while (0)
; #define PG8_WAIT_V(n) asm volatile("s_waitcnt vmcnt(" #n ")" ::: "memory")
; #define PG8_WAIT_L(n) asm volatile("s_waitcnt lgkmcnt(" #n ")" ::: "memory")
; #define PG8_BAR __builtin_amdgcn_s_barrier()
; #define PG8_SCHED __builtin_amdgcn_sched_barrier(0)
;     ...
;             PG8_STAGE(PG8_SB(0, 1), b2 + hstep, voffB);
;             PG8_WAIT_V(6); PG8_BAR; PG8_MMA(1, 1, At, B1); PG8_BAR;
;             PG8_LDB(B0, 1, 0); PG8_SCHED; PG8_LDA(At, 1, 0); PG8_STAGE(PG8_SA(0, 1), a2 + hstep, voffA);
;             PG8_WAIT_L(8); PG8_BAR; PG8_WAIT_L(0); PG8_MMA(0, 0, At, B0); PG8_BAR; PG8_SCHED;
;             PG8_LDB(B1, 1, 1); PG8_STAGE(PG8_SB(1, 0), b3, voffB);
;             PG8_BAR; PG8_WAIT_L(0); PG8_MMA(0, 1, At, B1); PG8_BAR;
	s_add_u32 s0, s8, 0x84000
	s_addc_u32 s1, s9, 0
	s_add_i32 s43, s44, s11
	v_lshl_add_u64 v[136:137], s[0:1], 0, v[64:65]
	s_mov_b32 m0, s43
	s_nop 0
	global_load_lds_dwordx4 v[136:137], off
	v_lshl_add_u64 v[136:137], s[0:1], 0, v[130:131]
	s_add_i32 m0, s43, 0x2000
	s_nop 0
	global_load_lds_dwordx4 v[136:137], off
	s_waitcnt vmcnt(6)
	s_barrier
	v_mfma_f32_16x16x32_bf16 v[52:55], v[190:193], v[158:161], v[52:55]
	v_mfma_f32_16x16x32_bf16 v[48:51], v[220:223], v[158:161], v[48:51]
	v_mfma_f32_16x16x32_bf16 v[36:39], v[190:193], v[166:169], v[36:39]
	v_mfma_f32_16x16x32_bf16 v[32:35], v[220:223], v[166:169], v[32:35]
	v_mfma_f32_16x16x32_bf16 v[20:23], v[190:193], v[174:177], v[20:23]
	v_mfma_f32_16x16x32_bf16 v[16:19], v[220:223], v[174:177], v[16:19]
	v_mfma_f32_16x16x32_bf16 v[4:7], v[190:193], v[182:185], v[4:7]
	v_mfma_f32_16x16x32_bf16 v[0:3], v[220:223], v[182:185], v[0:3]
	v_mfma_f32_16x16x32_bf16 v[52:55], v[194:197], v[162:165], v[52:55]
	v_mfma_f32_16x16x32_bf16 v[48:51], v[224:227], v[162:165], v[48:51]
	v_mfma_f32_16x16x32_bf16 v[36:39], v[194:197], v[170:173], v[36:39]
	v_mfma_f32_16x16x32_bf16 v[32:35], v[224:227], v[170:173], v[32:35]
	v_mfma_f32_16x16x32_bf16 v[20:23], v[194:197], v[178:181], v[20:23]
	v_mfma_f32_16x16x32_bf16 v[16:19], v[224:227], v[178:181], v[16:19]
	v_mfma_f32_16x16x32_bf16 v[4:7], v[194:197], v[186:189], v[4:7]
	v_mfma_f32_16x16x32_bf16 v[0:3], v[224:227], v[186:189], v[0:3]
	s_barrier
	s_add_i32 s43, 0, 0x18000
	v_add_u32_e32 v154, s43, v143
	ds_read_b128 v[136:139], v154
	ds_read_b128 v[146:149], v154 offset:1024
	ds_read_b128 v[150:153], v154 offset:2048
	ds_read_b128 v[154:157], v154 offset:3072
	s_add_u32 s0, s2, 0x84000
	s_addc_u32 s1, s3, 0
	s_mov_b32 m0, s14
	v_lshl_add_u64 v[190:191], s[0:1], 0, v[64:65]
	ds_read_b128 v[158:161], v145 offset:32768
	ds_read_b128 v[162:165], v145 offset:33792
	ds_read_b128 v[166:169], v145 offset:34816
	ds_read_b128 v[170:173], v145 offset:35840
	ds_read_b128 v[174:177], v145 offset:36864
	ds_read_b128 v[178:181], v145 offset:37888
	ds_read_b128 v[182:185], v145 offset:38912
	ds_read_b128 v[186:189], v145 offset:39936
	global_load_lds_dwordx4 v[190:191], off
	v_lshl_add_u64 v[190:191], s[0:1], 0, v[130:131]
	s_mov_b32 m0, s15
	s_nop 0
	global_load_lds_dwordx4 v[190:191], off
	s_waitcnt lgkmcnt(8)
	s_barrier
	s_waitcnt lgkmcnt(0)
	v_mfma_f32_16x16x32_bf16 v[126:129], v[136:139], v[158:161], v[126:129]
	v_mfma_f32_16x16x32_bf16 v[122:125], v[150:153], v[158:161], v[122:125]
	v_mfma_f32_16x16x32_bf16 v[110:113], v[136:139], v[166:169], v[110:113]
	v_mfma_f32_16x16x32_bf16 v[106:109], v[150:153], v[166:169], v[106:109]
	v_mfma_f32_16x16x32_bf16 v[94:97], v[136:139], v[174:177], v[94:97]
	v_mfma_f32_16x16x32_bf16 v[90:93], v[150:153], v[174:177], v[90:93]
	v_mfma_f32_16x16x32_bf16 v[78:81], v[136:139], v[182:185], v[78:81]
	v_mfma_f32_16x16x32_bf16 v[74:77], v[150:153], v[182:185], v[74:77]
	v_mfma_f32_16x16x32_bf16 v[126:129], v[146:149], v[162:165], v[126:129]
	v_mfma_f32_16x16x32_bf16 v[122:125], v[154:157], v[162:165], v[122:125]
	v_mfma_f32_16x16x32_bf16 v[110:113], v[146:149], v[170:173], v[110:113]
	v_mfma_f32_16x16x32_bf16 v[106:109], v[154:157], v[170:173], v[106:109]
	v_mfma_f32_16x16x32_bf16 v[94:97], v[146:149], v[178:181], v[94:97]
	v_mfma_f32_16x16x32_bf16 v[90:93], v[154:157], v[178:181], v[90:93]
	v_mfma_f32_16x16x32_bf16 v[78:81], v[146:149], v[186:189], v[78:81]
	v_mfma_f32_16x16x32_bf16 v[74:77], v[154:157], v[186:189], v[74:77]
	s_barrier
	s_add_i32 s2, 0, 0x1c000
	s_add_i32 s0, s43, s11
	v_add_u32_e32 v208, s2, v143
	v_lshl_add_u64 v[140:141], v[140:141], 0, s[16:17]
	s_mov_b32 m0, s0
	ds_read_b128 v[190:193], v208
	ds_read_b128 v[194:197], v208 offset:1024
	ds_read_b128 v[220:223], v208 offset:2048
	ds_read_b128 v[224:227], v208 offset:3072
	global_load_lds_dwordx4 v[140:141], off
	v_lshl_add_u64 v[140:141], v[198:199], 0, s[16:17]
	s_add_i32 m0, s0, 0x2000
	s_nop 0
	global_load_lds_dwordx4 v[140:141], off
	s_barrier
	s_waitcnt lgkmcnt(0)
	v_mfma_f32_16x16x32_bf16 v[118:121], v[190:193], v[158:161], v[118:121]
	v_mfma_f32_16x16x32_bf16 v[114:117], v[220:223], v[158:161], v[114:117]
	v_mfma_f32_16x16x32_bf16 v[102:105], v[190:193], v[166:169], v[102:105]
	v_mfma_f32_16x16x32_bf16 v[98:101], v[220:223], v[166:169], v[98:101]
	v_mfma_f32_16x16x32_bf16 v[86:89], v[190:193], v[174:177], v[86:89]
	v_mfma_f32_16x16x32_bf16 v[82:85], v[220:223], v[174:177], v[82:85]
	v_mfma_f32_16x16x32_bf16 v[70:73], v[190:193], v[182:185], v[70:73]
	v_mfma_f32_16x16x32_bf16 v[66:69], v[220:223], v[182:185], v[66:69]
	v_mfma_f32_16x16x32_bf16 v[118:121], v[194:197], v[162:165], v[118:121]
	v_mfma_f32_16x16x32_bf16 v[114:117], v[224:227], v[162:165], v[114:117]
	v_mfma_f32_16x16x32_bf16 v[102:105], v[194:197], v[170:173], v[102:105]
	v_mfma_f32_16x16x32_bf16 v[98:101], v[224:227], v[170:173], v[98:101]
	v_mfma_f32_16x16x32_bf16 v[86:89], v[194:197], v[178:181], v[86:89]
	v_mfma_f32_16x16x32_bf16 v[82:85], v[224:227], v[178:181], v[82:85]
	v_mfma_f32_16x16x32_bf16 v[70:73], v[194:197], v[186:189], v[70:73]
	v_mfma_f32_16x16x32_bf16 v[66:69], v[224:227], v[186:189], v[66:69]
	s_barrier
; #define PG8_STAGE(bufoff, gbase, voff) do { _Pragma("unroll") for (int _i = 0; _i < 2; ++_i) \
;         __builtin_amdgcn_global_load_lds((const unsigned*)((const char*)(gbase) + (voff)[_i]), (LAS unsigned*)(lds + (bufoff) + ldsw + _i * 8192), 16, 0, 0); } while (0)
; #define PG8_LDA(dst, b, h) do { _Pragma("unroll") for (int m = 0; m < 4; ++m) _Pragma("unroll") for (int k = 0; k < 2; ++k) dst[m][k] = *(const LAS bf16x8*)(lds + PG8_SA(b, h) + aoff + m * 2048 + k * 1024); } while (0)
; #define PG8_MMA(ai, bj, At, Bt) do { __builtin_amdgcn_s_setprio(1); _Pragma("unroll") for (int m = 0; m < 4; ++m) _Pragma("unroll") for (int n = 0; n < 2; ++n) _Pragma("unroll") for (int k = 0; k < 2; ++k) \
;         acc[ai][bj][m][n] = __builtin_amdgcn_mfma_f32_16x16x32_bf16(Bt[n][k], At[m][k], acc[ai][bj][m][n], 0, 0, 0); __builtin_amdgcn_s_setprio(0); } while (0)
; #define PG8_WAIT_V(n) asm volatile("s_waitcnt vmcnt(" #n ")" ::: "memory")
; #define PG8_WAIT_L(n) asm volatile("s_waitcnt lgkmcnt(" #n ")" ::: "memory")
; #define PG8_BAR __builtin_amdgcn_s_barrier()
; #define PG8_SCHED __builtin_amdgcn_sched_barrier(0)
; __device__ __forceinline__ f32x4 gelu4(const f32x4 x) {
;     const f32x4 t = x * x, a = x * (t * -0.10294324f + -2.3022082f);
;     f32x4 e; e[0] = __builtin_amdgcn_exp2f(a[0]); e[1] = __builtin_amdgcn_exp2f(a[1]); e[2] = __builtin_amdgcn_exp2f(a[2]); e[3] = __builtin_amdgcn_exp2f(a[3]);
;     const f32x4 d = e + 1.0f;
;     f32x4 r; r[0] = __builtin_amdgcn_rcpf(d[0]); r[1] = __builtin_amdgcn_rcpf(d[1]); r[2] = __builtin_amdgcn_rcpf(d[2]); r[3] = __builtin_amdgcn_rcpf(d[3]);
;     return x * r;
; }
;     ...
;             PG8_BAR; PG8_WAIT_L(0); PG8_MMA(0, 1, At, B1); PG8_BAR;
;             PG8_LDA(At, 1, 1); PG8_STAGE(PG8_SA(1, 0), a3, voffA);
;             PG8_BAR; PG8_WAIT_L(0); PG8_MMA(1, 0, At, B0); PG8_BAR; PG8_SCHED;
;             PG8_STAGE(PG8_SB(1, 1), b3 + hstep, voffB);
;             PG8_WAIT_V(6); PG8_BAR; PG8_MMA(1, 1, At, B1); PG8_BAR;
;         }
;         if constexpr (Epi::FUSE_LN) {
;             if (E.fuse && cur.ks < 0) { if (wr == 0) PG8_BAR; E.fused(acc, cur, wr, wc, fr, fq, lds); if (wr == 1) PG8_BAR; }
;             else E(acc, cur, wr, wc, fr, fq);
;         } else E(acc, cur, wr, wc, fr, fq);
;         if (!has_next) break;
	s_mov_b32 m0, s24
	v_lshl_add_u64 v[140:141], v[228:229], 0, s[16:17]
	ds_read_b128 v[158:161], v145 offset:49152
	ds_read_b128 v[162:165], v145 offset:50176
	ds_read_b128 v[166:169], v145 offset:51200
	ds_read_b128 v[170:173], v145 offset:52224
	ds_read_b128 v[174:177], v145 offset:53248
	ds_read_b128 v[178:181], v145 offset:54272
	ds_read_b128 v[182:185], v145 offset:55296
	ds_read_b128 v[186:189], v145 offset:56320
	global_load_lds_dwordx4 v[140:141], off
	v_lshl_add_u64 v[140:141], v[230:231], 0, s[16:17]
	s_mov_b32 m0, s25
	s_nop 0
	global_load_lds_dwordx4 v[140:141], off
	s_barrier
	s_waitcnt lgkmcnt(0)
	v_mfma_f32_16x16x32_bf16 v[60:63], v[136:139], v[158:161], v[60:63]
	v_mfma_f32_16x16x32_bf16 v[56:59], v[150:153], v[158:161], v[56:59]
	v_mfma_f32_16x16x32_bf16 v[44:47], v[136:139], v[166:169], v[44:47]
	v_mfma_f32_16x16x32_bf16 v[40:43], v[150:153], v[166:169], v[40:43]
	v_mfma_f32_16x16x32_bf16 v[28:31], v[136:139], v[174:177], v[28:31]
	v_mfma_f32_16x16x32_bf16 v[24:27], v[150:153], v[174:177], v[24:27]
	v_mfma_f32_16x16x32_bf16 v[12:15], v[136:139], v[182:185], v[12:15]
	v_mfma_f32_16x16x32_bf16 v[8:11], v[150:153], v[182:185], v[8:11]
	v_mfma_f32_16x16x32_bf16 v[60:63], v[146:149], v[162:165], v[60:63]
	v_mfma_f32_16x16x32_bf16 v[56:59], v[154:157], v[162:165], v[56:59]
	v_mfma_f32_16x16x32_bf16 v[44:47], v[146:149], v[170:173], v[44:47]
	v_mfma_f32_16x16x32_bf16 v[40:43], v[154:157], v[170:173], v[40:43]
	v_mfma_f32_16x16x32_bf16 v[28:31], v[146:149], v[178:181], v[28:31]
	v_mfma_f32_16x16x32_bf16 v[24:27], v[154:157], v[178:181], v[24:27]
	v_mfma_f32_16x16x32_bf16 v[12:15], v[146:149], v[186:189], v[12:15]
	v_mfma_f32_16x16x32_bf16 v[8:11], v[154:157], v[186:189], v[8:11]
	s_barrier
	s_add_u32 s0, s8, 0x84080
	s_addc_u32 s1, s9, 0
	s_add_i32 s2, s2, s11
	v_lshl_add_u64 v[136:137], s[0:1], 0, v[64:65]
	s_mov_b32 m0, s2
	s_nop 0
	global_load_lds_dwordx4 v[136:137], off
	v_lshl_add_u64 v[136:137], s[0:1], 0, v[130:131]
	s_add_i32 m0, s2, 0x2000
	s_nop 0
	global_load_lds_dwordx4 v[136:137], off
	s_waitcnt vmcnt(6)
	s_barrier
	v_mfma_f32_16x16x32_bf16 v[52:55], v[190:193], v[158:161], v[52:55]
	v_mfma_f32_16x16x32_bf16 v[48:51], v[220:223], v[158:161], v[48:51]
	v_mfma_f32_16x16x32_bf16 v[36:39], v[190:193], v[166:169], v[36:39]
	v_mfma_f32_16x16x32_bf16 v[32:35], v[220:223], v[166:169], v[32:35]
	v_mfma_f32_16x16x32_bf16 v[20:23], v[190:193], v[174:177], v[20:23]
	v_mfma_f32_16x16x32_bf16 v[16:19], v[220:223], v[174:177], v[16:19]
	v_mfma_f32_16x16x32_bf16 v[4:7], v[190:193], v[182:185], v[4:7]
	v_mfma_f32_16x16x32_bf16 v[0:3], v[220:223], v[182:185], v[0:3]
	v_mfma_f32_16x16x32_bf16 v[52:55], v[194:197], v[162:165], v[52:55]
	v_mfma_f32_16x16x32_bf16 v[48:51], v[224:227], v[162:165], v[48:51]
	v_mfma_f32_16x16x32_bf16 v[36:39], v[194:197], v[170:173], v[36:39]
	v_mfma_f32_16x16x32_bf16 v[32:35], v[224:227], v[170:173], v[32:35]
	v_mfma_f32_16x16x32_bf16 v[20:23], v[194:197], v[178:181], v[20:23]
	v_mfma_f32_16x16x32_bf16 v[16:19], v[224:227], v[178:181], v[16:19]
	v_mfma_f32_16x16x32_bf16 v[4:7], v[194:197], v[186:189], v[4:7]
	v_mfma_f32_16x16x32_bf16 v[0:3], v[224:227], v[186:189], v[0:3]
	s_barrier
	s_add_i32 s42, s42, 2
	s_add_u32 s40, s40, 0x100
	s_addc_u32 s41, s41, 0
	s_cmp_gt_u32 s42, 29
	s_mov_b64 s[0:1], s[4:5]
	s_cbranch_scc0 .LBB0_1441
	s_add_i32 s0, s38, -2
	s_cmp_lt_u32 s0, 8
	s_cselect_b64 s[2:3], -1, 0
	s_cmp_gt_u32 s0, 7
	s_cbranch_scc1 .LBB0_1444
	s_mov_b32 s40, 0xc0135761
	v_pk_mul_f32 v[136:137], v[128:129], v[128:129]
	v_pk_mul_f32 v[138:139], v[126:127], v[126:127]
	v_mov_b64_e32 v[140:141], s[40:41]
	s_mov_b32 s0, 0xbdd2d3e8
	v_pk_fma_f32 v[136:137], v[136:137], s[0:1], v[140:141] op_sel_hi:[1,0,0]
	v_pk_fma_f32 v[138:139], v[138:139], s[0:1], v[140:141] op_sel_hi:[1,0,0]
	v_pk_mul_f32 v[136:137], v[128:129], v[136:137]
	v_pk_mul_f32 v[138:139], v[126:127], v[138:139]
	v_exp_f32_e32 v136, v136
	v_exp_f32_e32 v138, v138
	v_exp_f32_e32 v137, v137
	v_exp_f32_e32 v139, v139
	v_pk_add_f32 v[136:137], v[136:137], 1.0 op_sel_hi:[1,0]
	v_pk_add_f32 v[138:139], v[138:139], 1.0 op_sel_hi:[1,0]
	v_rcp_f32_e32 v136, v136
	v_rcp_f32_e32 v138, v138
	v_rcp_f32_e32 v137, v137
	v_rcp_f32_e32 v139, v139
	v_pk_mul_f32 v[128:129], v[128:129], v[136:137]
	v_pk_mul_f32 v[126:127], v[126:127], v[138:139]
	s_branch .LBB0_1445
